# LDS read bases hoisted out of the K loop only (duplicate waits still present), for attribution
# speedup vs baseline: 1.0212x; 1.0212x over previous
; #define PG8_STAGE(bufoff, gbase, voff) do { _Pragma("unroll") for (int _i = 0; _i < 2; ++_i) \
;     __builtin_amdgcn_global_load_lds((const unsigned*)((const char*)(gbase) + (voff)[_i]), (LAS unsigned*)(lds + (bufoff) + ldsw + _i * 8192), 16, 0, 0); } while (0)
; #define PG8_LDA(dst, b, h) do { _Pragma("unroll") for (int m = 0; m < 4; ++m) _Pragma("unroll") for (int k = 0; k < 2; ++k) dst[m][k] = *(const LAS bf16x8*)(lds + PG8_SA(b, h) + aoff + m * 2048 + k * 1024); } while (0)
; #define PG8_LDB(dst, b, h) do { _Pragma("unroll") for (int n = 0; n < 2; ++n) _Pragma("unroll") for (int k = 0; k < 2; ++k) dst[n][k] = *(const LAS bf16x8*)(lds + PG8_SB(b, h) + boff + n * 2048 + k * 1024); } while (0)
; #define PG8_MMA(ai, bj, At, Bt) do { __builtin_amdgcn_s_setprio(1); _Pragma("unroll") for (int m = 0; m < 4; ++m) _Pragma("unroll") for (int n = 0; n < 2; ++n) _Pragma("unroll") for (int k = 0; k < 2; ++k) \
;     acc[ai][bj][m][n] = __builtin_amdgcn_mfma_f32_16x16x32_bf16(Bt[n][k], At[m][k], acc[ai][bj][m][n], 0, 0, 0); __builtin_amdgcn_s_setprio(0); } while (0)
; #define PG8_WAIT_L(n) asm volatile("s_waitcnt lgkmcnt(" #n ")" ::: "memory")
; #define PG8_BAR __builtin_amdgcn_s_barrier()
; #define PG8_SCHED __builtin_amdgcn_sched_barrier(0)
; template <class Epi, class Sched>
; DI void gemm_phase(LAS unsigned char* lds, const Gemm g, const Sched& S, const Epi& E) {
;     ...
;     for (int t = 0; t < nt; t += 2) {
;       const bool last = (t == nt - 2);
;       const char* a1 = cA + (size_t)(t + 1) * kstep;
;       const char* a2 = last ? nA : cA + (size_t)(t + 2) * kstep; const char* b2 = last ? nB : cB + (size_t)(t + 2) * kstep;
;       const char* a3 = a2 + kstep; const char* b3 = b2 + kstep;
;       PG8_LDB(B0, 0, 0); PG8_SCHED; PG8_LDA(At, 0, 0); PG8_STAGE(PG8_SA(1, 1), a1 + hstep, voffA);
;       PG8_WAIT_L(8); PG8_BAR; PG8_WAIT_L(0); PG8_MMA(0, 0, At, B0); PG8_BAR; PG8_SCHED;
;       PG8_LDB(B1, 0, 1); PG8_STAGE(PG8_SB(0, 0), b2, voffB);
;       PG8_BAR; PG8_WAIT_L(0); PG8_MMA(0, 1, At, B1); PG8_BAR;
;     ...
; #pragma unroll
;     for (int a = 0; a < 2; ++a)
; #pragma unroll
;       for (int b = 0; b < 2; ++b)
; #pragma unroll
;         for (int m = 0; m < 4; ++m)
; #pragma unroll
;           for (int n = 0; n < 2; ++n) acc[a][b][m][n] = (f32x4){0.f, 0.f, 0.f, 0.f};
;     cur = nxt; cA = nA; cB = nB; ++ui;
.LBB0_369:
	v_readlane_b32 s18, v239, 44
	v_readlane_b32 s19, v239, 45
	s_ashr_i32 s15, s14, 31
	s_mov_b32 s50, -2
	v_mov_b64_e32 v[0:1], s[18:19]
	v_cmp_lt_i64_e32 vcc, s[16:17], v[0:1]
	s_lshl_b64 s[16:17], s[14:15], 19
	s_add_u32 s16, s35, s16
	s_addc_u32 s17, s38, s17
	s_and_b64 s[18:19], vcc, exec
	s_cselect_b32 s15, s17, s3
	s_cselect_b32 s29, s16, s2
	s_ashr_i32 s13, s12, 31
	s_lshl_b64 s[18:19], s[12:13], 19
	s_add_u32 s18, s24, s18
	s_addc_u32 s19, s39, s19
	s_and_b64 s[20:21], vcc, exec
	s_cselect_b32 s13, s19, s5
	s_cselect_b32 s36, s18, s4
	s_add_u32 s2, s2, 0x40080
	s_addc_u32 s3, s3, 0
	s_add_u32 s37, s4, 0x100
	v_mov_b32_e32 v0, 0
	s_addc_u32 s49, s5, 0
	v_mov_b32_e32 v1, v0
	v_mov_b64_e32 v[2:3], v[0:1]
	v_mov_b64_e32 v[4:5], v[0:1]
	v_mov_b64_e32 v[6:7], v[0:1]
	v_mov_b64_e32 v[8:9], v[0:1]
	v_mov_b64_e32 v[10:11], v[0:1]
	v_mov_b64_e32 v[12:13], v[0:1]
	v_mov_b64_e32 v[14:15], v[0:1]
	v_mov_b64_e32 v[16:17], v[0:1]
	v_mov_b64_e32 v[18:19], v[0:1]
	v_mov_b64_e32 v[20:21], v[0:1]
	v_mov_b64_e32 v[22:23], v[0:1]
	v_mov_b64_e32 v[24:25], v[0:1]
	v_mov_b64_e32 v[26:27], v[0:1]
	v_mov_b64_e32 v[28:29], v[0:1]
	v_mov_b64_e32 v[30:31], v[0:1]
	v_mov_b64_e32 v[32:33], v[0:1]
	v_mov_b64_e32 v[34:35], v[0:1]
	v_mov_b64_e32 v[36:37], v[0:1]
	v_mov_b64_e32 v[38:39], v[0:1]
	v_mov_b64_e32 v[40:41], v[0:1]
	v_mov_b64_e32 v[42:43], v[0:1]
	v_mov_b64_e32 v[44:45], v[0:1]
	v_mov_b64_e32 v[46:47], v[0:1]
	v_mov_b64_e32 v[48:49], v[0:1]
	v_mov_b64_e32 v[50:51], v[0:1]
	v_mov_b64_e32 v[52:53], v[0:1]
	v_mov_b64_e32 v[54:55], v[0:1]
	v_mov_b64_e32 v[56:57], v[0:1]
	v_mov_b64_e32 v[58:59], v[0:1]
	v_mov_b64_e32 v[60:61], v[0:1]
	v_mov_b64_e32 v[62:63], v[0:1]
	v_mov_b64_e32 v[64:65], v[0:1]
	v_mov_b64_e32 v[66:67], v[0:1]
	v_mov_b64_e32 v[68:69], v[0:1]
	v_mov_b64_e32 v[70:71], v[0:1]
	v_mov_b64_e32 v[72:73], v[0:1]
	v_mov_b64_e32 v[74:75], v[0:1]
	v_mov_b64_e32 v[76:77], v[0:1]
	v_mov_b64_e32 v[78:79], v[0:1]
	v_mov_b64_e32 v[80:81], v[0:1]
	v_mov_b64_e32 v[82:83], v[0:1]
	v_mov_b64_e32 v[84:85], v[0:1]
	v_mov_b64_e32 v[86:87], v[0:1]
	v_mov_b64_e32 v[88:89], v[0:1]
	v_mov_b64_e32 v[90:91], v[0:1]
	v_mov_b64_e32 v[92:93], v[0:1]
	v_mov_b64_e32 v[94:95], v[0:1]
	v_mov_b64_e32 v[96:97], v[0:1]
	v_mov_b64_e32 v[98:99], v[0:1]
	v_mov_b64_e32 v[100:101], v[0:1]
	v_mov_b64_e32 v[102:103], v[0:1]
	v_mov_b64_e32 v[104:105], v[0:1]
	v_mov_b64_e32 v[106:107], v[0:1]
	v_mov_b64_e32 v[108:109], v[0:1]
	v_mov_b64_e32 v[110:111], v[0:1]
	v_mov_b64_e32 v[112:113], v[0:1]
	v_mov_b64_e32 v[114:115], v[0:1]
	v_mov_b64_e32 v[116:117], v[0:1]
	v_mov_b64_e32 v[118:119], v[0:1]
	v_mov_b64_e32 v[120:121], v[0:1]
	v_mov_b64_e32 v[122:123], v[0:1]
	v_mov_b64_e32 v[124:125], v[0:1]
	v_mov_b64_e32 v[126:127], v[0:1]
	v_add_u32_e32 v228, 0x10000, v155
	v_add_u32_e32 v229, 0x14000, v155
	v_add_u32_e32 v230, 0x18000, v155
	v_add_u32_e32 v231, 0x1c000, v155
.LBB0_370:
	s_add_u32 s4, s2, 0xfffc0080
	s_addc_u32 s5, s3, -1
	s_add_i32 s51, 0, 0x10000
	ds_read_b128 v[128:131], v228
	ds_read_b128 v[146:149], v228 offset:1024
	ds_read_b128 v[150:153], v228 offset:2048
	ds_read_b128 v[160:163], v228 offset:3072
	s_cmp_eq_u32 s50, 12
	s_cselect_b32 s21, s15, s5
	s_cselect_b32 s20, s29, s4
	s_cselect_b32 s5, s13, s49
	s_cselect_b32 s4, s36, s37
	s_add_i32 m0, s40, 0xc000
	ds_read_b128 v[164:167], v158
	ds_read_b128 v[168:171], v158 offset:1024
	ds_read_b128 v[172:175], v158 offset:2048
	ds_read_b128 v[176:179], v158 offset:3072
	ds_read_b128 v[196:199], v158 offset:4096
	ds_read_b128 v[200:203], v158 offset:5120
	ds_read_b128 v[204:207], v158 offset:6144
	ds_read_b128 v[208:211], v158 offset:7168
	global_load_lds_dwordx4 v140, s[2:3]
	s_add_i32 m0, s40, 0xe000
	s_nop 0
	global_load_lds_dwordx4 v142, s[2:3]
	s_waitcnt lgkmcnt(8)
	s_barrier
	s_waitcnt lgkmcnt(0)
	s_waitcnt lgkmcnt(0)
	v_mfma_f32_16x16x32_bf16 v[124:127], v[128:131], v[164:167], v[124:127]
	v_mfma_f32_16x16x32_bf16 v[120:123], v[150:153], v[164:167], v[120:123]
	v_mfma_f32_16x16x32_bf16 v[108:111], v[128:131], v[172:175], v[108:111]
	v_mfma_f32_16x16x32_bf16 v[104:107], v[150:153], v[172:175], v[104:107]
	v_mfma_f32_16x16x32_bf16 v[92:95], v[128:131], v[196:199], v[92:95]
	v_mfma_f32_16x16x32_bf16 v[88:91], v[150:153], v[196:199], v[88:91]
	v_mfma_f32_16x16x32_bf16 v[76:79], v[128:131], v[204:207], v[76:79]
	v_mfma_f32_16x16x32_bf16 v[72:75], v[150:153], v[204:207], v[72:75]
	v_mfma_f32_16x16x32_bf16 v[124:127], v[146:149], v[168:171], v[124:127]
	v_mfma_f32_16x16x32_bf16 v[120:123], v[160:163], v[168:171], v[120:123]
	v_mfma_f32_16x16x32_bf16 v[108:111], v[146:149], v[176:179], v[108:111]
	v_mfma_f32_16x16x32_bf16 v[104:107], v[160:163], v[176:179], v[104:107]
	v_mfma_f32_16x16x32_bf16 v[92:95], v[146:149], v[200:203], v[92:95]
	v_mfma_f32_16x16x32_bf16 v[88:91], v[160:163], v[200:203], v[88:91]
	v_mfma_f32_16x16x32_bf16 v[76:79], v[146:149], v[208:211], v[76:79]
	v_mfma_f32_16x16x32_bf16 v[72:75], v[160:163], v[208:211], v[72:75]
	s_barrier
	s_add_i32 s54, 0, 0x14000
	s_add_i32 s51, s51, s34
	s_add_u32 vcc_lo, s4, s0
	s_addc_u32 vcc_hi, s5, s1
	s_mov_b32 m0, s51
	ds_read_b128 v[212:215], v229
	ds_read_b128 v[216:219], v229 offset:1024
	ds_read_b128 v[220:223], v229 offset:2048
	ds_read_b128 v[224:227], v229 offset:3072
	global_load_lds_dwordx4 v136, s[4:5]
	s_add_i32 m0, s51, 0x2000
	s_nop 0
	global_load_lds_dwordx4 v132, s[4:5]
	s_barrier
; #define PG8_STAGE(bufoff, gbase, voff) do { _Pragma("unroll") for (int _i = 0; _i < 2; ++_i) \
;     __builtin_amdgcn_global_load_lds((const unsigned*)((const char*)(gbase) + (voff)[_i]), (LAS unsigned*)(lds + (bufoff) + ldsw + _i * 8192), 16, 0, 0); } while (0)
; #define PG8_LDA(dst, b, h) do { _Pragma("unroll") for (int m = 0; m < 4; ++m) _Pragma("unroll") for (int k = 0; k < 2; ++k) dst[m][k] = *(const LAS bf16x8*)(lds + PG8_SA(b, h) + aoff + m * 2048 + k * 1024); } while (0)
; #define PG8_LDB(dst, b, h) do { _Pragma("unroll") for (int n = 0; n < 2; ++n) _Pragma("unroll") for (int k = 0; k < 2; ++k) dst[n][k] = *(const LAS bf16x8*)(lds + PG8_SB(b, h) + boff + n * 2048 + k * 1024); } while (0)
; #define PG8_MMA(ai, bj, At, Bt) do { __builtin_amdgcn_s_setprio(1); _Pragma("unroll") for (int m = 0; m < 4; ++m) _Pragma("unroll") for (int n = 0; n < 2; ++n) _Pragma("unroll") for (int k = 0; k < 2; ++k) \
;     acc[ai][bj][m][n] = __builtin_amdgcn_mfma_f32_16x16x32_bf16(Bt[n][k], At[m][k], acc[ai][bj][m][n], 0, 0, 0); __builtin_amdgcn_s_setprio(0); } while (0)
; #define PG8_WAIT_V(n) asm volatile("s_waitcnt vmcnt(" #n ")" ::: "memory")
; #define PG8_WAIT_L(n) asm volatile("s_waitcnt lgkmcnt(" #n ")" ::: "memory")
; #define PG8_BAR __builtin_amdgcn_s_barrier()
; #define PG8_SCHED __builtin_amdgcn_sched_barrier(0)
; template <class Epi, class Sched>
; DI void gemm_phase(LAS unsigned char* lds, const Gemm g, const Sched& S, const Epi& E) {
;     ...
;       PG8_BAR; PG8_WAIT_L(0); PG8_MMA(0, 1, At, B1); PG8_BAR;
;       PG8_LDA(At, 0, 1); PG8_STAGE(PG8_SA(0, 0), a2, voffA);
;       PG8_BAR; PG8_WAIT_L(0); PG8_MMA(1, 0, At, B0); PG8_BAR; PG8_SCHED;
;       PG8_STAGE(PG8_SB(0, 1), b2 + hstep, voffB);
;       PG8_WAIT_V(6); PG8_BAR; PG8_MMA(1, 1, At, B1); PG8_BAR;
;       PG8_LDB(B0, 1, 0); PG8_SCHED; PG8_LDA(At, 1, 0); PG8_STAGE(PG8_SA(0, 1), a2 + hstep, voffA);
;       PG8_WAIT_L(8); PG8_BAR; PG8_WAIT_L(0); PG8_MMA(0, 0, At, B0); PG8_BAR; PG8_SCHED;
;       PG8_LDB(B1, 1, 1); PG8_STAGE(PG8_SB(1, 0), b3, voffB);
;       PG8_BAR; PG8_WAIT_L(0); PG8_MMA(0, 1, At, B1); PG8_BAR;
;       PG8_LDA(At, 1, 1); PG8_STAGE(PG8_SA(1, 0), a3, voffA);
	s_waitcnt lgkmcnt(0)
	s_waitcnt lgkmcnt(0)
	v_mfma_f32_16x16x32_bf16 v[116:119], v[212:215], v[164:167], v[116:119]
	v_mfma_f32_16x16x32_bf16 v[112:115], v[220:223], v[164:167], v[112:115]
	v_mfma_f32_16x16x32_bf16 v[100:103], v[212:215], v[172:175], v[100:103]
	v_mfma_f32_16x16x32_bf16 v[96:99], v[220:223], v[172:175], v[96:99]
	v_mfma_f32_16x16x32_bf16 v[84:87], v[212:215], v[196:199], v[84:87]
	v_mfma_f32_16x16x32_bf16 v[80:83], v[220:223], v[196:199], v[80:83]
	v_mfma_f32_16x16x32_bf16 v[68:71], v[212:215], v[204:207], v[68:71]
	v_mfma_f32_16x16x32_bf16 v[64:67], v[220:223], v[204:207], v[64:67]
	v_mfma_f32_16x16x32_bf16 v[116:119], v[216:219], v[168:171], v[116:119]
	v_mfma_f32_16x16x32_bf16 v[112:115], v[224:227], v[168:171], v[112:115]
	v_mfma_f32_16x16x32_bf16 v[100:103], v[216:219], v[176:179], v[100:103]
	v_mfma_f32_16x16x32_bf16 v[96:99], v[224:227], v[176:179], v[96:99]
	v_mfma_f32_16x16x32_bf16 v[84:87], v[216:219], v[200:203], v[84:87]
	v_mfma_f32_16x16x32_bf16 v[80:83], v[224:227], v[200:203], v[80:83]
	v_mfma_f32_16x16x32_bf16 v[68:71], v[216:219], v[208:211], v[68:71]
	v_mfma_f32_16x16x32_bf16 v[64:67], v[224:227], v[208:211], v[64:67]
	s_mov_b32 m0, s40
	s_add_u32 s100, s20, s0
	s_addc_u32 s101, s21, s1
	s_barrier
	ds_read_b128 v[164:167], v158 offset:16384
	ds_read_b128 v[168:171], v158 offset:17408
	ds_read_b128 v[172:175], v158 offset:18432
	ds_read_b128 v[176:179], v158 offset:19456
	ds_read_b128 v[196:199], v158 offset:20480
	ds_read_b128 v[200:203], v158 offset:21504
	ds_read_b128 v[204:207], v158 offset:22528
	ds_read_b128 v[208:211], v158 offset:23552
	global_load_lds_dwordx4 v138, s[20:21]
	s_mov_b32 m0, s41
	s_nop 0
	global_load_lds_dwordx4 v134, s[20:21]
	s_barrier
	s_waitcnt lgkmcnt(0)
	s_waitcnt lgkmcnt(0)
	v_mfma_f32_16x16x32_bf16 v[60:63], v[128:131], v[164:167], v[60:63]
	v_mfma_f32_16x16x32_bf16 v[56:59], v[150:153], v[164:167], v[56:59]
	v_mfma_f32_16x16x32_bf16 v[44:47], v[128:131], v[172:175], v[44:47]
	v_mfma_f32_16x16x32_bf16 v[40:43], v[150:153], v[172:175], v[40:43]
	v_mfma_f32_16x16x32_bf16 v[28:31], v[128:131], v[196:199], v[28:31]
	v_mfma_f32_16x16x32_bf16 v[24:27], v[150:153], v[196:199], v[24:27]
	v_mfma_f32_16x16x32_bf16 v[12:15], v[128:131], v[204:207], v[12:15]
	v_mfma_f32_16x16x32_bf16 v[8:11], v[150:153], v[204:207], v[8:11]
	v_mfma_f32_16x16x32_bf16 v[60:63], v[146:149], v[168:171], v[60:63]
	v_mfma_f32_16x16x32_bf16 v[56:59], v[160:163], v[168:171], v[56:59]
	v_mfma_f32_16x16x32_bf16 v[44:47], v[146:149], v[176:179], v[44:47]
	v_mfma_f32_16x16x32_bf16 v[40:43], v[160:163], v[176:179], v[40:43]
	v_mfma_f32_16x16x32_bf16 v[28:31], v[146:149], v[200:203], v[28:31]
	v_mfma_f32_16x16x32_bf16 v[24:27], v[160:163], v[200:203], v[24:27]
	v_mfma_f32_16x16x32_bf16 v[12:15], v[146:149], v[208:211], v[12:15]
	v_mfma_f32_16x16x32_bf16 v[8:11], v[160:163], v[208:211], v[8:11]
	s_barrier
	s_add_u32 s52, s4, 0x40000
	s_addc_u32 s53, s5, 0
	s_add_i32 s51, s54, s34
	s_mov_b32 m0, s51
	s_nop 0
	global_load_lds_dwordx4 v136, s[52:53]
	s_add_i32 m0, s51, 0x2000
	s_nop 0
	global_load_lds_dwordx4 v132, s[52:53]
	s_waitcnt vmcnt(6)
	s_barrier
	v_mfma_f32_16x16x32_bf16 v[52:55], v[212:215], v[164:167], v[52:55]
	v_mfma_f32_16x16x32_bf16 v[48:51], v[220:223], v[164:167], v[48:51]
	v_mfma_f32_16x16x32_bf16 v[36:39], v[212:215], v[172:175], v[36:39]
	v_mfma_f32_16x16x32_bf16 v[32:35], v[220:223], v[172:175], v[32:35]
	v_mfma_f32_16x16x32_bf16 v[20:23], v[212:215], v[196:199], v[20:23]
	v_mfma_f32_16x16x32_bf16 v[16:19], v[220:223], v[196:199], v[16:19]
	v_mfma_f32_16x16x32_bf16 v[4:7], v[212:215], v[204:207], v[4:7]
	v_mfma_f32_16x16x32_bf16 v[0:3], v[220:223], v[204:207], v[0:3]
	v_mfma_f32_16x16x32_bf16 v[52:55], v[216:219], v[168:171], v[52:55]
	v_mfma_f32_16x16x32_bf16 v[48:51], v[224:227], v[168:171], v[48:51]
	v_mfma_f32_16x16x32_bf16 v[36:39], v[216:219], v[176:179], v[36:39]
	v_mfma_f32_16x16x32_bf16 v[32:35], v[224:227], v[176:179], v[32:35]
	v_mfma_f32_16x16x32_bf16 v[20:23], v[216:219], v[200:203], v[20:23]
	v_mfma_f32_16x16x32_bf16 v[16:19], v[224:227], v[200:203], v[16:19]
	v_mfma_f32_16x16x32_bf16 v[4:7], v[216:219], v[208:211], v[4:7]
	v_mfma_f32_16x16x32_bf16 v[0:3], v[224:227], v[208:211], v[0:3]
	s_add_i32 s51, 0, 0x18000
	s_barrier
	ds_read_b128 v[128:131], v230
	ds_read_b128 v[146:149], v230 offset:1024
	ds_read_b128 v[150:153], v230 offset:2048
	ds_read_b128 v[160:163], v230 offset:3072
	s_add_u32 s20, s20, 0x40000
	s_addc_u32 s21, s21, 0
	s_mov_b32 m0, s42
	ds_read_b128 v[164:167], v158 offset:32768
	ds_read_b128 v[168:171], v158 offset:33792
	ds_read_b128 v[172:175], v158 offset:34816
	ds_read_b128 v[176:179], v158 offset:35840
	ds_read_b128 v[196:199], v158 offset:36864
	ds_read_b128 v[200:203], v158 offset:37888
	ds_read_b128 v[204:207], v158 offset:38912
	ds_read_b128 v[208:211], v158 offset:39936
	global_load_lds_dwordx4 v138, s[20:21]
	s_mov_b32 m0, s43
	s_nop 0
	global_load_lds_dwordx4 v134, s[20:21]
	s_waitcnt lgkmcnt(8)
	s_barrier
	s_waitcnt lgkmcnt(0)
	s_waitcnt lgkmcnt(0)
	v_mfma_f32_16x16x32_bf16 v[124:127], v[128:131], v[164:167], v[124:127]
	v_mfma_f32_16x16x32_bf16 v[120:123], v[150:153], v[164:167], v[120:123]
	v_mfma_f32_16x16x32_bf16 v[108:111], v[128:131], v[172:175], v[108:111]
	v_mfma_f32_16x16x32_bf16 v[104:107], v[150:153], v[172:175], v[104:107]
	v_mfma_f32_16x16x32_bf16 v[92:95], v[128:131], v[196:199], v[92:95]
	v_mfma_f32_16x16x32_bf16 v[88:91], v[150:153], v[196:199], v[88:91]
	v_mfma_f32_16x16x32_bf16 v[76:79], v[128:131], v[204:207], v[76:79]
	v_mfma_f32_16x16x32_bf16 v[72:75], v[150:153], v[204:207], v[72:75]
	v_mfma_f32_16x16x32_bf16 v[124:127], v[146:149], v[168:171], v[124:127]
	v_mfma_f32_16x16x32_bf16 v[120:123], v[160:163], v[168:171], v[120:123]
	v_mfma_f32_16x16x32_bf16 v[108:111], v[146:149], v[176:179], v[108:111]
	v_mfma_f32_16x16x32_bf16 v[104:107], v[160:163], v[176:179], v[104:107]
	v_mfma_f32_16x16x32_bf16 v[92:95], v[146:149], v[200:203], v[92:95]
	v_mfma_f32_16x16x32_bf16 v[88:91], v[160:163], v[200:203], v[88:91]
	v_mfma_f32_16x16x32_bf16 v[76:79], v[146:149], v[208:211], v[76:79]
	v_mfma_f32_16x16x32_bf16 v[72:75], v[160:163], v[208:211], v[72:75]
	s_barrier
; #define PG8_STAGE(bufoff, gbase, voff) do { _Pragma("unroll") for (int _i = 0; _i < 2; ++_i) \
;     __builtin_amdgcn_global_load_lds((const unsigned*)((const char*)(gbase) + (voff)[_i]), (LAS unsigned*)(lds + (bufoff) + ldsw + _i * 8192), 16, 0, 0); } while (0)
; #define PG8_LDA(dst, b, h) do { _Pragma("unroll") for (int m = 0; m < 4; ++m) _Pragma("unroll") for (int k = 0; k < 2; ++k) dst[m][k] = *(const LAS bf16x8*)(lds + PG8_SA(b, h) + aoff + m * 2048 + k * 1024); } while (0)
; #define PG8_MMA(ai, bj, At, Bt) do { __builtin_amdgcn_s_setprio(1); _Pragma("unroll") for (int m = 0; m < 4; ++m) _Pragma("unroll") for (int n = 0; n < 2; ++n) _Pragma("unroll") for (int k = 0; k < 2; ++k) \
;     acc[ai][bj][m][n] = __builtin_amdgcn_mfma_f32_16x16x32_bf16(Bt[n][k], At[m][k], acc[ai][bj][m][n], 0, 0, 0); __builtin_amdgcn_s_setprio(0); } while (0)
; #define PG8_WAIT_V(n) asm volatile("s_waitcnt vmcnt(" #n ")" ::: "memory")
; #define PG8_WAIT_L(n) asm volatile("s_waitcnt lgkmcnt(" #n ")" ::: "memory")
; #define PG8_BAR __builtin_amdgcn_s_barrier()
; #define PG8_SCHED __builtin_amdgcn_sched_barrier(0)
; template <class Epi, class Sched>
; DI void gemm_phase(LAS unsigned char* lds, const Gemm g, const Sched& S, const Epi& E) {
;     ...
;       PG8_LDA(At, 1, 1); PG8_STAGE(PG8_SA(1, 0), a3, voffA);
;       PG8_BAR; PG8_WAIT_L(0); PG8_MMA(1, 0, At, B0); PG8_BAR; PG8_SCHED;
;       PG8_STAGE(PG8_SB(1, 1), b3 + hstep, voffB);
;       PG8_WAIT_V(6); PG8_BAR; PG8_MMA(1, 1, At, B1); PG8_BAR;
;   DI void operator()(const f32x4 (&acc)[2][2][4][2], const pg8::Unit& u, int wr, int wc, int fr_, int fq_) const {
;     ...
;             } else if (EPI == EPI_CIN) {
;               if (n == 0) {
;                 const int gb = u.pn * 256 + bj * 128 + wc * 32;
;                 const int f8 = gb + 8 * fq;
;                 const f32x4 v1 = acc[ai][bj][m][1];
;                 if (gb < 1024) st_bf8((u16*)(big + O_QD) + (size_t)token * 1024 + f8, v, v1, rinv * (0.125f * LOG2E));
;                 else if (gb < 2048) st_bf8((u16*)(big + O_KD) + (size_t)token * 1024 + (f8 - 1024), v, v1, rinv);
;                 else st_bf8((u16*)(big + O_VDT) + (size_t)token * 1024 + (f8 - 2048), v, v1, rinv);
	s_add_i32 s20, 0, 0x1c000
	s_add_i32 s21, s51, s34
	s_mov_b32 m0, s21
	ds_read_b128 v[212:215], v231
	ds_read_b128 v[216:219], v231 offset:1024
	ds_read_b128 v[220:223], v231 offset:2048
	ds_read_b128 v[224:227], v231 offset:3072
	global_load_lds_dwordx4 v136, vcc
	s_add_i32 m0, s21, 0x2000
	s_nop 0
	global_load_lds_dwordx4 v132, vcc
	s_barrier
	s_waitcnt lgkmcnt(0)
	s_waitcnt lgkmcnt(0)
	v_mfma_f32_16x16x32_bf16 v[116:119], v[212:215], v[164:167], v[116:119]
	v_mfma_f32_16x16x32_bf16 v[112:115], v[220:223], v[164:167], v[112:115]
	v_mfma_f32_16x16x32_bf16 v[100:103], v[212:215], v[172:175], v[100:103]
	v_mfma_f32_16x16x32_bf16 v[96:99], v[220:223], v[172:175], v[96:99]
	v_mfma_f32_16x16x32_bf16 v[84:87], v[212:215], v[196:199], v[84:87]
	v_mfma_f32_16x16x32_bf16 v[80:83], v[220:223], v[196:199], v[80:83]
	v_mfma_f32_16x16x32_bf16 v[68:71], v[212:215], v[204:207], v[68:71]
	v_mfma_f32_16x16x32_bf16 v[64:67], v[220:223], v[204:207], v[64:67]
	v_mfma_f32_16x16x32_bf16 v[116:119], v[216:219], v[168:171], v[116:119]
	v_mfma_f32_16x16x32_bf16 v[112:115], v[224:227], v[168:171], v[112:115]
	v_mfma_f32_16x16x32_bf16 v[100:103], v[216:219], v[176:179], v[100:103]
	v_mfma_f32_16x16x32_bf16 v[96:99], v[224:227], v[176:179], v[96:99]
	v_mfma_f32_16x16x32_bf16 v[84:87], v[216:219], v[200:203], v[84:87]
	v_mfma_f32_16x16x32_bf16 v[80:83], v[224:227], v[200:203], v[80:83]
	v_mfma_f32_16x16x32_bf16 v[68:71], v[216:219], v[208:211], v[68:71]
	v_mfma_f32_16x16x32_bf16 v[64:67], v[224:227], v[208:211], v[64:67]
	s_mov_b32 m0, s46
	s_barrier
	ds_read_b128 v[164:167], v158 offset:49152
	ds_read_b128 v[168:171], v158 offset:50176
	ds_read_b128 v[172:175], v158 offset:51200
	ds_read_b128 v[176:179], v158 offset:52224
	ds_read_b128 v[196:199], v158 offset:53248
	ds_read_b128 v[200:203], v158 offset:54272
	ds_read_b128 v[204:207], v158 offset:55296
	ds_read_b128 v[208:211], v158 offset:56320
	global_load_lds_dwordx4 v138, s[100:101]
	s_mov_b32 m0, s47
	s_nop 0
	global_load_lds_dwordx4 v134, s[100:101]
	s_barrier
	s_waitcnt lgkmcnt(0)
	s_waitcnt lgkmcnt(0)
	v_mfma_f32_16x16x32_bf16 v[60:63], v[128:131], v[164:167], v[60:63]
	v_mfma_f32_16x16x32_bf16 v[56:59], v[150:153], v[164:167], v[56:59]
	v_mfma_f32_16x16x32_bf16 v[44:47], v[128:131], v[172:175], v[44:47]
	v_mfma_f32_16x16x32_bf16 v[40:43], v[150:153], v[172:175], v[40:43]
	v_mfma_f32_16x16x32_bf16 v[28:31], v[128:131], v[196:199], v[28:31]
	v_mfma_f32_16x16x32_bf16 v[24:27], v[150:153], v[196:199], v[24:27]
	v_mfma_f32_16x16x32_bf16 v[12:15], v[128:131], v[204:207], v[12:15]
	v_mfma_f32_16x16x32_bf16 v[8:11], v[150:153], v[204:207], v[8:11]
	v_mfma_f32_16x16x32_bf16 v[60:63], v[146:149], v[168:171], v[60:63]
	v_mfma_f32_16x16x32_bf16 v[56:59], v[160:163], v[168:171], v[56:59]
	v_mfma_f32_16x16x32_bf16 v[44:47], v[146:149], v[176:179], v[44:47]
	v_mfma_f32_16x16x32_bf16 v[40:43], v[160:163], v[176:179], v[40:43]
	v_mfma_f32_16x16x32_bf16 v[28:31], v[146:149], v[200:203], v[28:31]
	v_mfma_f32_16x16x32_bf16 v[24:27], v[160:163], v[200:203], v[24:27]
	v_mfma_f32_16x16x32_bf16 v[12:15], v[146:149], v[208:211], v[12:15]
	v_mfma_f32_16x16x32_bf16 v[8:11], v[160:163], v[208:211], v[8:11]
	s_barrier
	s_add_u32 s4, s4, 0x40080
	s_addc_u32 s5, s5, 0
	s_add_i32 s20, s20, s34
	s_mov_b32 m0, s20
	s_nop 0
	global_load_lds_dwordx4 v136, s[4:5]
	s_add_i32 m0, s20, 0x2000
	s_nop 0
	global_load_lds_dwordx4 v132, s[4:5]
	s_waitcnt vmcnt(6)
	s_barrier
	v_mfma_f32_16x16x32_bf16 v[52:55], v[212:215], v[164:167], v[52:55]
	v_mfma_f32_16x16x32_bf16 v[48:51], v[220:223], v[164:167], v[48:51]
	v_mfma_f32_16x16x32_bf16 v[36:39], v[212:215], v[172:175], v[36:39]
	v_mfma_f32_16x16x32_bf16 v[32:35], v[220:223], v[172:175], v[32:35]
	v_mfma_f32_16x16x32_bf16 v[20:23], v[212:215], v[196:199], v[20:23]
	v_mfma_f32_16x16x32_bf16 v[16:19], v[220:223], v[196:199], v[16:19]
	v_mfma_f32_16x16x32_bf16 v[4:7], v[212:215], v[204:207], v[4:7]
	v_mfma_f32_16x16x32_bf16 v[0:3], v[220:223], v[204:207], v[0:3]
	v_mfma_f32_16x16x32_bf16 v[52:55], v[216:219], v[168:171], v[52:55]
	v_mfma_f32_16x16x32_bf16 v[48:51], v[224:227], v[168:171], v[48:51]
	v_mfma_f32_16x16x32_bf16 v[36:39], v[216:219], v[176:179], v[36:39]
	v_mfma_f32_16x16x32_bf16 v[32:35], v[224:227], v[176:179], v[32:35]
	v_mfma_f32_16x16x32_bf16 v[20:23], v[216:219], v[200:203], v[20:23]
	v_mfma_f32_16x16x32_bf16 v[16:19], v[224:227], v[200:203], v[16:19]
	v_mfma_f32_16x16x32_bf16 v[4:7], v[216:219], v[208:211], v[4:7]
	v_mfma_f32_16x16x32_bf16 v[0:3], v[224:227], v[208:211], v[0:3]
	s_add_i32 s50, s50, 2
	s_add_u32 s2, s2, 0x100
	s_addc_u32 s3, s3, 0
	s_add_u32 s37, s37, 0x100
	s_addc_u32 s49, s49, 0
	s_cmp_gt_u32 s50, 13
	s_barrier
	s_cbranch_scc0 .LBB0_370
	v_mov_b32_e32 v128, v182
	s_lshl_b32 s2, s22, 10
	v_and_or_b32 v160, v128, 15, s44
	v_lshrrev_b32_e32 v128, 1, v128
	s_add_i32 s2, s2, 0
	v_and_b32_e32 v146, 24, v128
	v_lshl_add_u32 v128, v160, 2, s2
	v_add_u32_e32 v159, 0x20000, v128
	s_lshl_b32 s13, s28, 8
	s_lshl_b32 s3, s23, 8
	ds_read_b32 v154, v159
	v_add_u32_e32 v150, s13, v160
	s_or_b32 s20, s3, s45
	v_ashrrev_i32_e32 v151, 31, v150
	s_cmpk_gt_i32 s20, 0x3ff
	v_lshlrev_b64 v[128:129], 11, v[150:151]
	v_or_b32_e32 v148, s20, v146
	s_cselect_b64 s[4:5], -1, 0
	s_cmpk_gt_u32 s3, 0x7ff
	s_cselect_b64 s[2:3], -1, 0
	v_mov_b32_e32 v144, v148
	v_lshl_add_u64 v[152:153], s[10:11], 0, v[128:129]
	s_mov_b64 s[22:23], -1
	s_and_b64 vcc, exec, s[4:5]
	s_cbranch_vccz .LBB0_377
	s_waitcnt lgkmcnt(0)
	v_pk_mul_f32 v[128:129], v[124:125], v[154:155] op_sel_hi:[1,0]
	v_pk_mul_f32 v[130:131], v[126:127], v[154:155] op_sel_hi:[1,0]
	v_cvt_pk_bf16_f32 v128, v128, v129
	v_cvt_pk_bf16_f32 v129, v130, v131
	v_pk_mul_f32 v[130:131], v[120:121], v[154:155] op_sel_hi:[1,0]
	v_pk_mul_f32 v[162:163], v[122:123], v[154:155] op_sel_hi:[1,0]
	v_lshl_add_u64 v[156:157], v[144:145], 1, v[152:153]
	v_cvt_pk_bf16_f32 v130, v130, v131
	v_cvt_pk_bf16_f32 v131, v162, v163
	s_and_b64 vcc, exec, s[2:3]
	s_cbranch_vccz .LBB0_374
	v_add_co_u32_e32 v162, vcc, 0x7fff000, v156
	s_mov_b64 s[22:23], 0
	s_nop 0
	v_addc_co_u32_e32 v163, vcc, 0, v157, vcc
	global_store_dwordx4 v[162:163], v[128:131], off

; #define PG8_STAGE(bufoff, gbase, voff) do { _Pragma("unroll") for (int _i = 0; _i < 2; ++_i) \
;     __builtin_amdgcn_global_load_lds((const unsigned*)((const char*)(gbase) + (voff)[_i]), (LAS unsigned*)(lds + (bufoff) + ldsw + _i * 8192), 16, 0, 0); } while (0)
; #define PG8_LDA(dst, b, h) do { _Pragma("unroll") for (int m = 0; m < 4; ++m) _Pragma("unroll") for (int k = 0; k < 2; ++k) dst[m][k] = *(const LAS bf16x8*)(lds + PG8_SA(b, h) + aoff + m * 2048 + k * 1024); } while (0)
; #define PG8_LDB(dst, b, h) do { _Pragma("unroll") for (int n = 0; n < 2; ++n) _Pragma("unroll") for (int k = 0; k < 2; ++k) dst[n][k] = *(const LAS bf16x8*)(lds + PG8_SB(b, h) + boff + n * 2048 + k * 1024); } while (0)
; #define PG8_MMA(ai, bj, At, Bt) do { __builtin_amdgcn_s_setprio(1); _Pragma("unroll") for (int m = 0; m < 4; ++m) _Pragma("unroll") for (int n = 0; n < 2; ++n) _Pragma("unroll") for (int k = 0; k < 2; ++k) \
;     acc[ai][bj][m][n] = __builtin_amdgcn_mfma_f32_16x16x32_bf16(Bt[n][k], At[m][k], acc[ai][bj][m][n], 0, 0, 0); __builtin_amdgcn_s_setprio(0); } while (0)
; #define PG8_WAIT_L(n) asm volatile("s_waitcnt lgkmcnt(" #n ")" ::: "memory")
; #define PG8_BAR __builtin_amdgcn_s_barrier()
; #define PG8_SCHED __builtin_amdgcn_sched_barrier(0)
; template <class Epi, class Sched>
; DI void gemm_phase(LAS unsigned char* lds, const Gemm g, const Sched& S, const Epi& E) {
;     ...
;     for (int t = 0; t < nt; t += 2) {
;       const bool last = (t == nt - 2);
;       const char* a1 = cA + (size_t)(t + 1) * kstep;
;       const char* a2 = last ? nA : cA + (size_t)(t + 2) * kstep; const char* b2 = last ? nB : cB + (size_t)(t + 2) * kstep;
;       const char* a3 = a2 + kstep; const char* b3 = b2 + kstep;
;       PG8_LDB(B0, 0, 0); PG8_SCHED; PG8_LDA(At, 0, 0); PG8_STAGE(PG8_SA(1, 1), a1 + hstep, voffA);
;       PG8_WAIT_L(8); PG8_BAR; PG8_WAIT_L(0); PG8_MMA(0, 0, At, B0); PG8_BAR; PG8_SCHED;
;       PG8_LDB(B1, 0, 1); PG8_STAGE(PG8_SB(0, 0), b2, voffB);
;     ...
; #pragma unroll
;     for (int a = 0; a < 2; ++a)
; #pragma unroll
;       for (int b = 0; b < 2; ++b)
; #pragma unroll
;         for (int m = 0; m < 4; ++m)
; #pragma unroll
;           for (int n = 0; n < 2; ++n) acc[a][b][m][n] = (f32x4){0.f, 0.f, 0.f, 0.f};
;     cur = nxt; cA = nA; cB = nB; ++ui;
.LBB0_688:
	v_readlane_b32 s18, v238, 51
	v_readlane_b32 s19, v238, 52
	s_ashr_i32 s13, s12, 31
	s_mov_b32 s41, -2
	v_mov_b64_e32 v[0:1], s[18:19]
	v_cmp_lt_i64_e32 vcc, s[16:17], v[0:1]
	s_lshl_b64 s[16:17], s[12:13], 19
	s_add_u32 s16, s53, s16
	s_addc_u32 s17, s54, s17
	s_and_b64 s[18:19], vcc, exec
	s_cselect_b32 s13, s17, s21
	s_cselect_b32 s37, s16, s20
	s_ashr_i32 s15, s14, 31
	s_lshl_b64 s[18:19], s[14:15], 19
	s_add_u32 s18, s24, s18
	s_addc_u32 s19, s55, s19
	s_and_b64 s[28:29], vcc, exec
	s_cselect_b32 s15, s19, s23
	s_cselect_b32 s38, s18, s22
	s_add_u32 s20, s20, 0x40080
	s_addc_u32 s21, s21, 0
	s_add_u32 s39, s22, 0x100
	v_mov_b32_e32 v0, 0
	s_addc_u32 s40, s23, 0
	v_mov_b32_e32 v1, v0
	v_mov_b64_e32 v[2:3], v[0:1]
	v_mov_b64_e32 v[4:5], v[0:1]
	v_mov_b64_e32 v[6:7], v[0:1]
	v_mov_b64_e32 v[8:9], v[0:1]
	v_mov_b64_e32 v[10:11], v[0:1]
	v_mov_b64_e32 v[12:13], v[0:1]
	v_mov_b64_e32 v[14:15], v[0:1]
	v_mov_b64_e32 v[16:17], v[0:1]
	v_mov_b64_e32 v[18:19], v[0:1]
	v_mov_b64_e32 v[20:21], v[0:1]
	v_mov_b64_e32 v[22:23], v[0:1]
	v_mov_b64_e32 v[24:25], v[0:1]
	v_mov_b64_e32 v[26:27], v[0:1]
	v_mov_b64_e32 v[28:29], v[0:1]
	v_mov_b64_e32 v[30:31], v[0:1]
	v_mov_b64_e32 v[32:33], v[0:1]
	v_mov_b64_e32 v[34:35], v[0:1]
	v_mov_b64_e32 v[36:37], v[0:1]
	v_mov_b64_e32 v[38:39], v[0:1]
	v_mov_b64_e32 v[40:41], v[0:1]
	v_mov_b64_e32 v[42:43], v[0:1]
	v_mov_b64_e32 v[44:45], v[0:1]
	v_mov_b64_e32 v[46:47], v[0:1]
	v_mov_b64_e32 v[48:49], v[0:1]
	v_mov_b64_e32 v[50:51], v[0:1]
	v_mov_b64_e32 v[52:53], v[0:1]
	v_mov_b64_e32 v[54:55], v[0:1]
	v_mov_b64_e32 v[56:57], v[0:1]
	v_mov_b64_e32 v[58:59], v[0:1]
	v_mov_b64_e32 v[60:61], v[0:1]
	v_mov_b64_e32 v[62:63], v[0:1]
	v_mov_b64_e32 v[64:65], v[0:1]
	v_mov_b64_e32 v[66:67], v[0:1]
	v_mov_b64_e32 v[68:69], v[0:1]
	v_mov_b64_e32 v[70:71], v[0:1]
	v_mov_b64_e32 v[72:73], v[0:1]
	v_mov_b64_e32 v[74:75], v[0:1]
	v_mov_b64_e32 v[76:77], v[0:1]
	v_mov_b64_e32 v[78:79], v[0:1]
	v_mov_b64_e32 v[80:81], v[0:1]
	v_mov_b64_e32 v[82:83], v[0:1]
	v_mov_b64_e32 v[84:85], v[0:1]
	v_mov_b64_e32 v[86:87], v[0:1]
	v_mov_b64_e32 v[88:89], v[0:1]
	v_mov_b64_e32 v[90:91], v[0:1]
	v_mov_b64_e32 v[92:93], v[0:1]
	v_mov_b64_e32 v[94:95], v[0:1]
	v_mov_b64_e32 v[96:97], v[0:1]
	v_mov_b64_e32 v[98:99], v[0:1]
	v_mov_b64_e32 v[100:101], v[0:1]
	v_mov_b64_e32 v[102:103], v[0:1]
	v_mov_b64_e32 v[104:105], v[0:1]
	v_mov_b64_e32 v[106:107], v[0:1]
	v_mov_b64_e32 v[108:109], v[0:1]
	v_mov_b64_e32 v[110:111], v[0:1]
	v_mov_b64_e32 v[112:113], v[0:1]
	v_mov_b64_e32 v[114:115], v[0:1]
	v_mov_b64_e32 v[116:117], v[0:1]
	v_mov_b64_e32 v[118:119], v[0:1]
	v_mov_b64_e32 v[120:121], v[0:1]
	v_mov_b64_e32 v[122:123], v[0:1]
	v_mov_b64_e32 v[124:125], v[0:1]
	v_mov_b64_e32 v[126:127], v[0:1]
	v_add_u32_e32 v222, 0x10000, v196
	v_add_u32_e32 v223, 0x14000, v196
	v_add_u32_e32 v224, 0x18000, v196
	v_add_u32_e32 v225, 0x1c000, v196
.LBB0_689:
	s_add_u32 s22, s20, 0xfffc0080
	s_addc_u32 s23, s21, -1
	s_add_i32 s42, 0, 0x10000
	ds_read_b128 v[128:131], v222
	ds_read_b128 v[132:135], v222 offset:1024
	ds_read_b128 v[150:153], v222 offset:2048
	ds_read_b128 v[154:157], v222 offset:3072
	s_cmp_eq_u32 s41, 12
	s_cselect_b32 s29, s13, s23
	s_cselect_b32 s28, s37, s22
	s_cselect_b32 s23, s15, s40
	s_cselect_b32 s22, s38, s39
	s_add_i32 m0, s56, 0xc000
	ds_read_b128 v[158:161], v197
	ds_read_b128 v[162:165], v197 offset:1024
	ds_read_b128 v[166:169], v197 offset:2048
	ds_read_b128 v[170:173], v197 offset:3072
	ds_read_b128 v[174:177], v197 offset:4096
	ds_read_b128 v[178:181], v197 offset:5120
	ds_read_b128 v[198:201], v197 offset:6144
	ds_read_b128 v[202:205], v197 offset:7168
	global_load_lds_dwordx4 v146, s[20:21]
	s_add_i32 m0, s56, 0xe000
	s_nop 0
	global_load_lds_dwordx4 v148, s[20:21]
	s_waitcnt lgkmcnt(8)
	s_barrier
	s_waitcnt lgkmcnt(0)
	s_waitcnt lgkmcnt(0)
	v_mfma_f32_16x16x32_bf16 v[124:127], v[128:131], v[158:161], v[124:127]
	v_mfma_f32_16x16x32_bf16 v[120:123], v[150:153], v[158:161], v[120:123]
	v_mfma_f32_16x16x32_bf16 v[108:111], v[128:131], v[166:169], v[108:111]
	v_mfma_f32_16x16x32_bf16 v[104:107], v[150:153], v[166:169], v[104:107]
	v_mfma_f32_16x16x32_bf16 v[92:95], v[128:131], v[174:177], v[92:95]
	v_mfma_f32_16x16x32_bf16 v[88:91], v[150:153], v[174:177], v[88:91]
	v_mfma_f32_16x16x32_bf16 v[76:79], v[128:131], v[198:201], v[76:79]
	v_mfma_f32_16x16x32_bf16 v[72:75], v[150:153], v[198:201], v[72:75]
	v_mfma_f32_16x16x32_bf16 v[124:127], v[132:135], v[162:165], v[124:127]
	v_mfma_f32_16x16x32_bf16 v[120:123], v[154:157], v[162:165], v[120:123]
	v_mfma_f32_16x16x32_bf16 v[108:111], v[132:135], v[170:173], v[108:111]
	v_mfma_f32_16x16x32_bf16 v[104:107], v[154:157], v[170:173], v[104:107]
	v_mfma_f32_16x16x32_bf16 v[92:95], v[132:135], v[178:181], v[92:95]
	v_mfma_f32_16x16x32_bf16 v[88:91], v[154:157], v[178:181], v[88:91]
	v_mfma_f32_16x16x32_bf16 v[76:79], v[132:135], v[202:205], v[76:79]
	v_mfma_f32_16x16x32_bf16 v[72:75], v[154:157], v[202:205], v[72:75]
	s_barrier
	s_add_i32 s44, 0, 0x14000
	s_add_i32 s42, s42, s52
	s_add_u32 vcc_lo, s22, s0
	s_addc_u32 vcc_hi, s23, s1
	s_mov_b32 m0, s42
	ds_read_b128 v[206:209], v223
	ds_read_b128 v[210:213], v223 offset:1024
	ds_read_b128 v[214:217], v223 offset:2048
	ds_read_b128 v[218:221], v223 offset:3072
	global_load_lds_dwordx4 v140, s[22:23]
	s_add_i32 m0, s42, 0x2000
	s_nop 0
	global_load_lds_dwordx4 v136, s[22:23]
	s_barrier
; #define PG8_STAGE(bufoff, gbase, voff) do { _Pragma("unroll") for (int _i = 0; _i < 2; ++_i) \
;     __builtin_amdgcn_global_load_lds((const unsigned*)((const char*)(gbase) + (voff)[_i]), (LAS unsigned*)(lds + (bufoff) + ldsw + _i * 8192), 16, 0, 0); } while (0)
; #define PG8_LDA(dst, b, h) do { _Pragma("unroll") for (int m = 0; m < 4; ++m) _Pragma("unroll") for (int k = 0; k < 2; ++k) dst[m][k] = *(const LAS bf16x8*)(lds + PG8_SA(b, h) + aoff + m * 2048 + k * 1024); } while (0)
; #define PG8_LDB(dst, b, h) do { _Pragma("unroll") for (int n = 0; n < 2; ++n) _Pragma("unroll") for (int k = 0; k < 2; ++k) dst[n][k] = *(const LAS bf16x8*)(lds + PG8_SB(b, h) + boff + n * 2048 + k * 1024); } while (0)
; #define PG8_MMA(ai, bj, At, Bt) do { __builtin_amdgcn_s_setprio(1); _Pragma("unroll") for (int m = 0; m < 4; ++m) _Pragma("unroll") for (int n = 0; n < 2; ++n) _Pragma("unroll") for (int k = 0; k < 2; ++k) \
;     acc[ai][bj][m][n] = __builtin_amdgcn_mfma_f32_16x16x32_bf16(Bt[n][k], At[m][k], acc[ai][bj][m][n], 0, 0, 0); __builtin_amdgcn_s_setprio(0); } while (0)
; #define PG8_WAIT_V(n) asm volatile("s_waitcnt vmcnt(" #n ")" ::: "memory")
; #define PG8_WAIT_L(n) asm volatile("s_waitcnt lgkmcnt(" #n ")" ::: "memory")
; #define PG8_BAR __builtin_amdgcn_s_barrier()
; #define PG8_SCHED __builtin_amdgcn_sched_barrier(0)
; template <class Epi, class Sched>
; DI void gemm_phase(LAS unsigned char* lds, const Gemm g, const Sched& S, const Epi& E) {
;     ...
;       PG8_BAR; PG8_WAIT_L(0); PG8_MMA(0, 1, At, B1); PG8_BAR;
;       PG8_LDA(At, 0, 1); PG8_STAGE(PG8_SA(0, 0), a2, voffA);
;       PG8_BAR; PG8_WAIT_L(0); PG8_MMA(1, 0, At, B0); PG8_BAR; PG8_SCHED;
;       PG8_STAGE(PG8_SB(0, 1), b2 + hstep, voffB);
;       PG8_WAIT_V(6); PG8_BAR; PG8_MMA(1, 1, At, B1); PG8_BAR;
;       PG8_LDB(B0, 1, 0); PG8_SCHED; PG8_LDA(At, 1, 0); PG8_STAGE(PG8_SA(0, 1), a2 + hstep, voffA);
;       PG8_WAIT_L(8); PG8_BAR; PG8_WAIT_L(0); PG8_MMA(0, 0, At, B0); PG8_BAR; PG8_SCHED;
;       PG8_LDB(B1, 1, 1); PG8_STAGE(PG8_SB(1, 0), b3, voffB);
;       PG8_BAR; PG8_WAIT_L(0); PG8_MMA(0, 1, At, B1); PG8_BAR;
;       PG8_LDA(At, 1, 1); PG8_STAGE(PG8_SA(1, 0), a3, voffA);
	s_waitcnt lgkmcnt(0)
	s_waitcnt lgkmcnt(0)
	v_mfma_f32_16x16x32_bf16 v[116:119], v[206:209], v[158:161], v[116:119]
	v_mfma_f32_16x16x32_bf16 v[112:115], v[214:217], v[158:161], v[112:115]
	v_mfma_f32_16x16x32_bf16 v[100:103], v[206:209], v[166:169], v[100:103]
	v_mfma_f32_16x16x32_bf16 v[96:99], v[214:217], v[166:169], v[96:99]
	v_mfma_f32_16x16x32_bf16 v[84:87], v[206:209], v[174:177], v[84:87]
	v_mfma_f32_16x16x32_bf16 v[80:83], v[214:217], v[174:177], v[80:83]
	v_mfma_f32_16x16x32_bf16 v[68:71], v[206:209], v[198:201], v[68:71]
	v_mfma_f32_16x16x32_bf16 v[64:67], v[214:217], v[198:201], v[64:67]
	v_mfma_f32_16x16x32_bf16 v[116:119], v[210:213], v[162:165], v[116:119]
	v_mfma_f32_16x16x32_bf16 v[112:115], v[218:221], v[162:165], v[112:115]
	v_mfma_f32_16x16x32_bf16 v[100:103], v[210:213], v[170:173], v[100:103]
	v_mfma_f32_16x16x32_bf16 v[96:99], v[218:221], v[170:173], v[96:99]
	v_mfma_f32_16x16x32_bf16 v[84:87], v[210:213], v[178:181], v[84:87]
	v_mfma_f32_16x16x32_bf16 v[80:83], v[218:221], v[178:181], v[80:83]
	v_mfma_f32_16x16x32_bf16 v[68:71], v[210:213], v[202:205], v[68:71]
	v_mfma_f32_16x16x32_bf16 v[64:67], v[218:221], v[202:205], v[64:67]
	s_mov_b32 m0, s56
	s_add_u32 s100, s28, s0
	s_addc_u32 s101, s29, s1
	s_barrier
	ds_read_b128 v[158:161], v197 offset:16384
	ds_read_b128 v[162:165], v197 offset:17408
	ds_read_b128 v[166:169], v197 offset:18432
	ds_read_b128 v[170:173], v197 offset:19456
	ds_read_b128 v[174:177], v197 offset:20480
	ds_read_b128 v[178:181], v197 offset:21504
	ds_read_b128 v[198:201], v197 offset:22528
	ds_read_b128 v[202:205], v197 offset:23552
	global_load_lds_dwordx4 v142, s[28:29]
	s_mov_b32 m0, s57
	s_nop 0
	global_load_lds_dwordx4 v138, s[28:29]
	s_barrier
	s_waitcnt lgkmcnt(0)
	s_waitcnt lgkmcnt(0)
	v_mfma_f32_16x16x32_bf16 v[60:63], v[128:131], v[158:161], v[60:63]
	v_mfma_f32_16x16x32_bf16 v[56:59], v[150:153], v[158:161], v[56:59]
	v_mfma_f32_16x16x32_bf16 v[44:47], v[128:131], v[166:169], v[44:47]
	v_mfma_f32_16x16x32_bf16 v[40:43], v[150:153], v[166:169], v[40:43]
	v_mfma_f32_16x16x32_bf16 v[28:31], v[128:131], v[174:177], v[28:31]
	v_mfma_f32_16x16x32_bf16 v[24:27], v[150:153], v[174:177], v[24:27]
	v_mfma_f32_16x16x32_bf16 v[12:15], v[128:131], v[198:201], v[12:15]
	v_mfma_f32_16x16x32_bf16 v[8:11], v[150:153], v[198:201], v[8:11]
	v_mfma_f32_16x16x32_bf16 v[60:63], v[132:135], v[162:165], v[60:63]
	v_mfma_f32_16x16x32_bf16 v[56:59], v[154:157], v[162:165], v[56:59]
	v_mfma_f32_16x16x32_bf16 v[44:47], v[132:135], v[170:173], v[44:47]
	v_mfma_f32_16x16x32_bf16 v[40:43], v[154:157], v[170:173], v[40:43]
	v_mfma_f32_16x16x32_bf16 v[28:31], v[132:135], v[178:181], v[28:31]
	v_mfma_f32_16x16x32_bf16 v[24:27], v[154:157], v[178:181], v[24:27]
	v_mfma_f32_16x16x32_bf16 v[12:15], v[132:135], v[202:205], v[12:15]
	v_mfma_f32_16x16x32_bf16 v[8:11], v[154:157], v[202:205], v[8:11]
	s_barrier
	s_add_u32 s42, s22, 0x40000
	s_addc_u32 s43, s23, 0
	s_add_i32 s44, s44, s52
	s_mov_b32 m0, s44
	s_nop 0
	global_load_lds_dwordx4 v140, s[42:43]
	s_add_i32 m0, s44, 0x2000
	s_nop 0
	global_load_lds_dwordx4 v136, s[42:43]
	s_waitcnt vmcnt(6)
	s_barrier
	v_mfma_f32_16x16x32_bf16 v[52:55], v[206:209], v[158:161], v[52:55]
	v_mfma_f32_16x16x32_bf16 v[48:51], v[214:217], v[158:161], v[48:51]
	v_mfma_f32_16x16x32_bf16 v[36:39], v[206:209], v[166:169], v[36:39]
	v_mfma_f32_16x16x32_bf16 v[32:35], v[214:217], v[166:169], v[32:35]
	v_mfma_f32_16x16x32_bf16 v[20:23], v[206:209], v[174:177], v[20:23]
	v_mfma_f32_16x16x32_bf16 v[16:19], v[214:217], v[174:177], v[16:19]
	v_mfma_f32_16x16x32_bf16 v[4:7], v[206:209], v[198:201], v[4:7]
	v_mfma_f32_16x16x32_bf16 v[0:3], v[214:217], v[198:201], v[0:3]
	v_mfma_f32_16x16x32_bf16 v[52:55], v[210:213], v[162:165], v[52:55]
	v_mfma_f32_16x16x32_bf16 v[48:51], v[218:221], v[162:165], v[48:51]
	v_mfma_f32_16x16x32_bf16 v[36:39], v[210:213], v[170:173], v[36:39]
	v_mfma_f32_16x16x32_bf16 v[32:35], v[218:221], v[170:173], v[32:35]
	v_mfma_f32_16x16x32_bf16 v[20:23], v[210:213], v[178:181], v[20:23]
	v_mfma_f32_16x16x32_bf16 v[16:19], v[218:221], v[178:181], v[16:19]
	v_mfma_f32_16x16x32_bf16 v[4:7], v[210:213], v[202:205], v[4:7]
	v_mfma_f32_16x16x32_bf16 v[0:3], v[218:221], v[202:205], v[0:3]
	s_add_i32 s42, 0, 0x18000
	s_barrier
	ds_read_b128 v[128:131], v224
	ds_read_b128 v[132:135], v224 offset:1024
	ds_read_b128 v[150:153], v224 offset:2048
	ds_read_b128 v[154:157], v224 offset:3072
	s_add_u32 s28, s28, 0x40000
	s_addc_u32 s29, s29, 0
	s_mov_b32 m0, s58
	ds_read_b128 v[158:161], v197 offset:32768
	ds_read_b128 v[162:165], v197 offset:33792
	ds_read_b128 v[166:169], v197 offset:34816
	ds_read_b128 v[170:173], v197 offset:35840
	ds_read_b128 v[174:177], v197 offset:36864
	ds_read_b128 v[178:181], v197 offset:37888
	ds_read_b128 v[198:201], v197 offset:38912
	ds_read_b128 v[202:205], v197 offset:39936
	global_load_lds_dwordx4 v142, s[28:29]
	s_mov_b32 m0, s59
	s_nop 0
	global_load_lds_dwordx4 v138, s[28:29]
	s_waitcnt lgkmcnt(8)
	s_barrier
	s_waitcnt lgkmcnt(0)
	s_waitcnt lgkmcnt(0)
	v_mfma_f32_16x16x32_bf16 v[124:127], v[128:131], v[158:161], v[124:127]
	v_mfma_f32_16x16x32_bf16 v[120:123], v[150:153], v[158:161], v[120:123]
	v_mfma_f32_16x16x32_bf16 v[108:111], v[128:131], v[166:169], v[108:111]
	v_mfma_f32_16x16x32_bf16 v[104:107], v[150:153], v[166:169], v[104:107]
	v_mfma_f32_16x16x32_bf16 v[92:95], v[128:131], v[174:177], v[92:95]
	v_mfma_f32_16x16x32_bf16 v[88:91], v[150:153], v[174:177], v[88:91]
	v_mfma_f32_16x16x32_bf16 v[76:79], v[128:131], v[198:201], v[76:79]
	v_mfma_f32_16x16x32_bf16 v[72:75], v[150:153], v[198:201], v[72:75]
	v_mfma_f32_16x16x32_bf16 v[124:127], v[132:135], v[162:165], v[124:127]
	v_mfma_f32_16x16x32_bf16 v[120:123], v[154:157], v[162:165], v[120:123]
	v_mfma_f32_16x16x32_bf16 v[108:111], v[132:135], v[170:173], v[108:111]
	v_mfma_f32_16x16x32_bf16 v[104:107], v[154:157], v[170:173], v[104:107]
	v_mfma_f32_16x16x32_bf16 v[92:95], v[132:135], v[178:181], v[92:95]
	v_mfma_f32_16x16x32_bf16 v[88:91], v[154:157], v[178:181], v[88:91]
	v_mfma_f32_16x16x32_bf16 v[76:79], v[132:135], v[202:205], v[76:79]
	v_mfma_f32_16x16x32_bf16 v[72:75], v[154:157], v[202:205], v[72:75]
	s_barrier
; #define PG8_STAGE(bufoff, gbase, voff) do { _Pragma("unroll") for (int _i = 0; _i < 2; ++_i) \
;     __builtin_amdgcn_global_load_lds((const unsigned*)((const char*)(gbase) + (voff)[_i]), (LAS unsigned*)(lds + (bufoff) + ldsw + _i * 8192), 16, 0, 0); } while (0)
; #define PG8_LDA(dst, b, h) do { _Pragma("unroll") for (int m = 0; m < 4; ++m) _Pragma("unroll") for (int k = 0; k < 2; ++k) dst[m][k] = *(const LAS bf16x8*)(lds + PG8_SA(b, h) + aoff + m * 2048 + k * 1024); } while (0)
; #define PG8_WAIT_V(n) asm volatile("s_waitcnt vmcnt(" #n ")" ::: "memory")
; #define PG8_WAIT_L(n) asm volatile("s_waitcnt lgkmcnt(" #n ")" ::: "memory")
; #define PG8_BAR __builtin_amdgcn_s_barrier()
; #define PG8_SCHED __builtin_amdgcn_sched_barrier(0)
; template <class Epi, class Sched>
; DI void gemm_phase(LAS unsigned char* lds, const Gemm g, const Sched& S, const Epi& E) {
;     ...
;       PG8_LDA(At, 1, 1); PG8_STAGE(PG8_SA(1, 0), a3, voffA);
;       PG8_BAR; PG8_WAIT_L(0); PG8_MMA(1, 0, At, B0); PG8_BAR; PG8_SCHED;
;       PG8_STAGE(PG8_SB(1, 1), b3 + hstep, voffB);
;       PG8_WAIT_V(6); PG8_BAR; PG8_MMA(1, 1, At, B1); PG8_BAR;
;   DI void operator()(const f32x4 (&acc)[2][2][4][2], const pg8::Unit& u, int wr, int wc, int fr_, int fq_) const {
;     ...
;             if (EPI == EPI_ABIN) {
;               if (n == 0) {
;                 const int gb = u.pn * 256 + bj * 128 + wc * 32; const int f8 = gb + 8 * fq;
;                 const f32x4 v1 = acc[ai][bj][m][1];
;                 if (gb < 384) st_bf8((u16*)(big + E_CQ) + (size_t)token * 384 + f8, v, v1, rinv);
;                 else if (gb < 640) st_bf8((u16*)(big + E_CKV) + (size_t)token * 256 + (f8 - 384), v, v1, rinv);
;                 else if (gb < 672) {
;                   f32x4 a0 = v, a1 = v1;
;                   rope_perm(a0, a1, fq, t_ & 63, tcos, tsin, token & (S_ - 1));
;                   st_bf8((u16*)(big + E_KPE) + (size_t)token * 32 + 8 * fq, a0, a1, rinv);
;                 }
;                 else if (gb < 1184) st_bf8((u16*)(big + E_QNA) + (size_t)token * 512 + (f8 - 672), v, v1, rinv * (0.125f * LOG2E));
;                 else if (gb < 1696) st_bf8((u16*)(big + E_KNA) + (size_t)token * 512 + (f8 - 1184), v, v1, rinv);
;                 else if (gb < 2208) st_bf8((u16*)(big + E_VNAT) + (size_t)token * 512 + (f8 - 1696), v, v1, rinv);
	s_add_i32 s28, 0, 0x1c000
	s_add_i32 s29, s42, s52
	s_mov_b32 m0, s29
	ds_read_b128 v[206:209], v225
	ds_read_b128 v[210:213], v225 offset:1024
	ds_read_b128 v[214:217], v225 offset:2048
	ds_read_b128 v[218:221], v225 offset:3072
	global_load_lds_dwordx4 v140, vcc
	s_add_i32 m0, s29, 0x2000
	s_nop 0
	global_load_lds_dwordx4 v136, vcc
	s_barrier
	s_waitcnt lgkmcnt(0)
	s_waitcnt lgkmcnt(0)
	v_mfma_f32_16x16x32_bf16 v[116:119], v[206:209], v[158:161], v[116:119]
	v_mfma_f32_16x16x32_bf16 v[112:115], v[214:217], v[158:161], v[112:115]
	v_mfma_f32_16x16x32_bf16 v[100:103], v[206:209], v[166:169], v[100:103]
	v_mfma_f32_16x16x32_bf16 v[96:99], v[214:217], v[166:169], v[96:99]
	v_mfma_f32_16x16x32_bf16 v[84:87], v[206:209], v[174:177], v[84:87]
	v_mfma_f32_16x16x32_bf16 v[80:83], v[214:217], v[174:177], v[80:83]
	v_mfma_f32_16x16x32_bf16 v[68:71], v[206:209], v[198:201], v[68:71]
	v_mfma_f32_16x16x32_bf16 v[64:67], v[214:217], v[198:201], v[64:67]
	v_mfma_f32_16x16x32_bf16 v[116:119], v[210:213], v[162:165], v[116:119]
	v_mfma_f32_16x16x32_bf16 v[112:115], v[218:221], v[162:165], v[112:115]
	v_mfma_f32_16x16x32_bf16 v[100:103], v[210:213], v[170:173], v[100:103]
	v_mfma_f32_16x16x32_bf16 v[96:99], v[218:221], v[170:173], v[96:99]
	v_mfma_f32_16x16x32_bf16 v[84:87], v[210:213], v[178:181], v[84:87]
	v_mfma_f32_16x16x32_bf16 v[80:83], v[218:221], v[178:181], v[80:83]
	v_mfma_f32_16x16x32_bf16 v[68:71], v[210:213], v[202:205], v[68:71]
	v_mfma_f32_16x16x32_bf16 v[64:67], v[218:221], v[202:205], v[64:67]
	s_mov_b32 m0, s62
	s_barrier
	ds_read_b128 v[158:161], v197 offset:49152
	ds_read_b128 v[162:165], v197 offset:50176
	ds_read_b128 v[166:169], v197 offset:51200
	ds_read_b128 v[170:173], v197 offset:52224
	ds_read_b128 v[174:177], v197 offset:53248
	ds_read_b128 v[178:181], v197 offset:54272
	ds_read_b128 v[198:201], v197 offset:55296
	ds_read_b128 v[202:205], v197 offset:56320
	global_load_lds_dwordx4 v142, s[100:101]
	s_mov_b32 m0, s63
	s_nop 0
	global_load_lds_dwordx4 v138, s[100:101]
	s_barrier
	s_waitcnt lgkmcnt(0)
	s_waitcnt lgkmcnt(0)
	v_mfma_f32_16x16x32_bf16 v[60:63], v[128:131], v[158:161], v[60:63]
	v_mfma_f32_16x16x32_bf16 v[56:59], v[150:153], v[158:161], v[56:59]
	v_mfma_f32_16x16x32_bf16 v[44:47], v[128:131], v[166:169], v[44:47]
	v_mfma_f32_16x16x32_bf16 v[40:43], v[150:153], v[166:169], v[40:43]
	v_mfma_f32_16x16x32_bf16 v[28:31], v[128:131], v[174:177], v[28:31]
	v_mfma_f32_16x16x32_bf16 v[24:27], v[150:153], v[174:177], v[24:27]
	v_mfma_f32_16x16x32_bf16 v[12:15], v[128:131], v[198:201], v[12:15]
	v_mfma_f32_16x16x32_bf16 v[8:11], v[150:153], v[198:201], v[8:11]
	v_mfma_f32_16x16x32_bf16 v[60:63], v[132:135], v[162:165], v[60:63]
	v_mfma_f32_16x16x32_bf16 v[56:59], v[154:157], v[162:165], v[56:59]
	v_mfma_f32_16x16x32_bf16 v[44:47], v[132:135], v[170:173], v[44:47]
	v_mfma_f32_16x16x32_bf16 v[40:43], v[154:157], v[170:173], v[40:43]
	v_mfma_f32_16x16x32_bf16 v[28:31], v[132:135], v[178:181], v[28:31]
	v_mfma_f32_16x16x32_bf16 v[24:27], v[154:157], v[178:181], v[24:27]
	v_mfma_f32_16x16x32_bf16 v[12:15], v[132:135], v[202:205], v[12:15]
	v_mfma_f32_16x16x32_bf16 v[8:11], v[154:157], v[202:205], v[8:11]
	s_barrier
	s_add_u32 s22, s22, 0x40080
	s_addc_u32 s23, s23, 0
	s_add_i32 s28, s28, s52
	s_mov_b32 m0, s28
	s_nop 0
	global_load_lds_dwordx4 v140, s[22:23]
	s_add_i32 m0, s28, 0x2000
	s_nop 0
	global_load_lds_dwordx4 v136, s[22:23]
	s_waitcnt vmcnt(6)
	s_barrier
	v_mfma_f32_16x16x32_bf16 v[52:55], v[206:209], v[158:161], v[52:55]
	v_mfma_f32_16x16x32_bf16 v[48:51], v[214:217], v[158:161], v[48:51]
	v_mfma_f32_16x16x32_bf16 v[36:39], v[206:209], v[166:169], v[36:39]
	v_mfma_f32_16x16x32_bf16 v[32:35], v[214:217], v[166:169], v[32:35]
	v_mfma_f32_16x16x32_bf16 v[20:23], v[206:209], v[174:177], v[20:23]
	v_mfma_f32_16x16x32_bf16 v[16:19], v[214:217], v[174:177], v[16:19]
	v_mfma_f32_16x16x32_bf16 v[4:7], v[206:209], v[198:201], v[4:7]
	v_mfma_f32_16x16x32_bf16 v[0:3], v[214:217], v[198:201], v[0:3]
	v_mfma_f32_16x16x32_bf16 v[52:55], v[210:213], v[162:165], v[52:55]
	v_mfma_f32_16x16x32_bf16 v[48:51], v[218:221], v[162:165], v[48:51]
	v_mfma_f32_16x16x32_bf16 v[36:39], v[210:213], v[170:173], v[36:39]
	v_mfma_f32_16x16x32_bf16 v[32:35], v[218:221], v[170:173], v[32:35]
	v_mfma_f32_16x16x32_bf16 v[20:23], v[210:213], v[178:181], v[20:23]
	v_mfma_f32_16x16x32_bf16 v[16:19], v[218:221], v[178:181], v[16:19]
	v_mfma_f32_16x16x32_bf16 v[4:7], v[210:213], v[202:205], v[4:7]
	v_mfma_f32_16x16x32_bf16 v[0:3], v[218:221], v[202:205], v[0:3]
	s_add_i32 s41, s41, 2
	s_add_u32 s20, s20, 0x100
	s_addc_u32 s21, s21, 0
	s_add_u32 s39, s39, 0x100
	s_addc_u32 s40, s40, 0
	s_cmp_gt_u32 s41, 13
	s_barrier
	s_cbranch_scc0 .LBB0_689
	v_mov_b32_e32 v128, v182
	s_lshl_b32 s20, s34, 10
	v_bfe_u32 v129, v128, 4, 2
	v_and_or_b32 v201, v128, 15, s60
	s_lshl_b32 s13, s35, 8
	v_lshlrev_b32_e32 v128, 2, v128
	s_movk_i32 s21, 0x80
	s_add_i32 s20, s20, 0
	s_lshl_b32 s15, s36, 8
	v_bitop3_b32 v198, v128, s21, v190 bitop3:0x6c
	v_lshl_add_u32 v128, v201, 2, s20
	s_or_b32 s20, s13, s61
	v_add_u32_e32 v200, 0x20000, v128
	s_cmpk_gt_i32 s20, 0x17f
	ds_read_b32 v156, v200
	s_cselect_b64 s[28:29], -1, 0
	s_cmpk_gt_u32 s13, 0x27f
	s_cselect_b64 s[46:47], -1, 0
	s_cmpk_gt_u32 s20, 0x29f
	s_cselect_b64 s[40:41], -1, 0
	s_cmpk_gt_u32 s20, 0x49f
	v_lshlrev_b32_e32 v144, 3, v129
	v_add_u32_e32 v154, s15, v201
	s_cselect_b64 s[34:35], -1, 0
	s_cmpk_gt_u32 s20, 0x69f
	v_ashrrev_i32_e32 v155, 31, v154
	v_lshlrev_b32_e32 v128, 4, v154
	v_or_b32_e32 v150, s20, v144
	s_cselect_b64 s[22:23], -1, 0
	s_cmpk_lt_u32 s20, 0x8a0
	v_and_b32_e32 v199, 8, v144
	v_cmp_lt_u32_e64 s[92:93], 1, v129
	v_lshlrev_b64 v[164:165], 10, v[154:155]
	s_waitcnt lgkmcnt(0)
	v_mul_f32_e32 v162, 0x3e38aa3b, v156
	v_and_b32_e32 v157, 0xfcf0, v128
	v_lshlrev_b64 v[160:161], 6, v[154:155]
	v_lshlrev_b64 v[158:159], 9, v[154:155]
	s_cselect_b64 s[20:21], -1, 0
	v_mov_b32_e32 v152, v150
	v_mov_b32_e32 v153, v145
	s_mov_b64 s[36:37], -1
	s_and_b64 vcc, exec, s[28:29]
	s_cbranch_vccz .LBB0_714
	s_and_b64 vcc, exec, s[46:47]
	s_cbranch_vccz .LBB0_711
	s_and_b64 vcc, exec, s[40:41]
	s_cbranch_vccz .LBB0_704
	s_and_b64 vcc, exec, s[34:35]
	s_cbranch_vccz .LBB0_701
	s_and_b64 vcc, exec, s[22:23]
	s_cbranch_vccz .LBB0_698
	s_andn2_b64 vcc, exec, s[20:21]
	s_cbranch_vccnz .LBB0_697
	v_lshl_add_u64 v[128:129], s[2:3], 0, v[164:165]
	v_lshl_add_u64 v[132:133], v[152:153], 1, v[128:129]
	v_pk_mul_f32 v[128:129], v[124:125], v[156:157] op_sel_hi:[1,0]
	v_pk_mul_f32 v[130:131], v[126:127], v[156:157] op_sel_hi:[1,0]
	v_cvt_pk_bf16_f32 v128, v128, v129
	v_cvt_pk_bf16_f32 v129, v130, v131
	v_pk_mul_f32 v[130:131], v[120:121], v[156:157] op_sel_hi:[1,0]
	v_pk_mul_f32 v[134:135], v[122:123], v[156:157] op_sel_hi:[1,0]
	v_add_co_u32_e32 v132, vcc, 0x69ff000, v132
	v_cvt_pk_bf16_f32 v130, v130, v131
	v_cvt_pk_bf16_f32 v131, v134, v135
	v_addc_co_u32_e32 v133, vcc, 0, v133, vcc
	global_store_dwordx4 v[132:133], v[128:131], off offset:704

; #define PG8_STAGE(bufoff, gbase, voff) do { _Pragma("unroll") for (int _i = 0; _i < 2; ++_i) \
;     __builtin_amdgcn_global_load_lds((const unsigned*)((const char*)(gbase) + (voff)[_i]), (LAS unsigned*)(lds + (bufoff) + ldsw + _i * 8192), 16, 0, 0); } while (0)
; #define PG8_LDA(dst, b, h) do { _Pragma("unroll") for (int m = 0; m < 4; ++m) _Pragma("unroll") for (int k = 0; k < 2; ++k) dst[m][k] = *(const LAS bf16x8*)(lds + PG8_SA(b, h) + aoff + m * 2048 + k * 1024); } while (0)
; #define PG8_LDB(dst, b, h) do { _Pragma("unroll") for (int n = 0; n < 2; ++n) _Pragma("unroll") for (int k = 0; k < 2; ++k) dst[n][k] = *(const LAS bf16x8*)(lds + PG8_SB(b, h) + boff + n * 2048 + k * 1024); } while (0)
; #define PG8_MMA(ai, bj, At, Bt) do { __builtin_amdgcn_s_setprio(1); _Pragma("unroll") for (int m = 0; m < 4; ++m) _Pragma("unroll") for (int n = 0; n < 2; ++n) _Pragma("unroll") for (int k = 0; k < 2; ++k) \
;     acc[ai][bj][m][n] = __builtin_amdgcn_mfma_f32_16x16x32_bf16(Bt[n][k], At[m][k], acc[ai][bj][m][n], 0, 0, 0); __builtin_amdgcn_s_setprio(0); } while (0)
; #define PG8_WAIT_L(n) asm volatile("s_waitcnt lgkmcnt(" #n ")" ::: "memory")
; #define PG8_BAR __builtin_amdgcn_s_barrier()
; #define PG8_SCHED __builtin_amdgcn_sched_barrier(0)
; template <class Epi, class Sched>
; DI void gemm_phase(LAS unsigned char* lds, const Gemm g, const Sched& S, const Epi& E) {
;     ...
;     for (int t = 0; t < nt; t += 2) {
;       const bool last = (t == nt - 2);
;       const char* a1 = cA + (size_t)(t + 1) * kstep;
;       const char* a2 = last ? nA : cA + (size_t)(t + 2) * kstep; const char* b2 = last ? nB : cB + (size_t)(t + 2) * kstep;
;       const char* a3 = a2 + kstep; const char* b3 = b2 + kstep;
;       PG8_LDB(B0, 0, 0); PG8_SCHED; PG8_LDA(At, 0, 0); PG8_STAGE(PG8_SA(1, 1), a1 + hstep, voffA);
;       PG8_WAIT_L(8); PG8_BAR; PG8_WAIT_L(0); PG8_MMA(0, 0, At, B0); PG8_BAR; PG8_SCHED;
;       PG8_LDB(B1, 0, 1); PG8_STAGE(PG8_SB(0, 0), b2, voffB);
;       PG8_BAR; PG8_WAIT_L(0); PG8_MMA(0, 1, At, B1); PG8_BAR;
;     ...
; #pragma unroll
;     for (int a = 0; a < 2; ++a)
; #pragma unroll
;       for (int b = 0; b < 2; ++b)
; #pragma unroll
;         for (int m = 0; m < 4; ++m)
; #pragma unroll
;           for (int n = 0; n < 2; ++n) acc[a][b][m][n] = (f32x4){0.f, 0.f, 0.f, 0.f};
.LBB0_1201:
	s_add_u32 s52, s20, 0x100
	v_mov_b32_e32 v0, 0
	s_addc_u32 s53, s21, 0
	s_mov_b32 s54, -2
	v_mov_b32_e32 v1, v0
	v_mov_b64_e32 v[2:3], v[0:1]
	v_mov_b64_e32 v[4:5], v[0:1]
	v_mov_b64_e32 v[6:7], v[0:1]
	v_mov_b64_e32 v[8:9], v[0:1]
	v_mov_b64_e32 v[10:11], v[0:1]
	v_mov_b64_e32 v[12:13], v[0:1]
	v_mov_b64_e32 v[14:15], v[0:1]
	v_mov_b64_e32 v[16:17], v[0:1]
	v_mov_b64_e32 v[18:19], v[0:1]
	v_mov_b64_e32 v[20:21], v[0:1]
	v_mov_b64_e32 v[22:23], v[0:1]
	v_mov_b64_e32 v[24:25], v[0:1]
	v_mov_b64_e32 v[26:27], v[0:1]
	v_mov_b64_e32 v[28:29], v[0:1]
	v_mov_b64_e32 v[30:31], v[0:1]
	v_mov_b64_e32 v[32:33], v[0:1]
	v_mov_b64_e32 v[34:35], v[0:1]
	v_mov_b64_e32 v[36:37], v[0:1]
	v_mov_b64_e32 v[38:39], v[0:1]
	v_mov_b64_e32 v[40:41], v[0:1]
	v_mov_b64_e32 v[42:43], v[0:1]
	v_mov_b64_e32 v[44:45], v[0:1]
	v_mov_b64_e32 v[46:47], v[0:1]
	v_mov_b64_e32 v[48:49], v[0:1]
	v_mov_b64_e32 v[50:51], v[0:1]
	v_mov_b64_e32 v[52:53], v[0:1]
	v_mov_b64_e32 v[54:55], v[0:1]
	v_mov_b64_e32 v[56:57], v[0:1]
	v_mov_b64_e32 v[58:59], v[0:1]
	v_mov_b64_e32 v[60:61], v[0:1]
	v_mov_b64_e32 v[62:63], v[0:1]
	v_mov_b64_e32 v[64:65], v[0:1]
	v_mov_b64_e32 v[66:67], v[0:1]
	v_mov_b64_e32 v[68:69], v[0:1]
	v_mov_b64_e32 v[70:71], v[0:1]
	v_mov_b64_e32 v[72:73], v[0:1]
	v_mov_b64_e32 v[74:75], v[0:1]
	v_mov_b64_e32 v[76:77], v[0:1]
	v_mov_b64_e32 v[78:79], v[0:1]
	v_mov_b64_e32 v[80:81], v[0:1]
	v_mov_b64_e32 v[82:83], v[0:1]
	v_mov_b64_e32 v[84:85], v[0:1]
	v_mov_b64_e32 v[86:87], v[0:1]
	v_mov_b64_e32 v[88:89], v[0:1]
	v_mov_b64_e32 v[90:91], v[0:1]
	v_mov_b64_e32 v[92:93], v[0:1]
	v_mov_b64_e32 v[94:95], v[0:1]
	v_mov_b64_e32 v[96:97], v[0:1]
	v_mov_b64_e32 v[98:99], v[0:1]
	v_mov_b64_e32 v[100:101], v[0:1]
	v_mov_b64_e32 v[102:103], v[0:1]
	v_mov_b64_e32 v[104:105], v[0:1]
	v_mov_b64_e32 v[106:107], v[0:1]
	v_mov_b64_e32 v[108:109], v[0:1]
	v_mov_b64_e32 v[110:111], v[0:1]
	v_mov_b64_e32 v[112:113], v[0:1]
	v_mov_b64_e32 v[114:115], v[0:1]
	v_mov_b64_e32 v[116:117], v[0:1]
	v_mov_b64_e32 v[118:119], v[0:1]
	v_mov_b64_e32 v[120:121], v[0:1]
	v_mov_b64_e32 v[122:123], v[0:1]
	v_mov_b64_e32 v[124:125], v[0:1]
	v_mov_b64_e32 v[126:127], v[0:1]
	v_add_u32_e32 v224, 0x10000, v162
	v_add_u32_e32 v225, 0x14000, v162
	v_add_u32_e32 v226, 0x18000, v162
	v_add_u32_e32 v227, 0x1c000, v162
.LBB0_1202:
	s_add_u32 s20, s18, 0x100
	s_addc_u32 s21, s19, 0
	s_add_i32 s55, 0, 0x10000
	ds_read_b128 v[140:143], v224
	ds_read_b128 v[146:149], v224 offset:1024
	ds_read_b128 v[150:153], v224 offset:2048
	ds_read_b128 v[154:157], v224 offset:3072
	s_cmp_eq_u32 s54, 2
	s_cselect_b32 s29, s3, s21
	s_cselect_b32 s28, s2, s20
	s_cselect_b32 s23, s5, s53
	s_cselect_b32 s22, s4, s52
	s_add_i32 m0, s38, 0xc000
	ds_read_b128 v[158:161], v163
	ds_read_b128 v[164:167], v163 offset:1024
	ds_read_b128 v[168:171], v163 offset:2048
	ds_read_b128 v[172:175], v163 offset:3072
	ds_read_b128 v[176:179], v163 offset:4096
	ds_read_b128 v[196:199], v163 offset:5120
	ds_read_b128 v[200:203], v163 offset:6144
	ds_read_b128 v[204:207], v163 offset:7168
	global_load_lds_dwordx4 v136, s[18:19]
	s_add_i32 m0, s38, 0xe000
	s_nop 0
	global_load_lds_dwordx4 v138, s[18:19]
	s_waitcnt lgkmcnt(8)
	s_barrier
	s_waitcnt lgkmcnt(0)
	s_waitcnt lgkmcnt(0)
	v_mfma_f32_16x16x32_bf16 v[124:127], v[140:143], v[158:161], v[124:127]
	v_mfma_f32_16x16x32_bf16 v[120:123], v[150:153], v[158:161], v[120:123]
	v_mfma_f32_16x16x32_bf16 v[108:111], v[140:143], v[168:171], v[108:111]
	v_mfma_f32_16x16x32_bf16 v[104:107], v[150:153], v[168:171], v[104:107]
	v_mfma_f32_16x16x32_bf16 v[92:95], v[140:143], v[176:179], v[92:95]
	v_mfma_f32_16x16x32_bf16 v[88:91], v[150:153], v[176:179], v[88:91]
	v_mfma_f32_16x16x32_bf16 v[76:79], v[140:143], v[200:203], v[76:79]
	v_mfma_f32_16x16x32_bf16 v[72:75], v[150:153], v[200:203], v[72:75]
	v_mfma_f32_16x16x32_bf16 v[124:127], v[146:149], v[164:167], v[124:127]
	v_mfma_f32_16x16x32_bf16 v[120:123], v[154:157], v[164:167], v[120:123]
	v_mfma_f32_16x16x32_bf16 v[108:111], v[146:149], v[172:175], v[108:111]
	v_mfma_f32_16x16x32_bf16 v[104:107], v[154:157], v[172:175], v[104:107]
	v_mfma_f32_16x16x32_bf16 v[92:95], v[146:149], v[196:199], v[92:95]
	v_mfma_f32_16x16x32_bf16 v[88:91], v[154:157], v[196:199], v[88:91]
	v_mfma_f32_16x16x32_bf16 v[76:79], v[146:149], v[204:207], v[76:79]
	v_mfma_f32_16x16x32_bf16 v[72:75], v[154:157], v[204:207], v[72:75]
	s_barrier
	s_add_i32 s56, 0, 0x14000
	s_add_i32 s18, s55, s35
	s_add_u32 vcc_lo, s22, s0
	s_addc_u32 vcc_hi, s23, s1
	s_mov_b32 m0, s18
	ds_read_b128 v[208:211], v225
	ds_read_b128 v[212:215], v225 offset:1024
	ds_read_b128 v[216:219], v225 offset:2048
	ds_read_b128 v[220:223], v225 offset:3072
	global_load_lds_dwordx4 v130, s[22:23]
	s_add_i32 m0, s18, 0x2000
	s_nop 0
	global_load_lds_dwordx4 v134, s[22:23]
	s_barrier
	s_waitcnt lgkmcnt(0)
	s_waitcnt lgkmcnt(0)
	v_mfma_f32_16x16x32_bf16 v[116:119], v[208:211], v[158:161], v[116:119]
	v_mfma_f32_16x16x32_bf16 v[112:115], v[216:219], v[158:161], v[112:115]
	v_mfma_f32_16x16x32_bf16 v[100:103], v[208:211], v[168:171], v[100:103]
	v_mfma_f32_16x16x32_bf16 v[96:99], v[216:219], v[168:171], v[96:99]
	v_mfma_f32_16x16x32_bf16 v[84:87], v[208:211], v[176:179], v[84:87]
	v_mfma_f32_16x16x32_bf16 v[80:83], v[216:219], v[176:179], v[80:83]
	v_mfma_f32_16x16x32_bf16 v[68:71], v[208:211], v[200:203], v[68:71]
	v_mfma_f32_16x16x32_bf16 v[64:67], v[216:219], v[200:203], v[64:67]
	v_mfma_f32_16x16x32_bf16 v[116:119], v[212:215], v[164:167], v[116:119]
	v_mfma_f32_16x16x32_bf16 v[112:115], v[220:223], v[164:167], v[112:115]
	v_mfma_f32_16x16x32_bf16 v[100:103], v[212:215], v[172:175], v[100:103]
	v_mfma_f32_16x16x32_bf16 v[96:99], v[220:223], v[172:175], v[96:99]
	v_mfma_f32_16x16x32_bf16 v[84:87], v[212:215], v[196:199], v[84:87]
	v_mfma_f32_16x16x32_bf16 v[80:83], v[220:223], v[196:199], v[80:83]
	v_mfma_f32_16x16x32_bf16 v[68:71], v[212:215], v[204:207], v[68:71]
	v_mfma_f32_16x16x32_bf16 v[64:67], v[220:223], v[204:207], v[64:67]
	s_mov_b32 m0, s38
	s_add_u32 s100, s28, s0
	s_addc_u32 s101, s29, s1
	s_barrier
; #define PG8_STAGE(bufoff, gbase, voff) do { _Pragma("unroll") for (int _i = 0; _i < 2; ++_i) \
;     __builtin_amdgcn_global_load_lds((const unsigned*)((const char*)(gbase) + (voff)[_i]), (LAS unsigned*)(lds + (bufoff) + ldsw + _i * 8192), 16, 0, 0); } while (0)
; #define PG8_LDA(dst, b, h) do { _Pragma("unroll") for (int m = 0; m < 4; ++m) _Pragma("unroll") for (int k = 0; k < 2; ++k) dst[m][k] = *(const LAS bf16x8*)(lds + PG8_SA(b, h) + aoff + m * 2048 + k * 1024); } while (0)
; #define PG8_LDB(dst, b, h) do { _Pragma("unroll") for (int n = 0; n < 2; ++n) _Pragma("unroll") for (int k = 0; k < 2; ++k) dst[n][k] = *(const LAS bf16x8*)(lds + PG8_SB(b, h) + boff + n * 2048 + k * 1024); } while (0)
; #define PG8_MMA(ai, bj, At, Bt) do { __builtin_amdgcn_s_setprio(1); _Pragma("unroll") for (int m = 0; m < 4; ++m) _Pragma("unroll") for (int n = 0; n < 2; ++n) _Pragma("unroll") for (int k = 0; k < 2; ++k) \
;     acc[ai][bj][m][n] = __builtin_amdgcn_mfma_f32_16x16x32_bf16(Bt[n][k], At[m][k], acc[ai][bj][m][n], 0, 0, 0); __builtin_amdgcn_s_setprio(0); } while (0)
; #define PG8_WAIT_V(n) asm volatile("s_waitcnt vmcnt(" #n ")" ::: "memory")
; #define PG8_WAIT_L(n) asm volatile("s_waitcnt lgkmcnt(" #n ")" ::: "memory")
; #define PG8_BAR __builtin_amdgcn_s_barrier()
; #define PG8_SCHED __builtin_amdgcn_sched_barrier(0)
; template <class Epi, class Sched>
; DI void gemm_phase(LAS unsigned char* lds, const Gemm g, const Sched& S, const Epi& E) {
;     ...
;       PG8_LDA(At, 0, 1); PG8_STAGE(PG8_SA(0, 0), a2, voffA);
;       PG8_BAR; PG8_WAIT_L(0); PG8_MMA(1, 0, At, B0); PG8_BAR; PG8_SCHED;
;       PG8_STAGE(PG8_SB(0, 1), b2 + hstep, voffB);
;       PG8_WAIT_V(6); PG8_BAR; PG8_MMA(1, 1, At, B1); PG8_BAR;
;       PG8_LDB(B0, 1, 0); PG8_SCHED; PG8_LDA(At, 1, 0); PG8_STAGE(PG8_SA(0, 1), a2 + hstep, voffA);
;       PG8_WAIT_L(8); PG8_BAR; PG8_WAIT_L(0); PG8_MMA(0, 0, At, B0); PG8_BAR; PG8_SCHED;
;       PG8_LDB(B1, 1, 1); PG8_STAGE(PG8_SB(1, 0), b3, voffB);
;       PG8_BAR; PG8_WAIT_L(0); PG8_MMA(0, 1, At, B1); PG8_BAR;
;       PG8_LDA(At, 1, 1); PG8_STAGE(PG8_SA(1, 0), a3, voffA);
	ds_read_b128 v[158:161], v163 offset:16384
	ds_read_b128 v[164:167], v163 offset:17408
	ds_read_b128 v[168:171], v163 offset:18432
	ds_read_b128 v[172:175], v163 offset:19456
	ds_read_b128 v[176:179], v163 offset:20480
	ds_read_b128 v[196:199], v163 offset:21504
	ds_read_b128 v[200:203], v163 offset:22528
	ds_read_b128 v[204:207], v163 offset:23552
	global_load_lds_dwordx4 v128, s[28:29]
	s_mov_b32 m0, s39
	s_nop 0
	global_load_lds_dwordx4 v132, s[28:29]
	s_barrier
	s_waitcnt lgkmcnt(0)
	s_waitcnt lgkmcnt(0)
	v_mfma_f32_16x16x32_bf16 v[60:63], v[140:143], v[158:161], v[60:63]
	v_mfma_f32_16x16x32_bf16 v[56:59], v[150:153], v[158:161], v[56:59]
	v_mfma_f32_16x16x32_bf16 v[44:47], v[140:143], v[168:171], v[44:47]
	v_mfma_f32_16x16x32_bf16 v[40:43], v[150:153], v[168:171], v[40:43]
	v_mfma_f32_16x16x32_bf16 v[28:31], v[140:143], v[176:179], v[28:31]
	v_mfma_f32_16x16x32_bf16 v[24:27], v[150:153], v[176:179], v[24:27]
	v_mfma_f32_16x16x32_bf16 v[12:15], v[140:143], v[200:203], v[12:15]
	v_mfma_f32_16x16x32_bf16 v[8:11], v[150:153], v[200:203], v[8:11]
	v_mfma_f32_16x16x32_bf16 v[60:63], v[146:149], v[164:167], v[60:63]
	v_mfma_f32_16x16x32_bf16 v[56:59], v[154:157], v[164:167], v[56:59]
	v_mfma_f32_16x16x32_bf16 v[44:47], v[146:149], v[172:175], v[44:47]
	v_mfma_f32_16x16x32_bf16 v[40:43], v[154:157], v[172:175], v[40:43]
	v_mfma_f32_16x16x32_bf16 v[28:31], v[146:149], v[196:199], v[28:31]
	v_mfma_f32_16x16x32_bf16 v[24:27], v[154:157], v[196:199], v[24:27]
	v_mfma_f32_16x16x32_bf16 v[12:15], v[146:149], v[204:207], v[12:15]
	v_mfma_f32_16x16x32_bf16 v[8:11], v[154:157], v[204:207], v[8:11]
	s_barrier
	s_add_u32 s18, s22, 0x18000
	s_addc_u32 s19, s23, 0
	s_add_i32 s55, s56, s35
	s_mov_b32 m0, s55
	s_nop 0
	global_load_lds_dwordx4 v130, s[18:19]
	s_add_i32 m0, s55, 0x2000
	s_nop 0
	global_load_lds_dwordx4 v134, s[18:19]
	s_waitcnt vmcnt(6)
	s_barrier
	v_mfma_f32_16x16x32_bf16 v[52:55], v[208:211], v[158:161], v[52:55]
	v_mfma_f32_16x16x32_bf16 v[48:51], v[216:219], v[158:161], v[48:51]
	v_mfma_f32_16x16x32_bf16 v[36:39], v[208:211], v[168:171], v[36:39]
	v_mfma_f32_16x16x32_bf16 v[32:35], v[216:219], v[168:171], v[32:35]
	v_mfma_f32_16x16x32_bf16 v[20:23], v[208:211], v[176:179], v[20:23]
	v_mfma_f32_16x16x32_bf16 v[16:19], v[216:219], v[176:179], v[16:19]
	v_mfma_f32_16x16x32_bf16 v[4:7], v[208:211], v[200:203], v[4:7]
	v_mfma_f32_16x16x32_bf16 v[0:3], v[216:219], v[200:203], v[0:3]
	v_mfma_f32_16x16x32_bf16 v[52:55], v[212:215], v[164:167], v[52:55]
	v_mfma_f32_16x16x32_bf16 v[48:51], v[220:223], v[164:167], v[48:51]
	v_mfma_f32_16x16x32_bf16 v[36:39], v[212:215], v[172:175], v[36:39]
	v_mfma_f32_16x16x32_bf16 v[32:35], v[220:223], v[172:175], v[32:35]
	v_mfma_f32_16x16x32_bf16 v[20:23], v[212:215], v[196:199], v[20:23]
	v_mfma_f32_16x16x32_bf16 v[16:19], v[220:223], v[196:199], v[16:19]
	v_mfma_f32_16x16x32_bf16 v[4:7], v[212:215], v[204:207], v[4:7]
	v_mfma_f32_16x16x32_bf16 v[0:3], v[220:223], v[204:207], v[0:3]
	s_add_i32 s55, 0, 0x18000
	s_barrier
	ds_read_b128 v[140:143], v226
	ds_read_b128 v[146:149], v226 offset:1024
	ds_read_b128 v[150:153], v226 offset:2048
	ds_read_b128 v[154:157], v226 offset:3072
	s_add_u32 s18, s28, 0x18000
	s_addc_u32 s19, s29, 0
	s_mov_b32 m0, s40
	ds_read_b128 v[158:161], v163 offset:32768
	ds_read_b128 v[164:167], v163 offset:33792
	ds_read_b128 v[168:171], v163 offset:34816
	ds_read_b128 v[172:175], v163 offset:35840
	ds_read_b128 v[176:179], v163 offset:36864
	ds_read_b128 v[196:199], v163 offset:37888
	ds_read_b128 v[200:203], v163 offset:38912
	ds_read_b128 v[204:207], v163 offset:39936
	global_load_lds_dwordx4 v128, s[18:19]
	s_mov_b32 m0, s41
	s_nop 0
	global_load_lds_dwordx4 v132, s[18:19]
	s_waitcnt lgkmcnt(8)
	s_barrier
	s_waitcnt lgkmcnt(0)
	s_waitcnt lgkmcnt(0)
	v_mfma_f32_16x16x32_bf16 v[124:127], v[140:143], v[158:161], v[124:127]
	v_mfma_f32_16x16x32_bf16 v[120:123], v[150:153], v[158:161], v[120:123]
	v_mfma_f32_16x16x32_bf16 v[108:111], v[140:143], v[168:171], v[108:111]
	v_mfma_f32_16x16x32_bf16 v[104:107], v[150:153], v[168:171], v[104:107]
	v_mfma_f32_16x16x32_bf16 v[92:95], v[140:143], v[176:179], v[92:95]
	v_mfma_f32_16x16x32_bf16 v[88:91], v[150:153], v[176:179], v[88:91]
	v_mfma_f32_16x16x32_bf16 v[76:79], v[140:143], v[200:203], v[76:79]
	v_mfma_f32_16x16x32_bf16 v[72:75], v[150:153], v[200:203], v[72:75]
	v_mfma_f32_16x16x32_bf16 v[124:127], v[146:149], v[164:167], v[124:127]
	v_mfma_f32_16x16x32_bf16 v[120:123], v[154:157], v[164:167], v[120:123]
	v_mfma_f32_16x16x32_bf16 v[108:111], v[146:149], v[172:175], v[108:111]
	v_mfma_f32_16x16x32_bf16 v[104:107], v[154:157], v[172:175], v[104:107]
	v_mfma_f32_16x16x32_bf16 v[92:95], v[146:149], v[196:199], v[92:95]
	v_mfma_f32_16x16x32_bf16 v[88:91], v[154:157], v[196:199], v[88:91]
	v_mfma_f32_16x16x32_bf16 v[76:79], v[146:149], v[204:207], v[76:79]
	v_mfma_f32_16x16x32_bf16 v[72:75], v[154:157], v[204:207], v[72:75]
	s_barrier
	s_add_i32 s28, 0, 0x1c000
	s_add_i32 s18, s55, s35
	s_mov_b32 m0, s18
	ds_read_b128 v[208:211], v227
	ds_read_b128 v[212:215], v227 offset:1024
	ds_read_b128 v[216:219], v227 offset:2048
	ds_read_b128 v[220:223], v227 offset:3072
	global_load_lds_dwordx4 v130, vcc
	s_add_i32 m0, s18, 0x2000
	s_nop 0
	global_load_lds_dwordx4 v134, vcc
	s_barrier
; #define PG8_STAGE(bufoff, gbase, voff) do { _Pragma("unroll") for (int _i = 0; _i < 2; ++_i) \
;     __builtin_amdgcn_global_load_lds((const unsigned*)((const char*)(gbase) + (voff)[_i]), (LAS unsigned*)(lds + (bufoff) + ldsw + _i * 8192), 16, 0, 0); } while (0)
; #define PG8_LDA(dst, b, h) do { _Pragma("unroll") for (int m = 0; m < 4; ++m) _Pragma("unroll") for (int k = 0; k < 2; ++k) dst[m][k] = *(const LAS bf16x8*)(lds + PG8_SA(b, h) + aoff + m * 2048 + k * 1024); } while (0)
; #define PG8_MMA(ai, bj, At, Bt) do { __builtin_amdgcn_s_setprio(1); _Pragma("unroll") for (int m = 0; m < 4; ++m) _Pragma("unroll") for (int n = 0; n < 2; ++n) _Pragma("unroll") for (int k = 0; k < 2; ++k) \
;     acc[ai][bj][m][n] = __builtin_amdgcn_mfma_f32_16x16x32_bf16(Bt[n][k], At[m][k], acc[ai][bj][m][n], 0, 0, 0); __builtin_amdgcn_s_setprio(0); } while (0)
; #define PG8_WAIT_V(n) asm volatile("s_waitcnt vmcnt(" #n ")" ::: "memory")
; #define PG8_WAIT_L(n) asm volatile("s_waitcnt lgkmcnt(" #n ")" ::: "memory")
; #define PG8_BAR __builtin_amdgcn_s_barrier()
; #define PG8_SCHED __builtin_amdgcn_sched_barrier(0)
; template <class Epi, class Sched>
; DI void gemm_phase(LAS unsigned char* lds, const Gemm g, const Sched& S, const Epi& E) {
;     ...
;       PG8_LDA(At, 1, 1); PG8_STAGE(PG8_SA(1, 0), a3, voffA);
;       PG8_BAR; PG8_WAIT_L(0); PG8_MMA(1, 0, At, B0); PG8_BAR; PG8_SCHED;
;       PG8_STAGE(PG8_SB(1, 1), b3 + hstep, voffB);
;       PG8_WAIT_V(6); PG8_BAR; PG8_MMA(1, 1, At, B1); PG8_BAR;
; DI void rope_perm(f32x4& a0, f32x4& a1, int fq, int lane, const float* tcos, const float* tsin, int pos) {
;   f32x4 p0, p1;
; #pragma unroll
;   for (int e = 0; e < 4; ++e) { p0[e] = shx(a0[e], 32, lane); p1[e] = shx(a1[e], 32, lane); }
;   const int jb = 8 * (fq & 1);
;   const f32x4 c0 = *(const f32x4*)(tcos + pos * 16 + jb), c1 = *(const f32x4*)(tcos + pos * 16 + jb + 4);
;   const f32x4 s0 = *(const f32x4*)(tsin + pos * 16 + jb), s1 = *(const f32x4*)(tsin + pos * 16 + jb + 4);
;   if (fq < 2) { a0 = a0 * c0 - p0 * s0; a1 = a1 * c1 - p1 * s1; }
;   else        { a0 = a0 * c0 + p0 * s0; a1 = a1 * c1 + p1 * s1; }
; }
	s_waitcnt lgkmcnt(0)
	s_waitcnt lgkmcnt(0)
	v_mfma_f32_16x16x32_bf16 v[116:119], v[208:211], v[158:161], v[116:119]
	v_mfma_f32_16x16x32_bf16 v[112:115], v[216:219], v[158:161], v[112:115]
	v_mfma_f32_16x16x32_bf16 v[100:103], v[208:211], v[168:171], v[100:103]
	v_mfma_f32_16x16x32_bf16 v[96:99], v[216:219], v[168:171], v[96:99]
	v_mfma_f32_16x16x32_bf16 v[84:87], v[208:211], v[176:179], v[84:87]
	v_mfma_f32_16x16x32_bf16 v[80:83], v[216:219], v[176:179], v[80:83]
	v_mfma_f32_16x16x32_bf16 v[68:71], v[208:211], v[200:203], v[68:71]
	v_mfma_f32_16x16x32_bf16 v[64:67], v[216:219], v[200:203], v[64:67]
	v_mfma_f32_16x16x32_bf16 v[116:119], v[212:215], v[164:167], v[116:119]
	v_mfma_f32_16x16x32_bf16 v[112:115], v[220:223], v[164:167], v[112:115]
	v_mfma_f32_16x16x32_bf16 v[100:103], v[212:215], v[172:175], v[100:103]
	v_mfma_f32_16x16x32_bf16 v[96:99], v[220:223], v[172:175], v[96:99]
	v_mfma_f32_16x16x32_bf16 v[84:87], v[212:215], v[196:199], v[84:87]
	v_mfma_f32_16x16x32_bf16 v[80:83], v[220:223], v[196:199], v[80:83]
	v_mfma_f32_16x16x32_bf16 v[68:71], v[212:215], v[204:207], v[68:71]
	v_mfma_f32_16x16x32_bf16 v[64:67], v[220:223], v[204:207], v[64:67]
	s_mov_b32 m0, s44
	s_barrier
	ds_read_b128 v[158:161], v163 offset:49152
	ds_read_b128 v[164:167], v163 offset:50176
	ds_read_b128 v[168:171], v163 offset:51200
	ds_read_b128 v[172:175], v163 offset:52224
	ds_read_b128 v[176:179], v163 offset:53248
	ds_read_b128 v[196:199], v163 offset:54272
	ds_read_b128 v[200:203], v163 offset:55296
	ds_read_b128 v[204:207], v163 offset:56320
	global_load_lds_dwordx4 v128, s[100:101]
	s_mov_b32 m0, s45
	s_nop 0
	global_load_lds_dwordx4 v132, s[100:101]
	s_barrier
	s_waitcnt lgkmcnt(0)
	s_waitcnt lgkmcnt(0)
	v_mfma_f32_16x16x32_bf16 v[60:63], v[140:143], v[158:161], v[60:63]
	v_mfma_f32_16x16x32_bf16 v[56:59], v[150:153], v[158:161], v[56:59]
	v_mfma_f32_16x16x32_bf16 v[44:47], v[140:143], v[168:171], v[44:47]
	v_mfma_f32_16x16x32_bf16 v[40:43], v[150:153], v[168:171], v[40:43]
	v_mfma_f32_16x16x32_bf16 v[28:31], v[140:143], v[176:179], v[28:31]
	v_mfma_f32_16x16x32_bf16 v[24:27], v[150:153], v[176:179], v[24:27]
	v_mfma_f32_16x16x32_bf16 v[12:15], v[140:143], v[200:203], v[12:15]
	v_mfma_f32_16x16x32_bf16 v[8:11], v[150:153], v[200:203], v[8:11]
	v_mfma_f32_16x16x32_bf16 v[60:63], v[146:149], v[164:167], v[60:63]
	v_mfma_f32_16x16x32_bf16 v[56:59], v[154:157], v[164:167], v[56:59]
	v_mfma_f32_16x16x32_bf16 v[44:47], v[146:149], v[172:175], v[44:47]
	v_mfma_f32_16x16x32_bf16 v[40:43], v[154:157], v[172:175], v[40:43]
	v_mfma_f32_16x16x32_bf16 v[28:31], v[146:149], v[196:199], v[28:31]
	v_mfma_f32_16x16x32_bf16 v[24:27], v[154:157], v[196:199], v[24:27]
	v_mfma_f32_16x16x32_bf16 v[12:15], v[146:149], v[204:207], v[12:15]
	v_mfma_f32_16x16x32_bf16 v[8:11], v[154:157], v[204:207], v[8:11]
	s_barrier
	s_add_u32 s18, s22, 0x18080
	s_addc_u32 s19, s23, 0
	s_add_i32 s22, s28, s35
	s_mov_b32 m0, s22
	s_nop 0
	global_load_lds_dwordx4 v130, s[18:19]
	s_add_i32 m0, s22, 0x2000
	s_nop 0
	global_load_lds_dwordx4 v134, s[18:19]
	s_waitcnt vmcnt(6)
	s_barrier
	v_mfma_f32_16x16x32_bf16 v[52:55], v[208:211], v[158:161], v[52:55]
	v_mfma_f32_16x16x32_bf16 v[48:51], v[216:219], v[158:161], v[48:51]
	v_mfma_f32_16x16x32_bf16 v[36:39], v[208:211], v[168:171], v[36:39]
	v_mfma_f32_16x16x32_bf16 v[32:35], v[216:219], v[168:171], v[32:35]
	v_mfma_f32_16x16x32_bf16 v[20:23], v[208:211], v[176:179], v[20:23]
	v_mfma_f32_16x16x32_bf16 v[16:19], v[216:219], v[176:179], v[16:19]
	v_mfma_f32_16x16x32_bf16 v[4:7], v[208:211], v[200:203], v[4:7]
	v_mfma_f32_16x16x32_bf16 v[0:3], v[216:219], v[200:203], v[0:3]
	v_mfma_f32_16x16x32_bf16 v[52:55], v[212:215], v[164:167], v[52:55]
	v_mfma_f32_16x16x32_bf16 v[48:51], v[220:223], v[164:167], v[48:51]
	v_mfma_f32_16x16x32_bf16 v[36:39], v[212:215], v[172:175], v[36:39]
	v_mfma_f32_16x16x32_bf16 v[32:35], v[220:223], v[172:175], v[32:35]
	v_mfma_f32_16x16x32_bf16 v[20:23], v[212:215], v[196:199], v[20:23]
	v_mfma_f32_16x16x32_bf16 v[16:19], v[220:223], v[196:199], v[16:19]
	v_mfma_f32_16x16x32_bf16 v[4:7], v[212:215], v[204:207], v[4:7]
	v_mfma_f32_16x16x32_bf16 v[0:3], v[220:223], v[204:207], v[0:3]
	s_add_i32 s54, s54, 2
	s_add_u32 s52, s52, 0x100
	s_addc_u32 s53, s53, 0
	s_cmp_gt_u32 s54, 3
	s_mov_b64 s[18:19], s[20:21]
	s_barrier
	s_cbranch_scc0 .LBB0_1202
	v_mov_b32_e32 v140, v182
	s_lshl_b32 s19, s51, 10
	s_lshl_b32 s18, s49, 8
	s_or_b32 s18, s18, s43
	v_and_or_b32 v167, v140, 15, s42
	v_lshlrev_b32_e32 v141, 2, v140
	s_movk_i32 s20, 0x80
	s_add_i32 s19, s19, 0
	v_bitop3_b32 v164, v141, s20, v190 bitop3:0x6c
	v_lshl_add_u32 v141, v167, 2, s19
	s_mul_hi_i32 s19, s18, 0x2aaaaaab
	v_add_u32_e32 v166, 0x20000, v141
	s_lshr_b32 s20, s19, 31
	s_lshr_b32 s19, s19, 4
	s_lshl_b32 s50, s50, 8
	ds_read_b32 v144, v166
	s_add_i32 s19, s19, s20
	v_add_u32_e32 v165, s50, v167
	s_mulk_i32 s19, 0x60
	v_bfe_u32 v168, v140, 4, 2
	v_lshrrev_b32_e32 v140, 1, v140
	v_lshlrev_b32_e32 v141, 4, v165
	s_sub_i32 s19, s18, s19
	v_and_b32_e32 v140, 8, v140
	v_and_b32_e32 v141, 0xfcf0, v141
	s_cmp_eq_u32 s19, 64
	v_cmp_lt_u32_e64 s[78:79], 1, v168
	s_cselect_b64 s[20:21], -1, 0
	s_cmp_lg_u32 s19, 64
	v_lshlrev_b32_e32 v142, 2, v141
	v_lshlrev_b32_e32 v140, 2, v140
	s_cbranch_scc1 .LBB0_1209
	v_mov_b32_e32 v143, v145
	v_lshl_add_u64 v[146:147], s[12:13], 0, v[142:143]
	v_mov_b32_e32 v141, v145
	v_lshl_add_u64 v[152:153], s[14:15], 0, v[142:143]
	v_lshl_add_u64 v[146:147], v[146:147], 0, v[140:141]
	v_lshl_add_u64 v[152:153], v[152:153], 0, v[140:141]
	global_load_dwordx4 v[148:151], v[146:147], off
	global_load_dwordx4 v[154:157], v[152:153], off
	global_load_dwordx4 v[170:173], v[152:153], off offset:16
	global_load_dwordx4 v[174:177], v[146:147], off offset:16
	ds_bpermute_b32 v152, v164, v124
	ds_bpermute_b32 v160, v164, v120
	ds_bpermute_b32 v153, v164, v125
	ds_bpermute_b32 v161, v164, v121
	ds_bpermute_b32 v158, v164, v126
	ds_bpermute_b32 v178, v164, v122
	ds_bpermute_b32 v159, v164, v127
	ds_bpermute_b32 v179, v164, v123
	s_waitcnt vmcnt(0) lgkmcnt(0)
	v_pk_mul_f32 v[154:155], v[154:155], v[152:153]
	v_pk_mul_f32 v[146:147], v[126:127], v[150:151]
	v_pk_mul_f32 v[150:151], v[124:125], v[148:149]
	v_pk_mul_f32 v[158:159], v[156:157], v[158:159]
	v_pk_mul_f32 v[148:149], v[170:171], v[160:161]
	v_pk_mul_f32 v[152:153], v[172:173], v[178:179]
	v_pk_mul_f32 v[156:157], v[122:123], v[176:177]
	v_pk_mul_f32 v[160:161], v[120:121], v[174:175]
	s_and_saveexec_b64 s[22:23], s[78:79]
	s_xor_b64 s[22:23], exec, s[22:23]
	v_pk_add_f32 v[126:127], v[146:147], v[158:159]
	v_pk_add_f32 v[124:125], v[150:151], v[154:155]
	v_pk_add_f32 v[122:123], v[156:157], v[152:153]
	v_pk_add_f32 v[120:121], v[160:161], v[148:149]
	s_andn2_saveexec_b64 s[22:23], s[22:23]
	v_sub_f32_e32 v127, v147, v159
	v_sub_f32_e32 v126, v146, v158
	v_sub_f32_e32 v125, v151, v155
	v_sub_f32_e32 v124, v150, v154
	v_sub_f32_e32 v123, v157, v153
	v_sub_f32_e32 v122, v156, v152
	v_sub_f32_e32 v121, v161, v149
	v_sub_f32_e32 v120, v160, v148
	s_or_b64 exec, exec, s[22:23]

; #define PG8_STAGE(bufoff, gbase, voff) do { _Pragma("unroll") for (int _i = 0; _i < 2; ++_i) \
;     __builtin_amdgcn_global_load_lds((const unsigned*)((const char*)(gbase) + (voff)[_i]), (LAS unsigned*)(lds + (bufoff) + ldsw + _i * 8192), 16, 0, 0); } while (0)
; #define PG8_LDA(dst, b, h) do { _Pragma("unroll") for (int m = 0; m < 4; ++m) _Pragma("unroll") for (int k = 0; k < 2; ++k) dst[m][k] = *(const LAS bf16x8*)(lds + PG8_SA(b, h) + aoff + m * 2048 + k * 1024); } while (0)
; #define PG8_LDB(dst, b, h) do { _Pragma("unroll") for (int n = 0; n < 2; ++n) _Pragma("unroll") for (int k = 0; k < 2; ++k) dst[n][k] = *(const LAS bf16x8*)(lds + PG8_SB(b, h) + boff + n * 2048 + k * 1024); } while (0)
; #define PG8_MMA(ai, bj, At, Bt) do { __builtin_amdgcn_s_setprio(1); _Pragma("unroll") for (int m = 0; m < 4; ++m) _Pragma("unroll") for (int n = 0; n < 2; ++n) _Pragma("unroll") for (int k = 0; k < 2; ++k) \
;     acc[ai][bj][m][n] = __builtin_amdgcn_mfma_f32_16x16x32_bf16(Bt[n][k], At[m][k], acc[ai][bj][m][n], 0, 0, 0); __builtin_amdgcn_s_setprio(0); } while (0)
; #define PG8_WAIT_L(n) asm volatile("s_waitcnt lgkmcnt(" #n ")" ::: "memory")
; #define PG8_BAR __builtin_amdgcn_s_barrier()
; #define PG8_SCHED __builtin_amdgcn_sched_barrier(0)
; template <class Epi, class Sched>
; DI void gemm_phase(LAS unsigned char* lds, const Gemm g, const Sched& S, const Epi& E) {
;     ...
;     for (int t = 0; t < nt; t += 2) {
;       const bool last = (t == nt - 2);
;       const char* a1 = cA + (size_t)(t + 1) * kstep;
;       const char* a2 = last ? nA : cA + (size_t)(t + 2) * kstep; const char* b2 = last ? nB : cB + (size_t)(t + 2) * kstep;
;       const char* a3 = a2 + kstep; const char* b3 = b2 + kstep;
;       PG8_LDB(B0, 0, 0); PG8_SCHED; PG8_LDA(At, 0, 0); PG8_STAGE(PG8_SA(1, 1), a1 + hstep, voffA);
;       PG8_WAIT_L(8); PG8_BAR; PG8_WAIT_L(0); PG8_MMA(0, 0, At, B0); PG8_BAR; PG8_SCHED;
;       PG8_LDB(B1, 0, 1); PG8_STAGE(PG8_SB(0, 0), b2, voffB);
;     ...
; #pragma unroll
;     for (int a = 0; a < 2; ++a)
; #pragma unroll
;       for (int b = 0; b < 2; ++b)
; #pragma unroll
;         for (int m = 0; m < 4; ++m)
; #pragma unroll
;           for (int n = 0; n < 2; ++n) acc[a][b][m][n] = (f32x4){0.f, 0.f, 0.f, 0.f};
.LBB0_1345:
	v_mov_b64_e32 v[0:1], s[30:31]
	s_ashr_i32 s15, s14, 31
	v_cmp_lt_i64_e32 vcc, s[16:17], v[0:1]
	s_lshl_b64 s[16:17], s[14:15], 17
	s_add_u32 s16, s52, s16
	s_addc_u32 s17, s53, s17
	s_and_b64 s[18:19], vcc, exec
	s_cselect_b32 s15, s17, s29
	s_cselect_b32 s21, s16, s28
	s_ashr_i32 s13, s12, 31
	s_lshl_b64 s[18:19], s[12:13], 17
	s_add_u32 s18, s54, s18
	s_addc_u32 s19, s55, s19
	s_and_b64 s[34:35], vcc, exec
	v_mov_b32_e32 v0, 0
	s_cselect_b32 s13, s19, s23
	s_cselect_b32 s24, s18, s22
	s_mov_b64 s[40:41], 0
	s_mov_b64 s[34:35], -1
	s_mov_b64 s[36:37], 0
	v_mov_b32_e32 v1, v0
	v_mov_b64_e32 v[2:3], v[0:1]
	v_mov_b64_e32 v[4:5], v[0:1]
	v_mov_b64_e32 v[6:7], v[0:1]
	v_mov_b64_e32 v[8:9], v[0:1]
	v_mov_b64_e32 v[10:11], v[0:1]
	v_mov_b64_e32 v[12:13], v[0:1]
	v_mov_b64_e32 v[14:15], v[0:1]
	v_mov_b64_e32 v[16:17], v[0:1]
	v_mov_b64_e32 v[18:19], v[0:1]
	v_mov_b64_e32 v[20:21], v[0:1]
	v_mov_b64_e32 v[22:23], v[0:1]
	v_mov_b64_e32 v[24:25], v[0:1]
	v_mov_b64_e32 v[26:27], v[0:1]
	v_mov_b64_e32 v[28:29], v[0:1]
	v_mov_b64_e32 v[30:31], v[0:1]
	v_mov_b64_e32 v[32:33], v[0:1]
	v_mov_b64_e32 v[34:35], v[0:1]
	v_mov_b64_e32 v[36:37], v[0:1]
	v_mov_b64_e32 v[38:39], v[0:1]
	v_mov_b64_e32 v[40:41], v[0:1]
	v_mov_b64_e32 v[42:43], v[0:1]
	v_mov_b64_e32 v[44:45], v[0:1]
	v_mov_b64_e32 v[46:47], v[0:1]
	v_mov_b64_e32 v[48:49], v[0:1]
	v_mov_b64_e32 v[50:51], v[0:1]
	v_mov_b64_e32 v[52:53], v[0:1]
	v_mov_b64_e32 v[54:55], v[0:1]
	v_mov_b64_e32 v[56:57], v[0:1]
	v_mov_b64_e32 v[58:59], v[0:1]
	v_mov_b64_e32 v[60:61], v[0:1]
	v_mov_b64_e32 v[62:63], v[0:1]
	v_mov_b64_e32 v[64:65], v[0:1]
	v_mov_b64_e32 v[66:67], v[0:1]
	v_mov_b64_e32 v[68:69], v[0:1]
	v_mov_b64_e32 v[70:71], v[0:1]
	v_mov_b64_e32 v[72:73], v[0:1]
	v_mov_b64_e32 v[74:75], v[0:1]
	v_mov_b64_e32 v[76:77], v[0:1]
	v_mov_b64_e32 v[78:79], v[0:1]
	v_mov_b64_e32 v[80:81], v[0:1]
	v_mov_b64_e32 v[82:83], v[0:1]
	v_mov_b64_e32 v[84:85], v[0:1]
	v_mov_b64_e32 v[86:87], v[0:1]
	v_mov_b64_e32 v[88:89], v[0:1]
	v_mov_b64_e32 v[90:91], v[0:1]
	v_mov_b64_e32 v[92:93], v[0:1]
	v_mov_b64_e32 v[94:95], v[0:1]
	v_mov_b64_e32 v[96:97], v[0:1]
	v_mov_b64_e32 v[98:99], v[0:1]
	v_mov_b64_e32 v[100:101], v[0:1]
	v_mov_b64_e32 v[102:103], v[0:1]
	v_mov_b64_e32 v[104:105], v[0:1]
	v_mov_b64_e32 v[106:107], v[0:1]
	v_mov_b64_e32 v[108:109], v[0:1]
	v_mov_b64_e32 v[110:111], v[0:1]
	v_mov_b64_e32 v[112:113], v[0:1]
	v_mov_b64_e32 v[114:115], v[0:1]
	v_mov_b64_e32 v[116:117], v[0:1]
	v_mov_b64_e32 v[118:119], v[0:1]
	v_mov_b64_e32 v[120:121], v[0:1]
	v_mov_b64_e32 v[122:123], v[0:1]
	v_mov_b64_e32 v[124:125], v[0:1]
	v_mov_b64_e32 v[126:127], v[0:1]
	v_add_u32_e32 v220, 0x10000, v142
	v_add_u32_e32 v221, 0x14000, v142
	v_add_u32_e32 v222, 0x18000, v142
	v_add_u32_e32 v223, 0x1c000, v142
.LBB0_1346:
	s_add_u32 s48, s28, s40
	s_addc_u32 s49, s29, s41
	s_add_u32 s44, s48, 0x100
	s_addc_u32 s45, s49, 0
	s_and_b64 s[42:43], s[36:37], exec
	s_cselect_b32 s45, s15, s45
	s_cselect_b32 s44, s21, s44
	s_add_u32 s40, s22, s40
	s_addc_u32 s41, s23, s41
	s_add_u32 s40, s40, 0x100
	s_addc_u32 s41, s41, 0
	s_add_i32 s70, 0, 0x10000
	s_and_b64 s[36:37], s[36:37], exec
	s_cselect_b32 s47, s13, s41
	s_cselect_b32 s46, s24, s40
	s_add_u32 s48, s48, 0x10080
	s_addc_u32 s49, s49, 0
	s_add_i32 s74, s70, s51
	s_add_i32 m0, s56, 0xc000
	s_add_i32 s75, s56, 0xe000
	s_add_i32 s73, 0, 0x14000
	s_add_i32 s72, s74, 0x2000
	s_add_u32 s42, s46, 0x10000
	s_addc_u32 s43, s47, 0
	s_add_i32 s69, s73, s51
	ds_read_b128 v[136:139], v220
	ds_read_b128 v[146:149], v220 offset:1024
	ds_read_b128 v[150:153], v220 offset:2048
	ds_read_b128 v[154:157], v220 offset:3072
	s_add_i32 s68, s69, 0x2000
	s_add_i32 s67, 0, 0x18000
	s_add_u32 s40, s44, 0x10000
	s_addc_u32 s41, s45, 0
	s_add_i32 s66, s67, s51
	s_add_i32 s65, 0, 0x1c000
	s_add_i32 s64, s66, 0x2000
	s_add_u32 s36, s46, 0x10080
	s_addc_u32 s37, s47, 0
	s_add_i32 s71, s65, s51
	s_add_i32 s70, s71, 0x2000
	ds_read_b128 v[158:161], v143
	ds_read_b128 v[162:165], v143 offset:1024
	ds_read_b128 v[166:169], v143 offset:2048
	ds_read_b128 v[170:173], v143 offset:3072
	ds_read_b128 v[174:177], v143 offset:4096
	ds_read_b128 v[178:181], v143 offset:5120
	ds_read_b128 v[196:199], v143 offset:6144
	ds_read_b128 v[200:203], v143 offset:7168
	global_load_lds_dwordx4 v128, s[48:49]
	s_mov_b32 m0, s75
	s_nop 0
	global_load_lds_dwordx4 v132, s[48:49]
	s_waitcnt lgkmcnt(8)
	s_barrier
	s_waitcnt lgkmcnt(0)
	s_waitcnt lgkmcnt(0)
	v_mfma_f32_16x16x32_bf16 v[124:127], v[136:139], v[158:161], v[124:127]
	v_mfma_f32_16x16x32_bf16 v[120:123], v[150:153], v[158:161], v[120:123]
	v_mfma_f32_16x16x32_bf16 v[108:111], v[136:139], v[166:169], v[108:111]
	v_mfma_f32_16x16x32_bf16 v[104:107], v[150:153], v[166:169], v[104:107]
	v_mfma_f32_16x16x32_bf16 v[92:95], v[136:139], v[174:177], v[92:95]
	v_mfma_f32_16x16x32_bf16 v[88:91], v[150:153], v[174:177], v[88:91]
	v_mfma_f32_16x16x32_bf16 v[76:79], v[136:139], v[196:199], v[76:79]
	v_mfma_f32_16x16x32_bf16 v[72:75], v[150:153], v[196:199], v[72:75]
	v_mfma_f32_16x16x32_bf16 v[124:127], v[146:149], v[162:165], v[124:127]
	v_mfma_f32_16x16x32_bf16 v[120:123], v[154:157], v[162:165], v[120:123]
	v_mfma_f32_16x16x32_bf16 v[108:111], v[146:149], v[170:173], v[108:111]
	v_mfma_f32_16x16x32_bf16 v[104:107], v[154:157], v[170:173], v[104:107]
	v_mfma_f32_16x16x32_bf16 v[92:95], v[146:149], v[178:181], v[92:95]
	v_mfma_f32_16x16x32_bf16 v[88:91], v[154:157], v[178:181], v[88:91]
	v_mfma_f32_16x16x32_bf16 v[76:79], v[146:149], v[200:203], v[76:79]
	v_mfma_f32_16x16x32_bf16 v[72:75], v[154:157], v[200:203], v[72:75]
	s_barrier
; #define PG8_STAGE(bufoff, gbase, voff) do { _Pragma("unroll") for (int _i = 0; _i < 2; ++_i) \
;     __builtin_amdgcn_global_load_lds((const unsigned*)((const char*)(gbase) + (voff)[_i]), (LAS unsigned*)(lds + (bufoff) + ldsw + _i * 8192), 16, 0, 0); } while (0)
; #define PG8_LDA(dst, b, h) do { _Pragma("unroll") for (int m = 0; m < 4; ++m) _Pragma("unroll") for (int k = 0; k < 2; ++k) dst[m][k] = *(const LAS bf16x8*)(lds + PG8_SA(b, h) + aoff + m * 2048 + k * 1024); } while (0)
; #define PG8_LDB(dst, b, h) do { _Pragma("unroll") for (int n = 0; n < 2; ++n) _Pragma("unroll") for (int k = 0; k < 2; ++k) dst[n][k] = *(const LAS bf16x8*)(lds + PG8_SB(b, h) + boff + n * 2048 + k * 1024); } while (0)
; #define PG8_MMA(ai, bj, At, Bt) do { __builtin_amdgcn_s_setprio(1); _Pragma("unroll") for (int m = 0; m < 4; ++m) _Pragma("unroll") for (int n = 0; n < 2; ++n) _Pragma("unroll") for (int k = 0; k < 2; ++k) \
;     acc[ai][bj][m][n] = __builtin_amdgcn_mfma_f32_16x16x32_bf16(Bt[n][k], At[m][k], acc[ai][bj][m][n], 0, 0, 0); __builtin_amdgcn_s_setprio(0); } while (0)
; #define PG8_WAIT_V(n) asm volatile("s_waitcnt vmcnt(" #n ")" ::: "memory")
; #define PG8_WAIT_L(n) asm volatile("s_waitcnt lgkmcnt(" #n ")" ::: "memory")
; #define PG8_BAR __builtin_amdgcn_s_barrier()
; #define PG8_SCHED __builtin_amdgcn_sched_barrier(0)
; template <class Epi, class Sched>
; DI void gemm_phase(LAS unsigned char* lds, const Gemm g, const Sched& S, const Epi& E) {
;     ...
;       PG8_BAR; PG8_WAIT_L(0); PG8_MMA(0, 1, At, B1); PG8_BAR;
;       PG8_LDA(At, 0, 1); PG8_STAGE(PG8_SA(0, 0), a2, voffA);
;       PG8_BAR; PG8_WAIT_L(0); PG8_MMA(1, 0, At, B0); PG8_BAR; PG8_SCHED;
;       PG8_STAGE(PG8_SB(0, 1), b2 + hstep, voffB);
;       PG8_WAIT_V(6); PG8_BAR; PG8_MMA(1, 1, At, B1); PG8_BAR;
;       PG8_LDB(B0, 1, 0); PG8_SCHED; PG8_LDA(At, 1, 0); PG8_STAGE(PG8_SA(0, 1), a2 + hstep, voffA);
;       PG8_WAIT_L(8); PG8_BAR; PG8_WAIT_L(0); PG8_MMA(0, 0, At, B0); PG8_BAR; PG8_SCHED;
;       PG8_LDB(B1, 1, 1); PG8_STAGE(PG8_SB(1, 0), b3, voffB);
	s_mov_b32 m0, s74
	ds_read_b128 v[204:207], v221
	ds_read_b128 v[208:211], v221 offset:1024
	ds_read_b128 v[212:215], v221 offset:2048
	ds_read_b128 v[216:219], v221 offset:3072
	s_add_u32 vcc_lo, s46, s0
	s_addc_u32 vcc_hi, s47, s1
	global_load_lds_dwordx4 v130, s[46:47]
	s_mov_b32 m0, s72
	s_nop 0
	global_load_lds_dwordx4 v134, s[46:47]
	s_barrier
	s_waitcnt lgkmcnt(0)
	s_waitcnt lgkmcnt(0)
	v_mfma_f32_16x16x32_bf16 v[116:119], v[204:207], v[158:161], v[116:119]
	v_mfma_f32_16x16x32_bf16 v[112:115], v[212:215], v[158:161], v[112:115]
	v_mfma_f32_16x16x32_bf16 v[100:103], v[204:207], v[166:169], v[100:103]
	v_mfma_f32_16x16x32_bf16 v[96:99], v[212:215], v[166:169], v[96:99]
	v_mfma_f32_16x16x32_bf16 v[84:87], v[204:207], v[174:177], v[84:87]
	v_mfma_f32_16x16x32_bf16 v[80:83], v[212:215], v[174:177], v[80:83]
	v_mfma_f32_16x16x32_bf16 v[68:71], v[204:207], v[196:199], v[68:71]
	v_mfma_f32_16x16x32_bf16 v[64:67], v[212:215], v[196:199], v[64:67]
	v_mfma_f32_16x16x32_bf16 v[116:119], v[208:211], v[162:165], v[116:119]
	v_mfma_f32_16x16x32_bf16 v[112:115], v[216:219], v[162:165], v[112:115]
	v_mfma_f32_16x16x32_bf16 v[100:103], v[208:211], v[170:173], v[100:103]
	v_mfma_f32_16x16x32_bf16 v[96:99], v[216:219], v[170:173], v[96:99]
	v_mfma_f32_16x16x32_bf16 v[84:87], v[208:211], v[178:181], v[84:87]
	v_mfma_f32_16x16x32_bf16 v[80:83], v[216:219], v[178:181], v[80:83]
	v_mfma_f32_16x16x32_bf16 v[68:71], v[208:211], v[200:203], v[68:71]
	v_mfma_f32_16x16x32_bf16 v[64:67], v[216:219], v[200:203], v[64:67]
	s_mov_b32 m0, s56
	s_add_u32 s100, s44, s0
	s_addc_u32 s101, s45, s1
	s_barrier
	ds_read_b128 v[158:161], v143 offset:16384
	ds_read_b128 v[162:165], v143 offset:17408
	ds_read_b128 v[166:169], v143 offset:18432
	ds_read_b128 v[170:173], v143 offset:19456
	ds_read_b128 v[174:177], v143 offset:20480
	ds_read_b128 v[178:181], v143 offset:21504
	ds_read_b128 v[196:199], v143 offset:22528
	ds_read_b128 v[200:203], v143 offset:23552
	global_load_lds_dwordx4 v128, s[44:45]
	s_mov_b32 m0, s57
	s_nop 0
	global_load_lds_dwordx4 v132, s[44:45]
	s_barrier
	s_waitcnt lgkmcnt(0)
	s_waitcnt lgkmcnt(0)
	v_mfma_f32_16x16x32_bf16 v[60:63], v[136:139], v[158:161], v[60:63]
	v_mfma_f32_16x16x32_bf16 v[56:59], v[150:153], v[158:161], v[56:59]
	v_mfma_f32_16x16x32_bf16 v[44:47], v[136:139], v[166:169], v[44:47]
	v_mfma_f32_16x16x32_bf16 v[40:43], v[150:153], v[166:169], v[40:43]
	v_mfma_f32_16x16x32_bf16 v[28:31], v[136:139], v[174:177], v[28:31]
	v_mfma_f32_16x16x32_bf16 v[24:27], v[150:153], v[174:177], v[24:27]
	v_mfma_f32_16x16x32_bf16 v[12:15], v[136:139], v[196:199], v[12:15]
	v_mfma_f32_16x16x32_bf16 v[8:11], v[150:153], v[196:199], v[8:11]
	v_mfma_f32_16x16x32_bf16 v[60:63], v[146:149], v[162:165], v[60:63]
	v_mfma_f32_16x16x32_bf16 v[56:59], v[154:157], v[162:165], v[56:59]
	v_mfma_f32_16x16x32_bf16 v[44:47], v[146:149], v[170:173], v[44:47]
	v_mfma_f32_16x16x32_bf16 v[40:43], v[154:157], v[170:173], v[40:43]
	v_mfma_f32_16x16x32_bf16 v[28:31], v[146:149], v[178:181], v[28:31]
	v_mfma_f32_16x16x32_bf16 v[24:27], v[154:157], v[178:181], v[24:27]
	v_mfma_f32_16x16x32_bf16 v[12:15], v[146:149], v[200:203], v[12:15]
	v_mfma_f32_16x16x32_bf16 v[8:11], v[154:157], v[200:203], v[8:11]
	s_barrier
	s_mov_b32 m0, s69
	s_nop 0
	global_load_lds_dwordx4 v130, s[42:43]
	s_mov_b32 m0, s68
	s_nop 0
	global_load_lds_dwordx4 v134, s[42:43]
	s_waitcnt vmcnt(6)
	s_barrier
	v_mfma_f32_16x16x32_bf16 v[52:55], v[204:207], v[158:161], v[52:55]
	v_mfma_f32_16x16x32_bf16 v[48:51], v[212:215], v[158:161], v[48:51]
	v_mfma_f32_16x16x32_bf16 v[36:39], v[204:207], v[166:169], v[36:39]
	v_mfma_f32_16x16x32_bf16 v[32:35], v[212:215], v[166:169], v[32:35]
	v_mfma_f32_16x16x32_bf16 v[20:23], v[204:207], v[174:177], v[20:23]
	v_mfma_f32_16x16x32_bf16 v[16:19], v[212:215], v[174:177], v[16:19]
	v_mfma_f32_16x16x32_bf16 v[4:7], v[204:207], v[196:199], v[4:7]
	v_mfma_f32_16x16x32_bf16 v[0:3], v[212:215], v[196:199], v[0:3]
	v_mfma_f32_16x16x32_bf16 v[52:55], v[208:211], v[162:165], v[52:55]
	v_mfma_f32_16x16x32_bf16 v[48:51], v[216:219], v[162:165], v[48:51]
	v_mfma_f32_16x16x32_bf16 v[36:39], v[208:211], v[170:173], v[36:39]
	v_mfma_f32_16x16x32_bf16 v[32:35], v[216:219], v[170:173], v[32:35]
	v_mfma_f32_16x16x32_bf16 v[20:23], v[208:211], v[178:181], v[20:23]
	v_mfma_f32_16x16x32_bf16 v[16:19], v[216:219], v[178:181], v[16:19]
	v_mfma_f32_16x16x32_bf16 v[4:7], v[208:211], v[200:203], v[4:7]
	v_mfma_f32_16x16x32_bf16 v[0:3], v[216:219], v[200:203], v[0:3]
	s_barrier
	ds_read_b128 v[136:139], v222
	ds_read_b128 v[146:149], v222 offset:1024
	ds_read_b128 v[150:153], v222 offset:2048
	ds_read_b128 v[154:157], v222 offset:3072
	s_mov_b32 m0, s58
	ds_read_b128 v[158:161], v143 offset:32768
	ds_read_b128 v[162:165], v143 offset:33792
	ds_read_b128 v[166:169], v143 offset:34816
	ds_read_b128 v[170:173], v143 offset:35840
	ds_read_b128 v[174:177], v143 offset:36864
	ds_read_b128 v[178:181], v143 offset:37888
	ds_read_b128 v[196:199], v143 offset:38912
	ds_read_b128 v[200:203], v143 offset:39936
	global_load_lds_dwordx4 v128, s[40:41]
	s_mov_b32 m0, s59
	s_nop 0
	global_load_lds_dwordx4 v132, s[40:41]
	s_waitcnt lgkmcnt(8)
	s_barrier
; #define PG8_STAGE(bufoff, gbase, voff) do { _Pragma("unroll") for (int _i = 0; _i < 2; ++_i) \
;     __builtin_amdgcn_global_load_lds((const unsigned*)((const char*)(gbase) + (voff)[_i]), (LAS unsigned*)(lds + (bufoff) + ldsw + _i * 8192), 16, 0, 0); } while (0)
; #define PG8_LDA(dst, b, h) do { _Pragma("unroll") for (int m = 0; m < 4; ++m) _Pragma("unroll") for (int k = 0; k < 2; ++k) dst[m][k] = *(const LAS bf16x8*)(lds + PG8_SA(b, h) + aoff + m * 2048 + k * 1024); } while (0)
; #define PG8_LDB(dst, b, h) do { _Pragma("unroll") for (int n = 0; n < 2; ++n) _Pragma("unroll") for (int k = 0; k < 2; ++k) dst[n][k] = *(const LAS bf16x8*)(lds + PG8_SB(b, h) + boff + n * 2048 + k * 1024); } while (0)
; #define PG8_MMA(ai, bj, At, Bt) do { __builtin_amdgcn_s_setprio(1); _Pragma("unroll") for (int m = 0; m < 4; ++m) _Pragma("unroll") for (int n = 0; n < 2; ++n) _Pragma("unroll") for (int k = 0; k < 2; ++k) \
;     acc[ai][bj][m][n] = __builtin_amdgcn_mfma_f32_16x16x32_bf16(Bt[n][k], At[m][k], acc[ai][bj][m][n], 0, 0, 0); __builtin_amdgcn_s_setprio(0); } while (0)
; #define PG8_WAIT_V(n) asm volatile("s_waitcnt vmcnt(" #n ")" ::: "memory")
; #define PG8_WAIT_L(n) asm volatile("s_waitcnt lgkmcnt(" #n ")" ::: "memory")
; template <class Epi, class Sched>
; DI void gemm_phase(LAS unsigned char* lds, const Gemm g, const Sched& S, const Epi& E) {
;     ...
;       PG8_LDB(B1, 1, 1); PG8_STAGE(PG8_SB(1, 0), b3, voffB);
;       PG8_BAR; PG8_WAIT_L(0); PG8_MMA(0, 1, At, B1); PG8_BAR;
;       PG8_LDA(At, 1, 1); PG8_STAGE(PG8_SA(1, 0), a3, voffA);
;       PG8_BAR; PG8_WAIT_L(0); PG8_MMA(1, 0, At, B0); PG8_BAR; PG8_SCHED;
;       PG8_STAGE(PG8_SB(1, 1), b3 + hstep, voffB);
;       PG8_WAIT_V(6); PG8_BAR; PG8_MMA(1, 1, At, B1); PG8_BAR;
;   DI void operator()(const f32x4 (&acc)[2][2][4][2], const pg8::Unit& u, int wr, int wc, int fr_, int fq_) const {
;     ...
;             } else if (EPI == EPI_UKV) {
;               if (n == 0) {
;                 const int gb = u.pn * 256 + bj * 128 + wc * 32;
;                 const int hd = gb >> 7, within = (gb & 127) + 8 * fq;
;                 const f32x4 v1 = acc[ai][bj][m][1];
;                 if (within < 64) st_bf8((u16*)(big + E_KNOPE) + (size_t)token * 512 + hd * 64 + within, v, v1, rinv);
;                 else st_bf8((u16*)(big + E_VMLAT) + (size_t)token * 512 + hd * 64 + (within - 64), v, v1, rinv);
;               }
	s_waitcnt lgkmcnt(0)
	s_waitcnt lgkmcnt(0)
	v_mfma_f32_16x16x32_bf16 v[124:127], v[136:139], v[158:161], v[124:127]
	v_mfma_f32_16x16x32_bf16 v[120:123], v[150:153], v[158:161], v[120:123]
	v_mfma_f32_16x16x32_bf16 v[108:111], v[136:139], v[166:169], v[108:111]
	v_mfma_f32_16x16x32_bf16 v[104:107], v[150:153], v[166:169], v[104:107]
	v_mfma_f32_16x16x32_bf16 v[92:95], v[136:139], v[174:177], v[92:95]
	v_mfma_f32_16x16x32_bf16 v[88:91], v[150:153], v[174:177], v[88:91]
	v_mfma_f32_16x16x32_bf16 v[76:79], v[136:139], v[196:199], v[76:79]
	v_mfma_f32_16x16x32_bf16 v[72:75], v[150:153], v[196:199], v[72:75]
	v_mfma_f32_16x16x32_bf16 v[124:127], v[146:149], v[162:165], v[124:127]
	v_mfma_f32_16x16x32_bf16 v[120:123], v[154:157], v[162:165], v[120:123]
	v_mfma_f32_16x16x32_bf16 v[108:111], v[146:149], v[170:173], v[108:111]
	v_mfma_f32_16x16x32_bf16 v[104:107], v[154:157], v[170:173], v[104:107]
	v_mfma_f32_16x16x32_bf16 v[92:95], v[146:149], v[178:181], v[92:95]
	v_mfma_f32_16x16x32_bf16 v[88:91], v[154:157], v[178:181], v[88:91]
	v_mfma_f32_16x16x32_bf16 v[76:79], v[146:149], v[200:203], v[76:79]
	v_mfma_f32_16x16x32_bf16 v[72:75], v[154:157], v[200:203], v[72:75]
	s_barrier
	s_mov_b32 m0, s66
	ds_read_b128 v[204:207], v223
	ds_read_b128 v[208:211], v223 offset:1024
	ds_read_b128 v[212:215], v223 offset:2048
	ds_read_b128 v[216:219], v223 offset:3072
	global_load_lds_dwordx4 v130, vcc
	s_mov_b32 m0, s64
	s_nop 0
	global_load_lds_dwordx4 v134, vcc
	s_barrier
	s_waitcnt lgkmcnt(0)
	s_waitcnt lgkmcnt(0)
	v_mfma_f32_16x16x32_bf16 v[116:119], v[204:207], v[158:161], v[116:119]
	v_mfma_f32_16x16x32_bf16 v[112:115], v[212:215], v[158:161], v[112:115]
	v_mfma_f32_16x16x32_bf16 v[100:103], v[204:207], v[166:169], v[100:103]
	v_mfma_f32_16x16x32_bf16 v[96:99], v[212:215], v[166:169], v[96:99]
	v_mfma_f32_16x16x32_bf16 v[84:87], v[204:207], v[174:177], v[84:87]
	v_mfma_f32_16x16x32_bf16 v[80:83], v[212:215], v[174:177], v[80:83]
	v_mfma_f32_16x16x32_bf16 v[68:71], v[204:207], v[196:199], v[68:71]
	v_mfma_f32_16x16x32_bf16 v[64:67], v[212:215], v[196:199], v[64:67]
	v_mfma_f32_16x16x32_bf16 v[116:119], v[208:211], v[162:165], v[116:119]
	v_mfma_f32_16x16x32_bf16 v[112:115], v[216:219], v[162:165], v[112:115]
	v_mfma_f32_16x16x32_bf16 v[100:103], v[208:211], v[170:173], v[100:103]
	v_mfma_f32_16x16x32_bf16 v[96:99], v[216:219], v[170:173], v[96:99]
	v_mfma_f32_16x16x32_bf16 v[84:87], v[208:211], v[178:181], v[84:87]
	v_mfma_f32_16x16x32_bf16 v[80:83], v[216:219], v[178:181], v[80:83]
	v_mfma_f32_16x16x32_bf16 v[68:71], v[208:211], v[200:203], v[68:71]
	v_mfma_f32_16x16x32_bf16 v[64:67], v[216:219], v[200:203], v[64:67]
	s_mov_b32 m0, s62
	s_barrier
	ds_read_b128 v[158:161], v143 offset:49152
	ds_read_b128 v[162:165], v143 offset:50176
	ds_read_b128 v[166:169], v143 offset:51200
	ds_read_b128 v[170:173], v143 offset:52224
	ds_read_b128 v[174:177], v143 offset:53248
	ds_read_b128 v[178:181], v143 offset:54272
	ds_read_b128 v[196:199], v143 offset:55296
	ds_read_b128 v[200:203], v143 offset:56320
	global_load_lds_dwordx4 v128, s[100:101]
	s_mov_b32 m0, s63
	s_nop 0
	global_load_lds_dwordx4 v132, s[100:101]
	s_barrier
	s_waitcnt lgkmcnt(0)
	s_waitcnt lgkmcnt(0)
	v_mfma_f32_16x16x32_bf16 v[60:63], v[136:139], v[158:161], v[60:63]
	v_mfma_f32_16x16x32_bf16 v[56:59], v[150:153], v[158:161], v[56:59]
	v_mfma_f32_16x16x32_bf16 v[44:47], v[136:139], v[166:169], v[44:47]
	v_mfma_f32_16x16x32_bf16 v[40:43], v[150:153], v[166:169], v[40:43]
	v_mfma_f32_16x16x32_bf16 v[28:31], v[136:139], v[174:177], v[28:31]
	v_mfma_f32_16x16x32_bf16 v[24:27], v[150:153], v[174:177], v[24:27]
	v_mfma_f32_16x16x32_bf16 v[12:15], v[136:139], v[196:199], v[12:15]
	v_mfma_f32_16x16x32_bf16 v[8:11], v[150:153], v[196:199], v[8:11]
	v_mfma_f32_16x16x32_bf16 v[60:63], v[146:149], v[162:165], v[60:63]
	v_mfma_f32_16x16x32_bf16 v[56:59], v[154:157], v[162:165], v[56:59]
	v_mfma_f32_16x16x32_bf16 v[44:47], v[146:149], v[170:173], v[44:47]
	v_mfma_f32_16x16x32_bf16 v[40:43], v[154:157], v[170:173], v[40:43]
	v_mfma_f32_16x16x32_bf16 v[28:31], v[146:149], v[178:181], v[28:31]
	v_mfma_f32_16x16x32_bf16 v[24:27], v[154:157], v[178:181], v[24:27]
	v_mfma_f32_16x16x32_bf16 v[12:15], v[146:149], v[200:203], v[12:15]
	v_mfma_f32_16x16x32_bf16 v[8:11], v[154:157], v[200:203], v[8:11]
	s_barrier
	s_mov_b32 m0, s71
	s_nop 0
	global_load_lds_dwordx4 v130, s[36:37]
	s_mov_b32 m0, s70
	s_nop 0
	global_load_lds_dwordx4 v134, s[36:37]
	s_waitcnt vmcnt(6)
	s_barrier
	v_mfma_f32_16x16x32_bf16 v[52:55], v[204:207], v[158:161], v[52:55]
	v_mfma_f32_16x16x32_bf16 v[48:51], v[212:215], v[158:161], v[48:51]
	v_mfma_f32_16x16x32_bf16 v[36:39], v[204:207], v[166:169], v[36:39]
	v_mfma_f32_16x16x32_bf16 v[32:35], v[212:215], v[166:169], v[32:35]
	v_mfma_f32_16x16x32_bf16 v[20:23], v[204:207], v[174:177], v[20:23]
	v_mfma_f32_16x16x32_bf16 v[16:19], v[212:215], v[174:177], v[16:19]
	v_mfma_f32_16x16x32_bf16 v[4:7], v[204:207], v[196:199], v[4:7]
	v_mfma_f32_16x16x32_bf16 v[0:3], v[212:215], v[196:199], v[0:3]
	v_mfma_f32_16x16x32_bf16 v[52:55], v[208:211], v[162:165], v[52:55]
	v_mfma_f32_16x16x32_bf16 v[48:51], v[216:219], v[162:165], v[48:51]
	v_mfma_f32_16x16x32_bf16 v[36:39], v[208:211], v[170:173], v[36:39]
	v_mfma_f32_16x16x32_bf16 v[32:35], v[216:219], v[170:173], v[32:35]
	v_mfma_f32_16x16x32_bf16 v[20:23], v[208:211], v[178:181], v[20:23]
	v_mfma_f32_16x16x32_bf16 v[16:19], v[216:219], v[178:181], v[16:19]
	v_mfma_f32_16x16x32_bf16 v[4:7], v[208:211], v[200:203], v[4:7]
	v_mfma_f32_16x16x32_bf16 v[0:3], v[216:219], v[200:203], v[0:3]
	s_andn2_b64 vcc, exec, s[34:35]
	s_mov_b64 s[36:37], -1
	s_mov_b64 s[34:35], 0
	s_mov_b64 s[40:41], 0x100
	s_barrier
	s_cbranch_vccz .LBB0_1346
	v_mov_b32_e32 v136, v182
	s_lshl_b32 s3, s3, 10
	s_add_i32 s3, s3, 0
	v_and_or_b32 v147, v136, 15, s60
	v_lshl_add_u32 v137, v147, 2, s3
	v_add_u32_e32 v146, 0x20000, v137
	ds_read_b32 v138, v146
	s_lshl_b32 s13, s20, 8
	v_lshrrev_b32_e32 v136, 1, v136
	v_and_or_b32 v139, v136, 24, s61
	v_add_u32_e32 v136, s13, v147
	v_ashrrev_i32_e32 v137, 31, v136
	s_waitcnt lgkmcnt(0)
	v_pk_mul_f32 v[124:125], v[124:125], v[138:139] op_sel_hi:[1,0]
	v_pk_mul_f32 v[126:127], v[126:127], v[138:139] op_sel_hi:[1,0]
	v_pk_mul_f32 v[120:121], v[120:121], v[138:139] op_sel_hi:[1,0]
	v_lshlrev_b64 v[140:141], 10, v[136:137]
	s_lshl_b32 s20, s2, 7
	v_cvt_pk_bf16_f32 v124, v124, v125
	v_cvt_pk_bf16_f32 v125, v126, v127
	v_cvt_pk_bf16_f32 v126, v120, v121
	v_pk_mul_f32 v[120:121], v[122:123], v[138:139] op_sel_hi:[1,0]
	s_ashr_i32 s21, s20, 31
	v_cvt_pk_bf16_f32 v127, v120, v121
	v_lshl_add_u64 v[120:121], s[6:7], 0, v[140:141]
	s_mov_b64 s[2:3], -1
	s_and_b64 vcc, exec, s[4:5]
	v_lshl_add_u64 v[120:121], s[20:21], 1, v[120:121]
	v_lshlrev_b32_e32 v144, 1, v139
	s_cbranch_vccz .LBB0_1349
	v_lshl_add_u64 v[122:123], v[120:121], 0, v[144:145]
	v_add_co_u32_e32 v122, vcc, 0xd9ff000, v122
	s_mov_b64 s[2:3], 0
	s_nop 0
	v_addc_co_u32_e32 v123, vcc, 0, v123, vcc
	global_store_dwordx4 v[122:123], v[124:127], off offset:3968

; #define PG8_STAGE(bufoff, gbase, voff) do { _Pragma("unroll") for (int _i = 0; _i < 2; ++_i) \
;     __builtin_amdgcn_global_load_lds((const unsigned*)((const char*)(gbase) + (voff)[_i]), (LAS unsigned*)(lds + (bufoff) + ldsw + _i * 8192), 16, 0, 0); } while (0)
; #define PG8_LDA(dst, b, h) do { _Pragma("unroll") for (int m = 0; m < 4; ++m) _Pragma("unroll") for (int k = 0; k < 2; ++k) dst[m][k] = *(const LAS bf16x8*)(lds + PG8_SA(b, h) + aoff + m * 2048 + k * 1024); } while (0)
; #define PG8_LDB(dst, b, h) do { _Pragma("unroll") for (int n = 0; n < 2; ++n) _Pragma("unroll") for (int k = 0; k < 2; ++k) dst[n][k] = *(const LAS bf16x8*)(lds + PG8_SB(b, h) + boff + n * 2048 + k * 1024); } while (0)
; #define PG8_MMA(ai, bj, At, Bt) do { __builtin_amdgcn_s_setprio(1); _Pragma("unroll") for (int m = 0; m < 4; ++m) _Pragma("unroll") for (int n = 0; n < 2; ++n) _Pragma("unroll") for (int k = 0; k < 2; ++k) \
;     acc[ai][bj][m][n] = __builtin_amdgcn_mfma_f32_16x16x32_bf16(Bt[n][k], At[m][k], acc[ai][bj][m][n], 0, 0, 0); __builtin_amdgcn_s_setprio(0); } while (0)
; #define PG8_WAIT_L(n) asm volatile("s_waitcnt lgkmcnt(" #n ")" ::: "memory")
; #define PG8_BAR __builtin_amdgcn_s_barrier()
; #define PG8_SCHED __builtin_amdgcn_sched_barrier(0)
; template <class Epi, class Sched>
; DI void gemm_phase(LAS unsigned char* lds, const Gemm g, const Sched& S, const Epi& E) {
;     ...
;     for (int t = 0; t < nt; t += 2) {
;       const bool last = (t == nt - 2);
;       const char* a1 = cA + (size_t)(t + 1) * kstep;
;       const char* a2 = last ? nA : cA + (size_t)(t + 2) * kstep; const char* b2 = last ? nB : cB + (size_t)(t + 2) * kstep;
;       const char* a3 = a2 + kstep; const char* b3 = b2 + kstep;
;       PG8_LDB(B0, 0, 0); PG8_SCHED; PG8_LDA(At, 0, 0); PG8_STAGE(PG8_SA(1, 1), a1 + hstep, voffA);
;       PG8_WAIT_L(8); PG8_BAR; PG8_WAIT_L(0); PG8_MMA(0, 0, At, B0); PG8_BAR; PG8_SCHED;
;       PG8_LDB(B1, 0, 1); PG8_STAGE(PG8_SB(0, 0), b2, voffB);
;     ...
; #pragma unroll
;     for (int a = 0; a < 2; ++a)
; #pragma unroll
;       for (int b = 0; b < 2; ++b)
; #pragma unroll
;         for (int m = 0; m < 4; ++m)
; #pragma unroll
;           for (int n = 0; n < 2; ++n) acc[a][b][m][n] = (f32x4){0.f, 0.f, 0.f, 0.f};
;     cur = nxt; cA = nA; cB = nB; ++ui;
.LBB0_1643:
	v_mov_b64_e32 v[0:1], s[30:31]
	s_ashr_i32 s19, s18, 31
	v_cmp_lt_i64_e32 vcc, s[20:21], v[0:1]
	s_lshl_b64 s[20:21], s[18:19], 19
	s_add_u32 s20, s36, s20
	s_addc_u32 s21, s37, s21
	s_and_b64 s[22:23], vcc, exec
	s_cselect_b32 s19, s21, s3
	s_cselect_b32 s35, s20, s2
	s_ashr_i32 s17, s16, 31
	s_lshl_b64 s[22:23], s[16:17], 19
	s_add_u32 s22, s38, s22
	s_addc_u32 s23, s39, s23
	s_and_b64 s[28:29], vcc, exec
	s_cselect_b32 s17, s23, s5
	s_cselect_b32 s51, s22, s4
	s_add_u32 s2, s2, 0x40080
	s_addc_u32 s3, s3, 0
	s_add_u32 s52, s4, 0x100
	v_mov_b32_e32 v0, 0
	s_addc_u32 s53, s5, 0
	s_mov_b32 s54, -2
	v_mov_b32_e32 v1, v0
	v_mov_b64_e32 v[2:3], v[0:1]
	v_mov_b64_e32 v[4:5], v[0:1]
	v_mov_b64_e32 v[6:7], v[0:1]
	v_mov_b64_e32 v[8:9], v[0:1]
	v_mov_b64_e32 v[10:11], v[0:1]
	v_mov_b64_e32 v[12:13], v[0:1]
	v_mov_b64_e32 v[14:15], v[0:1]
	v_mov_b64_e32 v[16:17], v[0:1]
	v_mov_b64_e32 v[18:19], v[0:1]
	v_mov_b64_e32 v[20:21], v[0:1]
	v_mov_b64_e32 v[22:23], v[0:1]
	v_mov_b64_e32 v[24:25], v[0:1]
	v_mov_b64_e32 v[26:27], v[0:1]
	v_mov_b64_e32 v[28:29], v[0:1]
	v_mov_b64_e32 v[30:31], v[0:1]
	v_mov_b64_e32 v[32:33], v[0:1]
	v_mov_b64_e32 v[34:35], v[0:1]
	v_mov_b64_e32 v[36:37], v[0:1]
	v_mov_b64_e32 v[38:39], v[0:1]
	v_mov_b64_e32 v[40:41], v[0:1]
	v_mov_b64_e32 v[42:43], v[0:1]
	v_mov_b64_e32 v[44:45], v[0:1]
	v_mov_b64_e32 v[46:47], v[0:1]
	v_mov_b64_e32 v[48:49], v[0:1]
	v_mov_b64_e32 v[50:51], v[0:1]
	v_mov_b64_e32 v[52:53], v[0:1]
	v_mov_b64_e32 v[54:55], v[0:1]
	v_mov_b64_e32 v[56:57], v[0:1]
	v_mov_b64_e32 v[58:59], v[0:1]
	v_mov_b64_e32 v[60:61], v[0:1]
	v_mov_b64_e32 v[62:63], v[0:1]
	v_mov_b64_e32 v[64:65], v[0:1]
	v_mov_b64_e32 v[66:67], v[0:1]
	v_mov_b64_e32 v[68:69], v[0:1]
	v_mov_b64_e32 v[70:71], v[0:1]
	v_mov_b64_e32 v[72:73], v[0:1]
	v_mov_b64_e32 v[74:75], v[0:1]
	v_mov_b64_e32 v[76:77], v[0:1]
	v_mov_b64_e32 v[78:79], v[0:1]
	v_mov_b64_e32 v[80:81], v[0:1]
	v_mov_b64_e32 v[82:83], v[0:1]
	v_mov_b64_e32 v[84:85], v[0:1]
	v_mov_b64_e32 v[86:87], v[0:1]
	v_mov_b64_e32 v[88:89], v[0:1]
	v_mov_b64_e32 v[90:91], v[0:1]
	v_mov_b64_e32 v[92:93], v[0:1]
	v_mov_b64_e32 v[94:95], v[0:1]
	v_mov_b64_e32 v[96:97], v[0:1]
	v_mov_b64_e32 v[98:99], v[0:1]
	v_mov_b64_e32 v[100:101], v[0:1]
	v_mov_b64_e32 v[102:103], v[0:1]
	v_mov_b64_e32 v[104:105], v[0:1]
	v_mov_b64_e32 v[106:107], v[0:1]
	v_mov_b64_e32 v[108:109], v[0:1]
	v_mov_b64_e32 v[110:111], v[0:1]
	v_mov_b64_e32 v[112:113], v[0:1]
	v_mov_b64_e32 v[114:115], v[0:1]
	v_mov_b64_e32 v[116:117], v[0:1]
	v_mov_b64_e32 v[118:119], v[0:1]
	v_mov_b64_e32 v[120:121], v[0:1]
	v_mov_b64_e32 v[122:123], v[0:1]
	v_mov_b64_e32 v[124:125], v[0:1]
	v_mov_b64_e32 v[126:127], v[0:1]
	v_add_u32_e32 v224, 0x10000, v158
	v_add_u32_e32 v225, 0x14000, v158
	v_add_u32_e32 v226, 0x18000, v158
	v_add_u32_e32 v227, 0x1c000, v158
.LBB0_1644:
	s_add_u32 s4, s2, 0xfffc0080
	s_addc_u32 s5, s3, -1
	s_add_i32 s55, 0, 0x10000
	ds_read_b128 v[128:131], v224
	ds_read_b128 v[132:135], v224 offset:1024
	ds_read_b128 v[148:151], v224 offset:2048
	ds_read_b128 v[152:155], v224 offset:3072
	s_cmp_eq_u32 s54, 12
	s_cselect_b32 s29, s19, s5
	s_cselect_b32 s28, s35, s4
	s_cselect_b32 s5, s17, s53
	s_cselect_b32 s4, s51, s52
	s_add_i32 m0, s41, 0xc000
	ds_read_b128 v[160:163], v159
	ds_read_b128 v[164:167], v159 offset:1024
	ds_read_b128 v[168:171], v159 offset:2048
	ds_read_b128 v[172:175], v159 offset:3072
	ds_read_b128 v[176:179], v159 offset:4096
	ds_read_b128 v[196:199], v159 offset:5120
	ds_read_b128 v[200:203], v159 offset:6144
	ds_read_b128 v[204:207], v159 offset:7168
	global_load_lds_dwordx4 v142, s[2:3]
	s_add_i32 m0, s41, 0xe000
	s_nop 0
	global_load_lds_dwordx4 v146, s[2:3]
	s_waitcnt lgkmcnt(8)
	s_barrier
	s_waitcnt lgkmcnt(0)
	s_waitcnt lgkmcnt(0)
	v_mfma_f32_16x16x32_bf16 v[124:127], v[128:131], v[160:163], v[124:127]
	v_mfma_f32_16x16x32_bf16 v[120:123], v[148:151], v[160:163], v[120:123]
	v_mfma_f32_16x16x32_bf16 v[108:111], v[128:131], v[168:171], v[108:111]
	v_mfma_f32_16x16x32_bf16 v[104:107], v[148:151], v[168:171], v[104:107]
	v_mfma_f32_16x16x32_bf16 v[92:95], v[128:131], v[176:179], v[92:95]
	v_mfma_f32_16x16x32_bf16 v[88:91], v[148:151], v[176:179], v[88:91]
	v_mfma_f32_16x16x32_bf16 v[76:79], v[128:131], v[200:203], v[76:79]
	v_mfma_f32_16x16x32_bf16 v[72:75], v[148:151], v[200:203], v[72:75]
	v_mfma_f32_16x16x32_bf16 v[124:127], v[132:135], v[164:167], v[124:127]
	v_mfma_f32_16x16x32_bf16 v[120:123], v[152:155], v[164:167], v[120:123]
	v_mfma_f32_16x16x32_bf16 v[108:111], v[132:135], v[172:175], v[108:111]
	v_mfma_f32_16x16x32_bf16 v[104:107], v[152:155], v[172:175], v[104:107]
	v_mfma_f32_16x16x32_bf16 v[92:95], v[132:135], v[196:199], v[92:95]
	v_mfma_f32_16x16x32_bf16 v[88:91], v[152:155], v[196:199], v[88:91]
	v_mfma_f32_16x16x32_bf16 v[76:79], v[132:135], v[204:207], v[76:79]
	v_mfma_f32_16x16x32_bf16 v[72:75], v[152:155], v[204:207], v[72:75]
	s_barrier
	s_add_i32 s58, 0, 0x14000
	s_add_i32 s55, s55, s40
	ds_read_b128 v[208:211], v225
	ds_read_b128 v[212:215], v225 offset:1024
	ds_read_b128 v[216:219], v225 offset:2048
	ds_read_b128 v[220:223], v225 offset:3072
	s_add_u32 vcc_lo, s4, s0
	s_addc_u32 vcc_hi, s5, s1
	s_mov_b32 m0, s55
	s_nop 0
	global_load_lds_dwordx4 v144, s[4:5]
	s_add_i32 m0, s55, 0x2000
	s_nop 0
	global_load_lds_dwordx4 v136, s[4:5]
	s_barrier
; #define PG8_STAGE(bufoff, gbase, voff) do { _Pragma("unroll") for (int _i = 0; _i < 2; ++_i) \
;     __builtin_amdgcn_global_load_lds((const unsigned*)((const char*)(gbase) + (voff)[_i]), (LAS unsigned*)(lds + (bufoff) + ldsw + _i * 8192), 16, 0, 0); } while (0)
; #define PG8_LDA(dst, b, h) do { _Pragma("unroll") for (int m = 0; m < 4; ++m) _Pragma("unroll") for (int k = 0; k < 2; ++k) dst[m][k] = *(const LAS bf16x8*)(lds + PG8_SA(b, h) + aoff + m * 2048 + k * 1024); } while (0)
; #define PG8_LDB(dst, b, h) do { _Pragma("unroll") for (int n = 0; n < 2; ++n) _Pragma("unroll") for (int k = 0; k < 2; ++k) dst[n][k] = *(const LAS bf16x8*)(lds + PG8_SB(b, h) + boff + n * 2048 + k * 1024); } while (0)
; #define PG8_MMA(ai, bj, At, Bt) do { __builtin_amdgcn_s_setprio(1); _Pragma("unroll") for (int m = 0; m < 4; ++m) _Pragma("unroll") for (int n = 0; n < 2; ++n) _Pragma("unroll") for (int k = 0; k < 2; ++k) \
;     acc[ai][bj][m][n] = __builtin_amdgcn_mfma_f32_16x16x32_bf16(Bt[n][k], At[m][k], acc[ai][bj][m][n], 0, 0, 0); __builtin_amdgcn_s_setprio(0); } while (0)
; #define PG8_WAIT_V(n) asm volatile("s_waitcnt vmcnt(" #n ")" ::: "memory")
; #define PG8_WAIT_L(n) asm volatile("s_waitcnt lgkmcnt(" #n ")" ::: "memory")
; #define PG8_BAR __builtin_amdgcn_s_barrier()
; #define PG8_SCHED __builtin_amdgcn_sched_barrier(0)
; template <class Epi, class Sched>
; DI void gemm_phase(LAS unsigned char* lds, const Gemm g, const Sched& S, const Epi& E) {
;     ...
;       PG8_BAR; PG8_WAIT_L(0); PG8_MMA(0, 1, At, B1); PG8_BAR;
;       PG8_LDA(At, 0, 1); PG8_STAGE(PG8_SA(0, 0), a2, voffA);
;       PG8_BAR; PG8_WAIT_L(0); PG8_MMA(1, 0, At, B0); PG8_BAR; PG8_SCHED;
;       PG8_STAGE(PG8_SB(0, 1), b2 + hstep, voffB);
;       PG8_WAIT_V(6); PG8_BAR; PG8_MMA(1, 1, At, B1); PG8_BAR;
;       PG8_LDB(B0, 1, 0); PG8_SCHED; PG8_LDA(At, 1, 0); PG8_STAGE(PG8_SA(0, 1), a2 + hstep, voffA);
;       PG8_WAIT_L(8); PG8_BAR; PG8_WAIT_L(0); PG8_MMA(0, 0, At, B0); PG8_BAR; PG8_SCHED;
;       PG8_LDB(B1, 1, 1); PG8_STAGE(PG8_SB(1, 0), b3, voffB);
;       PG8_BAR; PG8_WAIT_L(0); PG8_MMA(0, 1, At, B1); PG8_BAR;
;       PG8_LDA(At, 1, 1); PG8_STAGE(PG8_SA(1, 0), a3, voffA);
	s_waitcnt lgkmcnt(0)
	s_waitcnt lgkmcnt(0)
	v_mfma_f32_16x16x32_bf16 v[116:119], v[208:211], v[160:163], v[116:119]
	v_mfma_f32_16x16x32_bf16 v[112:115], v[216:219], v[160:163], v[112:115]
	v_mfma_f32_16x16x32_bf16 v[100:103], v[208:211], v[168:171], v[100:103]
	v_mfma_f32_16x16x32_bf16 v[96:99], v[216:219], v[168:171], v[96:99]
	v_mfma_f32_16x16x32_bf16 v[84:87], v[208:211], v[176:179], v[84:87]
	v_mfma_f32_16x16x32_bf16 v[80:83], v[216:219], v[176:179], v[80:83]
	v_mfma_f32_16x16x32_bf16 v[68:71], v[208:211], v[200:203], v[68:71]
	v_mfma_f32_16x16x32_bf16 v[64:67], v[216:219], v[200:203], v[64:67]
	v_mfma_f32_16x16x32_bf16 v[116:119], v[212:215], v[164:167], v[116:119]
	v_mfma_f32_16x16x32_bf16 v[112:115], v[220:223], v[164:167], v[112:115]
	v_mfma_f32_16x16x32_bf16 v[100:103], v[212:215], v[172:175], v[100:103]
	v_mfma_f32_16x16x32_bf16 v[96:99], v[220:223], v[172:175], v[96:99]
	v_mfma_f32_16x16x32_bf16 v[84:87], v[212:215], v[196:199], v[84:87]
	v_mfma_f32_16x16x32_bf16 v[80:83], v[220:223], v[196:199], v[80:83]
	v_mfma_f32_16x16x32_bf16 v[68:71], v[212:215], v[204:207], v[68:71]
	v_mfma_f32_16x16x32_bf16 v[64:67], v[220:223], v[204:207], v[64:67]
	s_mov_b32 m0, s41
	s_add_u32 s100, s28, s0
	s_addc_u32 s101, s29, s1
	s_barrier
	ds_read_b128 v[160:163], v159 offset:16384
	ds_read_b128 v[164:167], v159 offset:17408
	ds_read_b128 v[168:171], v159 offset:18432
	ds_read_b128 v[172:175], v159 offset:19456
	ds_read_b128 v[176:179], v159 offset:20480
	ds_read_b128 v[196:199], v159 offset:21504
	ds_read_b128 v[200:203], v159 offset:22528
	ds_read_b128 v[204:207], v159 offset:23552
	global_load_lds_dwordx4 v140, s[28:29]
	s_mov_b32 m0, s42
	s_nop 0
	global_load_lds_dwordx4 v138, s[28:29]
	s_barrier
	s_waitcnt lgkmcnt(0)
	s_waitcnt lgkmcnt(0)
	v_mfma_f32_16x16x32_bf16 v[60:63], v[128:131], v[160:163], v[60:63]
	v_mfma_f32_16x16x32_bf16 v[56:59], v[148:151], v[160:163], v[56:59]
	v_mfma_f32_16x16x32_bf16 v[44:47], v[128:131], v[168:171], v[44:47]
	v_mfma_f32_16x16x32_bf16 v[40:43], v[148:151], v[168:171], v[40:43]
	v_mfma_f32_16x16x32_bf16 v[28:31], v[128:131], v[176:179], v[28:31]
	v_mfma_f32_16x16x32_bf16 v[24:27], v[148:151], v[176:179], v[24:27]
	v_mfma_f32_16x16x32_bf16 v[12:15], v[128:131], v[200:203], v[12:15]
	v_mfma_f32_16x16x32_bf16 v[8:11], v[148:151], v[200:203], v[8:11]
	v_mfma_f32_16x16x32_bf16 v[60:63], v[132:135], v[164:167], v[60:63]
	v_mfma_f32_16x16x32_bf16 v[56:59], v[152:155], v[164:167], v[56:59]
	v_mfma_f32_16x16x32_bf16 v[44:47], v[132:135], v[172:175], v[44:47]
	v_mfma_f32_16x16x32_bf16 v[40:43], v[152:155], v[172:175], v[40:43]
	v_mfma_f32_16x16x32_bf16 v[28:31], v[132:135], v[196:199], v[28:31]
	v_mfma_f32_16x16x32_bf16 v[24:27], v[152:155], v[196:199], v[24:27]
	v_mfma_f32_16x16x32_bf16 v[12:15], v[132:135], v[204:207], v[12:15]
	v_mfma_f32_16x16x32_bf16 v[8:11], v[152:155], v[204:207], v[8:11]
	s_barrier
	s_add_u32 s56, s4, 0x40000
	s_addc_u32 s57, s5, 0
	s_add_i32 s55, s58, s40
	s_mov_b32 m0, s55
	s_nop 0
	global_load_lds_dwordx4 v144, s[56:57]
	s_add_i32 m0, s55, 0x2000
	s_nop 0
	global_load_lds_dwordx4 v136, s[56:57]
	s_waitcnt vmcnt(6)
	s_barrier
	v_mfma_f32_16x16x32_bf16 v[52:55], v[208:211], v[160:163], v[52:55]
	v_mfma_f32_16x16x32_bf16 v[48:51], v[216:219], v[160:163], v[48:51]
	v_mfma_f32_16x16x32_bf16 v[36:39], v[208:211], v[168:171], v[36:39]
	v_mfma_f32_16x16x32_bf16 v[32:35], v[216:219], v[168:171], v[32:35]
	v_mfma_f32_16x16x32_bf16 v[20:23], v[208:211], v[176:179], v[20:23]
	v_mfma_f32_16x16x32_bf16 v[16:19], v[216:219], v[176:179], v[16:19]
	v_mfma_f32_16x16x32_bf16 v[4:7], v[208:211], v[200:203], v[4:7]
	v_mfma_f32_16x16x32_bf16 v[0:3], v[216:219], v[200:203], v[0:3]
	v_mfma_f32_16x16x32_bf16 v[52:55], v[212:215], v[164:167], v[52:55]
	v_mfma_f32_16x16x32_bf16 v[48:51], v[220:223], v[164:167], v[48:51]
	v_mfma_f32_16x16x32_bf16 v[36:39], v[212:215], v[172:175], v[36:39]
	v_mfma_f32_16x16x32_bf16 v[32:35], v[220:223], v[172:175], v[32:35]
	v_mfma_f32_16x16x32_bf16 v[20:23], v[212:215], v[196:199], v[20:23]
	v_mfma_f32_16x16x32_bf16 v[16:19], v[220:223], v[196:199], v[16:19]
	v_mfma_f32_16x16x32_bf16 v[4:7], v[212:215], v[204:207], v[4:7]
	v_mfma_f32_16x16x32_bf16 v[0:3], v[220:223], v[204:207], v[0:3]
	s_add_i32 s55, 0, 0x18000
	s_barrier
	ds_read_b128 v[128:131], v226
	ds_read_b128 v[132:135], v226 offset:1024
	ds_read_b128 v[148:151], v226 offset:2048
	ds_read_b128 v[152:155], v226 offset:3072
	s_add_u32 s28, s28, 0x40000
	s_addc_u32 s29, s29, 0
	s_mov_b32 m0, s43
	ds_read_b128 v[160:163], v159 offset:32768
	ds_read_b128 v[164:167], v159 offset:33792
	ds_read_b128 v[168:171], v159 offset:34816
	ds_read_b128 v[172:175], v159 offset:35840
	ds_read_b128 v[176:179], v159 offset:36864
	ds_read_b128 v[196:199], v159 offset:37888
	ds_read_b128 v[200:203], v159 offset:38912
	ds_read_b128 v[204:207], v159 offset:39936
	global_load_lds_dwordx4 v140, s[28:29]
	s_mov_b32 m0, s44
	s_nop 0
	global_load_lds_dwordx4 v138, s[28:29]
	s_waitcnt lgkmcnt(8)
	s_barrier
	s_waitcnt lgkmcnt(0)
	s_waitcnt lgkmcnt(0)
	v_mfma_f32_16x16x32_bf16 v[124:127], v[128:131], v[160:163], v[124:127]
	v_mfma_f32_16x16x32_bf16 v[120:123], v[148:151], v[160:163], v[120:123]
	v_mfma_f32_16x16x32_bf16 v[108:111], v[128:131], v[168:171], v[108:111]
	v_mfma_f32_16x16x32_bf16 v[104:107], v[148:151], v[168:171], v[104:107]
	v_mfma_f32_16x16x32_bf16 v[92:95], v[128:131], v[176:179], v[92:95]
	v_mfma_f32_16x16x32_bf16 v[88:91], v[148:151], v[176:179], v[88:91]
	v_mfma_f32_16x16x32_bf16 v[76:79], v[128:131], v[200:203], v[76:79]
	v_mfma_f32_16x16x32_bf16 v[72:75], v[148:151], v[200:203], v[72:75]
	v_mfma_f32_16x16x32_bf16 v[124:127], v[132:135], v[164:167], v[124:127]
	v_mfma_f32_16x16x32_bf16 v[120:123], v[152:155], v[164:167], v[120:123]
	v_mfma_f32_16x16x32_bf16 v[108:111], v[132:135], v[172:175], v[108:111]
	v_mfma_f32_16x16x32_bf16 v[104:107], v[152:155], v[172:175], v[104:107]
	v_mfma_f32_16x16x32_bf16 v[92:95], v[132:135], v[196:199], v[92:95]
	v_mfma_f32_16x16x32_bf16 v[88:91], v[152:155], v[196:199], v[88:91]
	v_mfma_f32_16x16x32_bf16 v[76:79], v[132:135], v[204:207], v[76:79]
	v_mfma_f32_16x16x32_bf16 v[72:75], v[152:155], v[204:207], v[72:75]
	s_barrier
; DI float bf2f(unsigned v) { return __uint_as_float(v << 16); }
; #define PG8_STAGE(bufoff, gbase, voff) do { _Pragma("unroll") for (int _i = 0; _i < 2; ++_i) \
;     __builtin_amdgcn_global_load_lds((const unsigned*)((const char*)(gbase) + (voff)[_i]), (LAS unsigned*)(lds + (bufoff) + ldsw + _i * 8192), 16, 0, 0); } while (0)
; #define PG8_LDA(dst, b, h) do { _Pragma("unroll") for (int m = 0; m < 4; ++m) _Pragma("unroll") for (int k = 0; k < 2; ++k) dst[m][k] = *(const LAS bf16x8*)(lds + PG8_SA(b, h) + aoff + m * 2048 + k * 1024); } while (0)
; #define PG8_MMA(ai, bj, At, Bt) do { __builtin_amdgcn_s_setprio(1); _Pragma("unroll") for (int m = 0; m < 4; ++m) _Pragma("unroll") for (int n = 0; n < 2; ++n) _Pragma("unroll") for (int k = 0; k < 2; ++k) \
;     acc[ai][bj][m][n] = __builtin_amdgcn_mfma_f32_16x16x32_bf16(Bt[n][k], At[m][k], acc[ai][bj][m][n], 0, 0, 0); __builtin_amdgcn_s_setprio(0); } while (0)
; #define PG8_WAIT_V(n) asm volatile("s_waitcnt vmcnt(" #n ")" ::: "memory")
; #define PG8_WAIT_L(n) asm volatile("s_waitcnt lgkmcnt(" #n ")" ::: "memory")
; #define PG8_BAR __builtin_amdgcn_s_barrier()
; template <class Epi, class Sched>
; DI void gemm_phase(LAS unsigned char* lds, const Gemm g, const Sched& S, const Epi& E) {
;     ...
;       PG8_LDA(At, 1, 1); PG8_STAGE(PG8_SA(1, 0), a3, voffA);
;       PG8_BAR; PG8_WAIT_L(0); PG8_MMA(1, 0, At, B0); PG8_BAR; PG8_SCHED;
;       PG8_STAGE(PG8_SB(1, 1), b3 + hstep, voffB);
;       PG8_WAIT_V(6); PG8_BAR; PG8_MMA(1, 1, At, B1); PG8_BAR;
;   DI void operator()(const f32x4 (&acc)[2][2][4][2], const pg8::Unit& u, int wr, int wc, int fr_, int fq_) const {
;     ...
;             } else if (EPI == EPI_RESID) {
;               if (n == 0) {
;                 const int f8 = u.pn * 256 + bj * 128 + wc * 32 + 8 * fq;
;                 const f32x4 v1 = acc[ai][bj][m][1];
;                 f32x4 r0, r1;
;                 if (rsrc) {
;                   r0 = *(const f32x4*)(rsrc + (size_t)token * 1024 + f8); r1 = *(const f32x4*)(rsrc + (size_t)token * 1024 + f8 + 4);
;                 } else {
;                   const u32x4 xu = *(const u32x4*)(xr + (size_t)token * 1024 + f8);
;                   r0 = (f32x4){bf2f(xu.x & 0xffffu), bf2f(xu.x >> 16), bf2f(xu.y & 0xffffu), bf2f(xu.y >> 16)};
;                   r1 = (f32x4){bf2f(xu.z & 0xffffu), bf2f(xu.z >> 16), bf2f(xu.w & 0xffffu), bf2f(xu.w >> 16)};
;                 }
	s_add_i32 s28, 0, 0x1c000
	s_add_i32 s29, s55, s40
	s_mov_b32 m0, s29
	ds_read_b128 v[208:211], v227
	ds_read_b128 v[212:215], v227 offset:1024
	ds_read_b128 v[216:219], v227 offset:2048
	ds_read_b128 v[220:223], v227 offset:3072
	global_load_lds_dwordx4 v144, vcc
	s_add_i32 m0, s29, 0x2000
	s_nop 0
	global_load_lds_dwordx4 v136, vcc
	s_barrier
	s_waitcnt lgkmcnt(0)
	s_waitcnt lgkmcnt(0)
	v_mfma_f32_16x16x32_bf16 v[116:119], v[208:211], v[160:163], v[116:119]
	v_mfma_f32_16x16x32_bf16 v[112:115], v[216:219], v[160:163], v[112:115]
	v_mfma_f32_16x16x32_bf16 v[100:103], v[208:211], v[168:171], v[100:103]
	v_mfma_f32_16x16x32_bf16 v[96:99], v[216:219], v[168:171], v[96:99]
	v_mfma_f32_16x16x32_bf16 v[84:87], v[208:211], v[176:179], v[84:87]
	v_mfma_f32_16x16x32_bf16 v[80:83], v[216:219], v[176:179], v[80:83]
	v_mfma_f32_16x16x32_bf16 v[68:71], v[208:211], v[200:203], v[68:71]
	v_mfma_f32_16x16x32_bf16 v[64:67], v[216:219], v[200:203], v[64:67]
	v_mfma_f32_16x16x32_bf16 v[116:119], v[212:215], v[164:167], v[116:119]
	v_mfma_f32_16x16x32_bf16 v[112:115], v[220:223], v[164:167], v[112:115]
	v_mfma_f32_16x16x32_bf16 v[100:103], v[212:215], v[172:175], v[100:103]
	v_mfma_f32_16x16x32_bf16 v[96:99], v[220:223], v[172:175], v[96:99]
	v_mfma_f32_16x16x32_bf16 v[84:87], v[212:215], v[196:199], v[84:87]
	v_mfma_f32_16x16x32_bf16 v[80:83], v[220:223], v[196:199], v[80:83]
	v_mfma_f32_16x16x32_bf16 v[68:71], v[212:215], v[204:207], v[68:71]
	v_mfma_f32_16x16x32_bf16 v[64:67], v[220:223], v[204:207], v[64:67]
	s_mov_b32 m0, s49
	s_barrier
	ds_read_b128 v[160:163], v159 offset:49152
	ds_read_b128 v[164:167], v159 offset:50176
	ds_read_b128 v[168:171], v159 offset:51200
	ds_read_b128 v[172:175], v159 offset:52224
	ds_read_b128 v[176:179], v159 offset:53248
	ds_read_b128 v[196:199], v159 offset:54272
	ds_read_b128 v[200:203], v159 offset:55296
	ds_read_b128 v[204:207], v159 offset:56320
	global_load_lds_dwordx4 v140, s[100:101]
	s_mov_b32 m0, s50
	s_nop 0
	global_load_lds_dwordx4 v138, s[100:101]
	s_barrier
	s_waitcnt lgkmcnt(0)
	s_waitcnt lgkmcnt(0)
	v_mfma_f32_16x16x32_bf16 v[60:63], v[128:131], v[160:163], v[60:63]
	v_mfma_f32_16x16x32_bf16 v[56:59], v[148:151], v[160:163], v[56:59]
	v_mfma_f32_16x16x32_bf16 v[44:47], v[128:131], v[168:171], v[44:47]
	v_mfma_f32_16x16x32_bf16 v[40:43], v[148:151], v[168:171], v[40:43]
	v_mfma_f32_16x16x32_bf16 v[28:31], v[128:131], v[176:179], v[28:31]
	v_mfma_f32_16x16x32_bf16 v[24:27], v[148:151], v[176:179], v[24:27]
	v_mfma_f32_16x16x32_bf16 v[12:15], v[128:131], v[200:203], v[12:15]
	v_mfma_f32_16x16x32_bf16 v[8:11], v[148:151], v[200:203], v[8:11]
	v_mfma_f32_16x16x32_bf16 v[60:63], v[132:135], v[164:167], v[60:63]
	v_mfma_f32_16x16x32_bf16 v[56:59], v[152:155], v[164:167], v[56:59]
	v_mfma_f32_16x16x32_bf16 v[44:47], v[132:135], v[172:175], v[44:47]
	v_mfma_f32_16x16x32_bf16 v[40:43], v[152:155], v[172:175], v[40:43]
	v_mfma_f32_16x16x32_bf16 v[28:31], v[132:135], v[196:199], v[28:31]
	v_mfma_f32_16x16x32_bf16 v[24:27], v[152:155], v[196:199], v[24:27]
	v_mfma_f32_16x16x32_bf16 v[12:15], v[132:135], v[204:207], v[12:15]
	v_mfma_f32_16x16x32_bf16 v[8:11], v[152:155], v[204:207], v[8:11]
	s_barrier
	s_add_u32 s4, s4, 0x40080
	s_addc_u32 s5, s5, 0
	s_add_i32 s28, s28, s40
	s_mov_b32 m0, s28
	s_nop 0
	global_load_lds_dwordx4 v144, s[4:5]
	s_add_i32 m0, s28, 0x2000
	s_nop 0
	global_load_lds_dwordx4 v136, s[4:5]
	s_waitcnt vmcnt(6)
	s_barrier
	v_mfma_f32_16x16x32_bf16 v[52:55], v[208:211], v[160:163], v[52:55]
	v_mfma_f32_16x16x32_bf16 v[48:51], v[216:219], v[160:163], v[48:51]
	v_mfma_f32_16x16x32_bf16 v[36:39], v[208:211], v[168:171], v[36:39]
	v_mfma_f32_16x16x32_bf16 v[32:35], v[216:219], v[168:171], v[32:35]
	v_mfma_f32_16x16x32_bf16 v[20:23], v[208:211], v[176:179], v[20:23]
	v_mfma_f32_16x16x32_bf16 v[16:19], v[216:219], v[176:179], v[16:19]
	v_mfma_f32_16x16x32_bf16 v[4:7], v[208:211], v[200:203], v[4:7]
	v_mfma_f32_16x16x32_bf16 v[0:3], v[216:219], v[200:203], v[0:3]
	v_mfma_f32_16x16x32_bf16 v[52:55], v[212:215], v[164:167], v[52:55]
	v_mfma_f32_16x16x32_bf16 v[48:51], v[220:223], v[164:167], v[48:51]
	v_mfma_f32_16x16x32_bf16 v[36:39], v[212:215], v[172:175], v[36:39]
	v_mfma_f32_16x16x32_bf16 v[32:35], v[220:223], v[172:175], v[32:35]
	v_mfma_f32_16x16x32_bf16 v[20:23], v[212:215], v[196:199], v[20:23]
	v_mfma_f32_16x16x32_bf16 v[16:19], v[220:223], v[196:199], v[16:19]
	v_mfma_f32_16x16x32_bf16 v[4:7], v[212:215], v[204:207], v[4:7]
	v_mfma_f32_16x16x32_bf16 v[0:3], v[220:223], v[204:207], v[0:3]
	s_add_i32 s54, s54, 2
	s_add_u32 s2, s2, 0x100
	s_addc_u32 s3, s3, 0
	s_add_u32 s52, s52, 0x100
	s_addc_u32 s53, s53, 0
	s_cmp_gt_u32 s54, 13
	s_barrier
	s_cbranch_scc0 .LBB0_1644
	s_lshl_b32 s2, s34, 8
	v_mov_b32_e32 v161, v182
	s_add_i32 s2, s2, s47
	v_cndmask_b32_e64 v130, 0, 1, s[14:15]
	v_and_or_b32 v150, v161, 15, s2
	s_lshl_b32 s2, s24, 8
	v_bfe_u32 v160, v161, 4, 2
	s_or_b32 s2, s2, s48
	v_ashrrev_i32_e32 v151, 31, v150
	v_lshl_or_b32 v148, v160, 3, s2
	v_lshlrev_b64 v[128:129], 12, v[150:151]
	v_ashrrev_i32_e32 v149, 31, v148
	v_lshl_add_u64 v[128:129], s[6:7], 0, v[128:129]
	v_cmp_ne_u32_e64 s[2:3], 1, v130
	s_andn2_b64 vcc, exec, s[14:15]
	v_lshl_add_u64 v[154:155], v[148:149], 2, v[128:129]
	s_cbranch_vccnz .LBB0_1647
	global_load_dwordx4 v[132:135], v[154:155], off offset:16
	global_load_dwordx4 v[128:131], v[154:155], off
	s_mov_b64 s[4:5], 0
	s_branch .LBB0_1648

; #define PG8_STAGE(bufoff, gbase, voff) do { _Pragma("unroll") for (int _i = 0; _i < 2; ++_i) \
;     __builtin_amdgcn_global_load_lds((const unsigned*)((const char*)(gbase) + (voff)[_i]), (LAS unsigned*)(lds + (bufoff) + ldsw + _i * 8192), 16, 0, 0); } while (0)
; #define PG8_LDA(dst, b, h) do { _Pragma("unroll") for (int m = 0; m < 4; ++m) _Pragma("unroll") for (int k = 0; k < 2; ++k) dst[m][k] = *(const LAS bf16x8*)(lds + PG8_SA(b, h) + aoff + m * 2048 + k * 1024); } while (0)
; #define PG8_LDB(dst, b, h) do { _Pragma("unroll") for (int n = 0; n < 2; ++n) _Pragma("unroll") for (int k = 0; k < 2; ++k) dst[n][k] = *(const LAS bf16x8*)(lds + PG8_SB(b, h) + boff + n * 2048 + k * 1024); } while (0)
; #define PG8_MMA(ai, bj, At, Bt) do { __builtin_amdgcn_s_setprio(1); _Pragma("unroll") for (int m = 0; m < 4; ++m) _Pragma("unroll") for (int n = 0; n < 2; ++n) _Pragma("unroll") for (int k = 0; k < 2; ++k) \
;     acc[ai][bj][m][n] = __builtin_amdgcn_mfma_f32_16x16x32_bf16(Bt[n][k], At[m][k], acc[ai][bj][m][n], 0, 0, 0); __builtin_amdgcn_s_setprio(0); } while (0)
; #define PG8_WAIT_L(n) asm volatile("s_waitcnt lgkmcnt(" #n ")" ::: "memory")
; #define PG8_BAR __builtin_amdgcn_s_barrier()
; #define PG8_SCHED __builtin_amdgcn_sched_barrier(0)
; template <class Epi, class Sched>
; DI void gemm_phase(LAS unsigned char* lds, const Gemm g, const Sched& S, const Epi& E) {
;     ...
;     for (int t = 0; t < nt; t += 2) {
;       const bool last = (t == nt - 2);
;       const char* a1 = cA + (size_t)(t + 1) * kstep;
;       const char* a2 = last ? nA : cA + (size_t)(t + 2) * kstep; const char* b2 = last ? nB : cB + (size_t)(t + 2) * kstep;
;       const char* a3 = a2 + kstep; const char* b3 = b2 + kstep;
;       PG8_LDB(B0, 0, 0); PG8_SCHED; PG8_LDA(At, 0, 0); PG8_STAGE(PG8_SA(1, 1), a1 + hstep, voffA);
;       PG8_WAIT_L(8); PG8_BAR; PG8_WAIT_L(0); PG8_MMA(0, 0, At, B0); PG8_BAR; PG8_SCHED;
;       PG8_LDB(B1, 0, 1); PG8_STAGE(PG8_SB(0, 0), b2, voffB);
;     ...
; #pragma unroll
;     for (int a = 0; a < 2; ++a)
; #pragma unroll
;       for (int b = 0; b < 2; ++b)
; #pragma unroll
;         for (int m = 0; m < 4; ++m)
; #pragma unroll
;           for (int n = 0; n < 2; ++n) acc[a][b][m][n] = (f32x4){0.f, 0.f, 0.f, 0.f};
;     cur = nxt; cA = nA; cB = nB; ++ui;
.LBB0_1828:
	v_readlane_b32 s12, v238, 61
	v_readlane_b32 s13, v238, 62
	s_ashr_i32 s7, s6, 31
	s_mov_b32 s50, -2
	v_mov_b64_e32 v[0:1], s[12:13]
	v_cmp_lt_i64_e32 vcc, s[10:11], v[0:1]
	s_lshl_b64 s[10:11], s[6:7], 19
	s_add_u32 s10, s21, s10
	s_addc_u32 s11, s22, s11
	s_and_b64 s[12:13], vcc, exec
	s_cselect_b32 s7, s11, s15
	s_cselect_b32 s46, s10, s14
	s_ashr_i32 s5, s4, 31
	s_lshl_b64 s[12:13], s[4:5], 19
	s_add_u32 s12, s23, s12
	s_addc_u32 s13, s28, s13
	s_and_b64 s[18:19], vcc, exec
	s_cselect_b32 s5, s13, s17
	s_cselect_b32 s47, s12, s16
	s_add_u32 s14, s14, 0x40080
	s_addc_u32 s15, s15, 0
	s_add_u32 s48, s16, 0x100
	v_mov_b32_e32 v0, 0
	s_addc_u32 s49, s17, 0
	v_mov_b32_e32 v1, v0
	v_mov_b64_e32 v[2:3], v[0:1]
	v_mov_b64_e32 v[4:5], v[0:1]
	v_mov_b64_e32 v[6:7], v[0:1]
	v_mov_b64_e32 v[8:9], v[0:1]
	v_mov_b64_e32 v[10:11], v[0:1]
	v_mov_b64_e32 v[12:13], v[0:1]
	v_mov_b64_e32 v[14:15], v[0:1]
	v_mov_b64_e32 v[16:17], v[0:1]
	v_mov_b64_e32 v[18:19], v[0:1]
	v_mov_b64_e32 v[20:21], v[0:1]
	v_mov_b64_e32 v[22:23], v[0:1]
	v_mov_b64_e32 v[24:25], v[0:1]
	v_mov_b64_e32 v[26:27], v[0:1]
	v_mov_b64_e32 v[28:29], v[0:1]
	v_mov_b64_e32 v[30:31], v[0:1]
	v_mov_b64_e32 v[32:33], v[0:1]
	v_mov_b64_e32 v[34:35], v[0:1]
	v_mov_b64_e32 v[36:37], v[0:1]
	v_mov_b64_e32 v[38:39], v[0:1]
	v_mov_b64_e32 v[40:41], v[0:1]
	v_mov_b64_e32 v[42:43], v[0:1]
	v_mov_b64_e32 v[44:45], v[0:1]
	v_mov_b64_e32 v[46:47], v[0:1]
	v_mov_b64_e32 v[48:49], v[0:1]
	v_mov_b64_e32 v[50:51], v[0:1]
	v_mov_b64_e32 v[52:53], v[0:1]
	v_mov_b64_e32 v[54:55], v[0:1]
	v_mov_b64_e32 v[56:57], v[0:1]
	v_mov_b64_e32 v[58:59], v[0:1]
	v_mov_b64_e32 v[60:61], v[0:1]
	v_mov_b64_e32 v[62:63], v[0:1]
	v_mov_b64_e32 v[64:65], v[0:1]
	v_mov_b64_e32 v[66:67], v[0:1]
	v_mov_b64_e32 v[68:69], v[0:1]
	v_mov_b64_e32 v[70:71], v[0:1]
	v_mov_b64_e32 v[72:73], v[0:1]
	v_mov_b64_e32 v[74:75], v[0:1]
	v_mov_b64_e32 v[76:77], v[0:1]
	v_mov_b64_e32 v[78:79], v[0:1]
	v_mov_b64_e32 v[80:81], v[0:1]
	v_mov_b64_e32 v[82:83], v[0:1]
	v_mov_b64_e32 v[84:85], v[0:1]
	v_mov_b64_e32 v[86:87], v[0:1]
	v_mov_b64_e32 v[88:89], v[0:1]
	v_mov_b64_e32 v[90:91], v[0:1]
	v_mov_b64_e32 v[92:93], v[0:1]
	v_mov_b64_e32 v[94:95], v[0:1]
	v_mov_b64_e32 v[96:97], v[0:1]
	v_mov_b64_e32 v[98:99], v[0:1]
	v_mov_b64_e32 v[100:101], v[0:1]
	v_mov_b64_e32 v[102:103], v[0:1]
	v_mov_b64_e32 v[104:105], v[0:1]
	v_mov_b64_e32 v[106:107], v[0:1]
	v_mov_b64_e32 v[108:109], v[0:1]
	v_mov_b64_e32 v[110:111], v[0:1]
	v_mov_b64_e32 v[112:113], v[0:1]
	v_mov_b64_e32 v[114:115], v[0:1]
	v_mov_b64_e32 v[116:117], v[0:1]
	v_mov_b64_e32 v[118:119], v[0:1]
	v_mov_b64_e32 v[120:121], v[0:1]
	v_mov_b64_e32 v[122:123], v[0:1]
	v_mov_b64_e32 v[124:125], v[0:1]
	v_mov_b64_e32 v[126:127], v[0:1]
	v_add_u32_e32 v224, 0x10000, v142
	v_add_u32_e32 v225, 0x14000, v142
	v_add_u32_e32 v226, 0x18000, v142
	v_add_u32_e32 v227, 0x1c000, v142
.LBB0_1829:
	s_add_u32 s16, s14, 0xfffc0080
	s_addc_u32 s17, s15, -1
	s_add_i32 s51, 0, 0x10000
	ds_read_b128 v[146:149], v224
	ds_read_b128 v[150:153], v224 offset:1024
	ds_read_b128 v[154:157], v224 offset:2048
	ds_read_b128 v[158:161], v224 offset:3072
	s_cmp_eq_u32 s50, 12
	s_cselect_b32 s19, s7, s17
	s_cselect_b32 s18, s46, s16
	s_cselect_b32 s17, s5, s49
	s_cselect_b32 s16, s47, s48
	s_add_i32 m0, s29, 0xc000
	ds_read_b128 v[162:165], v143
	ds_read_b128 v[166:169], v143 offset:1024
	ds_read_b128 v[170:173], v143 offset:2048
	ds_read_b128 v[174:177], v143 offset:3072
	ds_read_b128 v[178:181], v143 offset:4096
	ds_read_b128 v[196:199], v143 offset:5120
	ds_read_b128 v[200:203], v143 offset:6144
	ds_read_b128 v[204:207], v143 offset:7168
	global_load_lds_dwordx4 v136, s[14:15]
	s_add_i32 m0, s29, 0xe000
	s_nop 0
	global_load_lds_dwordx4 v138, s[14:15]
	s_waitcnt lgkmcnt(8)
	s_barrier
	s_waitcnt lgkmcnt(0)
	s_waitcnt lgkmcnt(0)
	v_mfma_f32_16x16x32_bf16 v[124:127], v[146:149], v[162:165], v[124:127]
	v_mfma_f32_16x16x32_bf16 v[120:123], v[154:157], v[162:165], v[120:123]
	v_mfma_f32_16x16x32_bf16 v[112:115], v[146:149], v[170:173], v[112:115]
	v_mfma_f32_16x16x32_bf16 v[104:107], v[154:157], v[170:173], v[104:107]
	v_mfma_f32_16x16x32_bf16 v[92:95], v[146:149], v[178:181], v[92:95]
	v_mfma_f32_16x16x32_bf16 v[88:91], v[154:157], v[178:181], v[88:91]
	v_mfma_f32_16x16x32_bf16 v[80:83], v[146:149], v[200:203], v[80:83]
	v_mfma_f32_16x16x32_bf16 v[72:75], v[154:157], v[200:203], v[72:75]
	v_mfma_f32_16x16x32_bf16 v[124:127], v[150:153], v[166:169], v[124:127]
	v_mfma_f32_16x16x32_bf16 v[120:123], v[158:161], v[166:169], v[120:123]
	v_mfma_f32_16x16x32_bf16 v[112:115], v[150:153], v[174:177], v[112:115]
	v_mfma_f32_16x16x32_bf16 v[104:107], v[158:161], v[174:177], v[104:107]
	v_mfma_f32_16x16x32_bf16 v[92:95], v[150:153], v[196:199], v[92:95]
	v_mfma_f32_16x16x32_bf16 v[88:91], v[158:161], v[196:199], v[88:91]
	v_mfma_f32_16x16x32_bf16 v[80:83], v[150:153], v[204:207], v[80:83]
	v_mfma_f32_16x16x32_bf16 v[72:75], v[158:161], v[204:207], v[72:75]
	s_barrier
	s_add_i32 s54, 0, 0x14000
	s_add_i32 s51, s51, s20
	ds_read_b128 v[208:211], v225
	ds_read_b128 v[212:215], v225 offset:1024
	ds_read_b128 v[216:219], v225 offset:2048
	ds_read_b128 v[220:223], v225 offset:3072
	s_add_u32 vcc_lo, s16, s0
	s_addc_u32 vcc_hi, s17, s1
	s_mov_b32 m0, s51
	s_nop 0
	global_load_lds_dwordx4 v132, s[16:17]
	s_add_i32 m0, s51, 0x2000
	s_nop 0
	global_load_lds_dwordx4 v128, s[16:17]
	s_barrier
; #define PG8_STAGE(bufoff, gbase, voff) do { _Pragma("unroll") for (int _i = 0; _i < 2; ++_i) \
;     __builtin_amdgcn_global_load_lds((const unsigned*)((const char*)(gbase) + (voff)[_i]), (LAS unsigned*)(lds + (bufoff) + ldsw + _i * 8192), 16, 0, 0); } while (0)
; #define PG8_LDA(dst, b, h) do { _Pragma("unroll") for (int m = 0; m < 4; ++m) _Pragma("unroll") for (int k = 0; k < 2; ++k) dst[m][k] = *(const LAS bf16x8*)(lds + PG8_SA(b, h) + aoff + m * 2048 + k * 1024); } while (0)
; #define PG8_LDB(dst, b, h) do { _Pragma("unroll") for (int n = 0; n < 2; ++n) _Pragma("unroll") for (int k = 0; k < 2; ++k) dst[n][k] = *(const LAS bf16x8*)(lds + PG8_SB(b, h) + boff + n * 2048 + k * 1024); } while (0)
; #define PG8_MMA(ai, bj, At, Bt) do { __builtin_amdgcn_s_setprio(1); _Pragma("unroll") for (int m = 0; m < 4; ++m) _Pragma("unroll") for (int n = 0; n < 2; ++n) _Pragma("unroll") for (int k = 0; k < 2; ++k) \
;     acc[ai][bj][m][n] = __builtin_amdgcn_mfma_f32_16x16x32_bf16(Bt[n][k], At[m][k], acc[ai][bj][m][n], 0, 0, 0); __builtin_amdgcn_s_setprio(0); } while (0)
; #define PG8_WAIT_V(n) asm volatile("s_waitcnt vmcnt(" #n ")" ::: "memory")
; #define PG8_WAIT_L(n) asm volatile("s_waitcnt lgkmcnt(" #n ")" ::: "memory")
; #define PG8_BAR __builtin_amdgcn_s_barrier()
; #define PG8_SCHED __builtin_amdgcn_sched_barrier(0)
; template <class Epi, class Sched>
; DI void gemm_phase(LAS unsigned char* lds, const Gemm g, const Sched& S, const Epi& E) {
;     ...
;       PG8_BAR; PG8_WAIT_L(0); PG8_MMA(0, 1, At, B1); PG8_BAR;
;       PG8_LDA(At, 0, 1); PG8_STAGE(PG8_SA(0, 0), a2, voffA);
;       PG8_BAR; PG8_WAIT_L(0); PG8_MMA(1, 0, At, B0); PG8_BAR; PG8_SCHED;
;       PG8_STAGE(PG8_SB(0, 1), b2 + hstep, voffB);
;       PG8_WAIT_V(6); PG8_BAR; PG8_MMA(1, 1, At, B1); PG8_BAR;
;       PG8_LDB(B0, 1, 0); PG8_SCHED; PG8_LDA(At, 1, 0); PG8_STAGE(PG8_SA(0, 1), a2 + hstep, voffA);
;       PG8_WAIT_L(8); PG8_BAR; PG8_WAIT_L(0); PG8_MMA(0, 0, At, B0); PG8_BAR; PG8_SCHED;
;       PG8_LDB(B1, 1, 1); PG8_STAGE(PG8_SB(1, 0), b3, voffB);
;       PG8_BAR; PG8_WAIT_L(0); PG8_MMA(0, 1, At, B1); PG8_BAR;
;       PG8_LDA(At, 1, 1); PG8_STAGE(PG8_SA(1, 0), a3, voffA);
	s_waitcnt lgkmcnt(0)
	s_waitcnt lgkmcnt(0)
	v_mfma_f32_16x16x32_bf16 v[116:119], v[208:211], v[162:165], v[116:119]
	v_mfma_f32_16x16x32_bf16 v[108:111], v[216:219], v[162:165], v[108:111]
	v_mfma_f32_16x16x32_bf16 v[100:103], v[208:211], v[170:173], v[100:103]
	v_mfma_f32_16x16x32_bf16 v[96:99], v[216:219], v[170:173], v[96:99]
	v_mfma_f32_16x16x32_bf16 v[84:87], v[208:211], v[178:181], v[84:87]
	v_mfma_f32_16x16x32_bf16 v[76:79], v[216:219], v[178:181], v[76:79]
	v_mfma_f32_16x16x32_bf16 v[68:71], v[208:211], v[200:203], v[68:71]
	v_mfma_f32_16x16x32_bf16 v[64:67], v[216:219], v[200:203], v[64:67]
	v_mfma_f32_16x16x32_bf16 v[116:119], v[212:215], v[166:169], v[116:119]
	v_mfma_f32_16x16x32_bf16 v[108:111], v[220:223], v[166:169], v[108:111]
	v_mfma_f32_16x16x32_bf16 v[100:103], v[212:215], v[174:177], v[100:103]
	v_mfma_f32_16x16x32_bf16 v[96:99], v[220:223], v[174:177], v[96:99]
	v_mfma_f32_16x16x32_bf16 v[84:87], v[212:215], v[196:199], v[84:87]
	v_mfma_f32_16x16x32_bf16 v[76:79], v[220:223], v[196:199], v[76:79]
	v_mfma_f32_16x16x32_bf16 v[68:71], v[212:215], v[204:207], v[68:71]
	v_mfma_f32_16x16x32_bf16 v[64:67], v[220:223], v[204:207], v[64:67]
	s_mov_b32 m0, s29
	s_add_u32 s100, s18, s0
	s_addc_u32 s101, s19, s1
	s_barrier
	ds_read_b128 v[162:165], v143 offset:16384
	ds_read_b128 v[166:169], v143 offset:17408
	ds_read_b128 v[170:173], v143 offset:18432
	ds_read_b128 v[174:177], v143 offset:19456
	ds_read_b128 v[178:181], v143 offset:20480
	ds_read_b128 v[196:199], v143 offset:21504
	ds_read_b128 v[200:203], v143 offset:22528
	ds_read_b128 v[204:207], v143 offset:23552
	global_load_lds_dwordx4 v134, s[18:19]
	s_mov_b32 m0, s34
	s_nop 0
	global_load_lds_dwordx4 v130, s[18:19]
	s_barrier
	s_waitcnt lgkmcnt(0)
	s_waitcnt lgkmcnt(0)
	v_mfma_f32_16x16x32_bf16 v[60:63], v[146:149], v[162:165], v[60:63]
	v_mfma_f32_16x16x32_bf16 v[56:59], v[154:157], v[162:165], v[56:59]
	v_mfma_f32_16x16x32_bf16 v[48:51], v[146:149], v[170:173], v[48:51]
	v_mfma_f32_16x16x32_bf16 v[40:43], v[154:157], v[170:173], v[40:43]
	v_mfma_f32_16x16x32_bf16 v[28:31], v[146:149], v[178:181], v[28:31]
	v_mfma_f32_16x16x32_bf16 v[24:27], v[154:157], v[178:181], v[24:27]
	v_mfma_f32_16x16x32_bf16 v[16:19], v[146:149], v[200:203], v[16:19]
	v_mfma_f32_16x16x32_bf16 v[8:11], v[154:157], v[200:203], v[8:11]
	v_mfma_f32_16x16x32_bf16 v[60:63], v[150:153], v[166:169], v[60:63]
	v_mfma_f32_16x16x32_bf16 v[56:59], v[158:161], v[166:169], v[56:59]
	v_mfma_f32_16x16x32_bf16 v[48:51], v[150:153], v[174:177], v[48:51]
	v_mfma_f32_16x16x32_bf16 v[40:43], v[158:161], v[174:177], v[40:43]
	v_mfma_f32_16x16x32_bf16 v[28:31], v[150:153], v[196:199], v[28:31]
	v_mfma_f32_16x16x32_bf16 v[24:27], v[158:161], v[196:199], v[24:27]
	v_mfma_f32_16x16x32_bf16 v[16:19], v[150:153], v[204:207], v[16:19]
	v_mfma_f32_16x16x32_bf16 v[8:11], v[158:161], v[204:207], v[8:11]
	s_barrier
	s_add_u32 s52, s16, 0x40000
	s_addc_u32 s53, s17, 0
	s_add_i32 s51, s54, s20
	s_mov_b32 m0, s51
	s_nop 0
	global_load_lds_dwordx4 v132, s[52:53]
	s_add_i32 m0, s51, 0x2000
	s_nop 0
	global_load_lds_dwordx4 v128, s[52:53]
	s_waitcnt vmcnt(6)
	s_barrier
	v_mfma_f32_16x16x32_bf16 v[52:55], v[208:211], v[162:165], v[52:55]
	v_mfma_f32_16x16x32_bf16 v[44:47], v[216:219], v[162:165], v[44:47]
	v_mfma_f32_16x16x32_bf16 v[36:39], v[208:211], v[170:173], v[36:39]
	v_mfma_f32_16x16x32_bf16 v[32:35], v[216:219], v[170:173], v[32:35]
	v_mfma_f32_16x16x32_bf16 v[20:23], v[208:211], v[178:181], v[20:23]
	v_mfma_f32_16x16x32_bf16 v[12:15], v[216:219], v[178:181], v[12:15]
	v_mfma_f32_16x16x32_bf16 v[4:7], v[208:211], v[200:203], v[4:7]
	v_mfma_f32_16x16x32_bf16 v[0:3], v[216:219], v[200:203], v[0:3]
	v_mfma_f32_16x16x32_bf16 v[52:55], v[212:215], v[166:169], v[52:55]
	v_mfma_f32_16x16x32_bf16 v[44:47], v[220:223], v[166:169], v[44:47]
	v_mfma_f32_16x16x32_bf16 v[36:39], v[212:215], v[174:177], v[36:39]
	v_mfma_f32_16x16x32_bf16 v[32:35], v[220:223], v[174:177], v[32:35]
	v_mfma_f32_16x16x32_bf16 v[20:23], v[212:215], v[196:199], v[20:23]
	v_mfma_f32_16x16x32_bf16 v[12:15], v[220:223], v[196:199], v[12:15]
	v_mfma_f32_16x16x32_bf16 v[4:7], v[212:215], v[204:207], v[4:7]
	v_mfma_f32_16x16x32_bf16 v[0:3], v[220:223], v[204:207], v[0:3]
	s_add_i32 s51, 0, 0x18000
	s_barrier
	ds_read_b128 v[146:149], v226
	ds_read_b128 v[150:153], v226 offset:1024
	ds_read_b128 v[154:157], v226 offset:2048
	ds_read_b128 v[158:161], v226 offset:3072
	s_add_u32 s18, s18, 0x40000
	s_addc_u32 s19, s19, 0
	s_mov_b32 m0, s35
	ds_read_b128 v[162:165], v143 offset:32768
	ds_read_b128 v[166:169], v143 offset:33792
	ds_read_b128 v[170:173], v143 offset:34816
	ds_read_b128 v[174:177], v143 offset:35840
	ds_read_b128 v[178:181], v143 offset:36864
	ds_read_b128 v[196:199], v143 offset:37888
	ds_read_b128 v[200:203], v143 offset:38912
	ds_read_b128 v[204:207], v143 offset:39936
	global_load_lds_dwordx4 v134, s[18:19]
	s_mov_b32 m0, s38
	s_nop 0
	global_load_lds_dwordx4 v130, s[18:19]
	s_waitcnt lgkmcnt(8)
	s_barrier
	s_waitcnt lgkmcnt(0)
	s_waitcnt lgkmcnt(0)
	v_mfma_f32_16x16x32_bf16 v[124:127], v[146:149], v[162:165], v[124:127]
	v_mfma_f32_16x16x32_bf16 v[120:123], v[154:157], v[162:165], v[120:123]
	v_mfma_f32_16x16x32_bf16 v[112:115], v[146:149], v[170:173], v[112:115]
	v_mfma_f32_16x16x32_bf16 v[104:107], v[154:157], v[170:173], v[104:107]
	v_mfma_f32_16x16x32_bf16 v[92:95], v[146:149], v[178:181], v[92:95]
	v_mfma_f32_16x16x32_bf16 v[88:91], v[154:157], v[178:181], v[88:91]
	v_mfma_f32_16x16x32_bf16 v[80:83], v[146:149], v[200:203], v[80:83]
	v_mfma_f32_16x16x32_bf16 v[72:75], v[154:157], v[200:203], v[72:75]
	v_mfma_f32_16x16x32_bf16 v[124:127], v[150:153], v[166:169], v[124:127]
	v_mfma_f32_16x16x32_bf16 v[120:123], v[158:161], v[166:169], v[120:123]
	v_mfma_f32_16x16x32_bf16 v[112:115], v[150:153], v[174:177], v[112:115]
	v_mfma_f32_16x16x32_bf16 v[104:107], v[158:161], v[174:177], v[104:107]
	v_mfma_f32_16x16x32_bf16 v[92:95], v[150:153], v[196:199], v[92:95]
	v_mfma_f32_16x16x32_bf16 v[88:91], v[158:161], v[196:199], v[88:91]
	v_mfma_f32_16x16x32_bf16 v[80:83], v[150:153], v[204:207], v[80:83]
	v_mfma_f32_16x16x32_bf16 v[72:75], v[158:161], v[204:207], v[72:75]
	s_barrier
; #define PG8_STAGE(bufoff, gbase, voff) do { _Pragma("unroll") for (int _i = 0; _i < 2; ++_i) \
;     __builtin_amdgcn_global_load_lds((const unsigned*)((const char*)(gbase) + (voff)[_i]), (LAS unsigned*)(lds + (bufoff) + ldsw + _i * 8192), 16, 0, 0); } while (0)
; #define PG8_LDA(dst, b, h) do { _Pragma("unroll") for (int m = 0; m < 4; ++m) _Pragma("unroll") for (int k = 0; k < 2; ++k) dst[m][k] = *(const LAS bf16x8*)(lds + PG8_SA(b, h) + aoff + m * 2048 + k * 1024); } while (0)
; #define PG8_MMA(ai, bj, At, Bt) do { __builtin_amdgcn_s_setprio(1); _Pragma("unroll") for (int m = 0; m < 4; ++m) _Pragma("unroll") for (int n = 0; n < 2; ++n) _Pragma("unroll") for (int k = 0; k < 2; ++k) \
;     acc[ai][bj][m][n] = __builtin_amdgcn_mfma_f32_16x16x32_bf16(Bt[n][k], At[m][k], acc[ai][bj][m][n], 0, 0, 0); __builtin_amdgcn_s_setprio(0); } while (0)
; #define PG8_WAIT_V(n) asm volatile("s_waitcnt vmcnt(" #n ")" ::: "memory")
; #define PG8_WAIT_L(n) asm volatile("s_waitcnt lgkmcnt(" #n ")" ::: "memory")
; #define PG8_BAR __builtin_amdgcn_s_barrier()
; #define PG8_SCHED __builtin_amdgcn_sched_barrier(0)
; template <class Epi, class Sched>
; DI void gemm_phase(LAS unsigned char* lds, const Gemm g, const Sched& S, const Epi& E) {
;     ...
;       PG8_LDA(At, 1, 1); PG8_STAGE(PG8_SA(1, 0), a3, voffA);
;       PG8_BAR; PG8_WAIT_L(0); PG8_MMA(1, 0, At, B0); PG8_BAR; PG8_SCHED;
;       PG8_STAGE(PG8_SB(1, 1), b3 + hstep, voffB);
;       PG8_WAIT_V(6); PG8_BAR; PG8_MMA(1, 1, At, B1); PG8_BAR;
	s_add_i32 s18, 0, 0x1c000
	s_add_i32 s19, s51, s20
	s_mov_b32 m0, s19
	ds_read_b128 v[208:211], v227
	ds_read_b128 v[212:215], v227 offset:1024
	ds_read_b128 v[216:219], v227 offset:2048
	ds_read_b128 v[220:223], v227 offset:3072
	global_load_lds_dwordx4 v132, vcc
	s_add_i32 m0, s19, 0x2000
	s_nop 0
	global_load_lds_dwordx4 v128, vcc
	s_barrier
	s_waitcnt lgkmcnt(0)
	s_waitcnt lgkmcnt(0)
	v_mfma_f32_16x16x32_bf16 v[116:119], v[208:211], v[162:165], v[116:119]
	v_mfma_f32_16x16x32_bf16 v[108:111], v[216:219], v[162:165], v[108:111]
	v_mfma_f32_16x16x32_bf16 v[100:103], v[208:211], v[170:173], v[100:103]
	v_mfma_f32_16x16x32_bf16 v[96:99], v[216:219], v[170:173], v[96:99]
	v_mfma_f32_16x16x32_bf16 v[84:87], v[208:211], v[178:181], v[84:87]
	v_mfma_f32_16x16x32_bf16 v[76:79], v[216:219], v[178:181], v[76:79]
	v_mfma_f32_16x16x32_bf16 v[68:71], v[208:211], v[200:203], v[68:71]
	v_mfma_f32_16x16x32_bf16 v[64:67], v[216:219], v[200:203], v[64:67]
	v_mfma_f32_16x16x32_bf16 v[116:119], v[212:215], v[166:169], v[116:119]
	v_mfma_f32_16x16x32_bf16 v[108:111], v[220:223], v[166:169], v[108:111]
	v_mfma_f32_16x16x32_bf16 v[100:103], v[212:215], v[174:177], v[100:103]
	v_mfma_f32_16x16x32_bf16 v[96:99], v[220:223], v[174:177], v[96:99]
	v_mfma_f32_16x16x32_bf16 v[84:87], v[212:215], v[196:199], v[84:87]
	v_mfma_f32_16x16x32_bf16 v[76:79], v[220:223], v[196:199], v[76:79]
	v_mfma_f32_16x16x32_bf16 v[68:71], v[212:215], v[204:207], v[68:71]
	v_mfma_f32_16x16x32_bf16 v[64:67], v[220:223], v[204:207], v[64:67]
	s_mov_b32 m0, s40
	s_barrier
	ds_read_b128 v[162:165], v143 offset:49152
	ds_read_b128 v[166:169], v143 offset:50176
	ds_read_b128 v[170:173], v143 offset:51200
	ds_read_b128 v[174:177], v143 offset:52224
	ds_read_b128 v[178:181], v143 offset:53248
	ds_read_b128 v[196:199], v143 offset:54272
	ds_read_b128 v[200:203], v143 offset:55296
	ds_read_b128 v[204:207], v143 offset:56320
	global_load_lds_dwordx4 v134, s[100:101]
	s_mov_b32 m0, s41
	s_nop 0
	global_load_lds_dwordx4 v130, s[100:101]
	s_barrier
	s_waitcnt lgkmcnt(0)
	s_waitcnt lgkmcnt(0)
	v_mfma_f32_16x16x32_bf16 v[60:63], v[146:149], v[162:165], v[60:63]
	v_mfma_f32_16x16x32_bf16 v[56:59], v[154:157], v[162:165], v[56:59]
	v_mfma_f32_16x16x32_bf16 v[48:51], v[146:149], v[170:173], v[48:51]
	v_mfma_f32_16x16x32_bf16 v[40:43], v[154:157], v[170:173], v[40:43]
	v_mfma_f32_16x16x32_bf16 v[28:31], v[146:149], v[178:181], v[28:31]
	v_mfma_f32_16x16x32_bf16 v[24:27], v[154:157], v[178:181], v[24:27]
	v_mfma_f32_16x16x32_bf16 v[16:19], v[146:149], v[200:203], v[16:19]
	v_mfma_f32_16x16x32_bf16 v[8:11], v[154:157], v[200:203], v[8:11]
	v_mfma_f32_16x16x32_bf16 v[60:63], v[150:153], v[166:169], v[60:63]
	v_mfma_f32_16x16x32_bf16 v[56:59], v[158:161], v[166:169], v[56:59]
	v_mfma_f32_16x16x32_bf16 v[48:51], v[150:153], v[174:177], v[48:51]
	v_mfma_f32_16x16x32_bf16 v[40:43], v[158:161], v[174:177], v[40:43]
	v_mfma_f32_16x16x32_bf16 v[28:31], v[150:153], v[196:199], v[28:31]
	v_mfma_f32_16x16x32_bf16 v[24:27], v[158:161], v[196:199], v[24:27]
	v_mfma_f32_16x16x32_bf16 v[16:19], v[150:153], v[204:207], v[16:19]
	v_mfma_f32_16x16x32_bf16 v[8:11], v[158:161], v[204:207], v[8:11]
	s_barrier
	s_add_u32 s16, s16, 0x40080
	s_addc_u32 s17, s17, 0
	s_add_i32 s18, s18, s20
	s_mov_b32 m0, s18
	s_nop 0
	global_load_lds_dwordx4 v132, s[16:17]
	s_add_i32 m0, s18, 0x2000
	s_nop 0
	global_load_lds_dwordx4 v128, s[16:17]
	s_waitcnt vmcnt(6)
	s_barrier
	v_mfma_f32_16x16x32_bf16 v[52:55], v[208:211], v[162:165], v[52:55]
	v_mfma_f32_16x16x32_bf16 v[44:47], v[216:219], v[162:165], v[44:47]
	v_mfma_f32_16x16x32_bf16 v[36:39], v[208:211], v[170:173], v[36:39]
	v_mfma_f32_16x16x32_bf16 v[32:35], v[216:219], v[170:173], v[32:35]
	v_mfma_f32_16x16x32_bf16 v[20:23], v[208:211], v[178:181], v[20:23]
	v_mfma_f32_16x16x32_bf16 v[12:15], v[216:219], v[178:181], v[12:15]
	v_mfma_f32_16x16x32_bf16 v[4:7], v[208:211], v[200:203], v[4:7]
	v_mfma_f32_16x16x32_bf16 v[0:3], v[216:219], v[200:203], v[0:3]
	v_mfma_f32_16x16x32_bf16 v[52:55], v[212:215], v[166:169], v[52:55]
	v_mfma_f32_16x16x32_bf16 v[44:47], v[220:223], v[166:169], v[44:47]
	v_mfma_f32_16x16x32_bf16 v[36:39], v[212:215], v[174:177], v[36:39]
	v_mfma_f32_16x16x32_bf16 v[32:35], v[220:223], v[174:177], v[32:35]
	v_mfma_f32_16x16x32_bf16 v[20:23], v[212:215], v[196:199], v[20:23]
	v_mfma_f32_16x16x32_bf16 v[12:15], v[220:223], v[196:199], v[12:15]
	v_mfma_f32_16x16x32_bf16 v[4:7], v[212:215], v[204:207], v[4:7]
	v_mfma_f32_16x16x32_bf16 v[0:3], v[220:223], v[204:207], v[0:3]
	s_add_i32 s50, s50, 2
	s_add_u32 s14, s14, 0x100
	s_addc_u32 s15, s15, 0
	s_add_u32 s48, s48, 0x100
	s_addc_u32 s49, s49, 0
	s_cmp_gt_u32 s50, 13
	s_barrier
	s_cbranch_scc0 .LBB0_1829
;   DI void operator()(const f32x4 (&acc)[2][2][4][2], const pg8::Unit& u, int wr, int wc, int fr_, int fq_) const {
;     ...
;             } else {
;               if (n == 0) {
;                 const f32x4 v1 = acc[ai][bj][m][1];
;                 u32x4 o4;
;                 { const float t0 = fmaxf(v[0], 0.f) * rinv, t1 = fmaxf(v[1], 0.f) * rinv, t2 = fmaxf(v[2], 0.f) * rinv, t3 = fmaxf(v[3], 0.f) * rinv;
;                   o4.x = pack2(t0 * t0, t1 * t1); o4.y = pack2(t2 * t2, t3 * t3); }
;                 { const float t0 = fmaxf(v1[0], 0.f) * rinv, t1 = fmaxf(v1[1], 0.f) * rinv, t2 = fmaxf(v1[2], 0.f) * rinv, t3 = fmaxf(v1[3], 0.f) * rinv;
;                   o4.z = pack2(t0 * t0, t1 * t1); o4.w = pack2(t2 * t2, t3 * t3); }
;                 *(u32x4*)((u16*)big + (size_t)token * 4096 + u.pn * 256 + bj * 128 + wc * 32 + 8 * fq) = o4;
;               }
	v_mov_b32_e32 v144, v182
	s_lshl_b32 s5, s43, 10
	s_add_i32 s5, s5, 0
	v_and_or_b32 v141, v144, 15, s39
	v_lshl_add_u32 v140, s44, 8, v141
	v_lshl_add_u32 v141, v141, 2, s5
	v_add_u32_e32 v146, 0x20000, v141
	ds_read2_b32 v[148:149], v146 offset1:16
	v_max_f32_e32 v124, 0, v124
	v_max_f32_e32 v125, 0, v125
	v_max_f32_e32 v126, 0, v126
	v_max_f32_e32 v127, 0, v127
	v_max_f32_e32 v120, 0, v120
	v_max_f32_e32 v121, 0, v121
	s_waitcnt lgkmcnt(0)
	v_pk_mul_f32 v[124:125], v[124:125], v[148:149] op_sel_hi:[1,0]
	v_pk_mul_f32 v[126:127], v[126:127], v[148:149] op_sel_hi:[1,0]
	v_pk_mul_f32 v[120:121], v[120:121], v[148:149] op_sel_hi:[1,0]
	v_pk_mul_f32 v[124:125], v[124:125], v[124:125]
	v_pk_mul_f32 v[126:127], v[126:127], v[126:127]
	v_max_f32_e32 v122, 0, v122
	v_max_f32_e32 v123, 0, v123
	v_pk_mul_f32 v[120:121], v[120:121], v[120:121]
	v_max_f32_e32 v116, 0, v116
	v_max_f32_e32 v117, 0, v117
	v_max_f32_e32 v118, 0, v118
	v_max_f32_e32 v119, 0, v119
	v_max_f32_e32 v108, 0, v108
	v_max_f32_e32 v109, 0, v109
	s_lshl_b32 s14, s45, 8
	v_ashrrev_i32_e32 v141, 31, v140
	v_cvt_pk_bf16_f32 v124, v124, v125
	v_cvt_pk_bf16_f32 v125, v126, v127
	v_cvt_pk_bf16_f32 v126, v120, v121
	v_pk_mul_f32 v[120:121], v[122:123], v[148:149] op_sel_hi:[1,0]
	v_pk_mul_f32 v[116:117], v[116:117], v[148:149] op_sel_hi:[1,0]
	v_pk_mul_f32 v[118:119], v[118:119], v[148:149] op_sel_hi:[1,0]
	v_pk_mul_f32 v[108:109], v[108:109], v[148:149] op_sel_hi:[1,0]
	s_ashr_i32 s15, s14, 31
	v_lshlrev_b64 v[150:151], 13, v[140:141]
	v_pk_mul_f32 v[120:121], v[120:121], v[120:121]
	v_pk_mul_f32 v[116:117], v[116:117], v[116:117]
	v_pk_mul_f32 v[118:119], v[118:119], v[118:119]
	v_max_f32_e32 v110, 0, v110
	v_max_f32_e32 v111, 0, v111
	v_pk_mul_f32 v[108:109], v[108:109], v[108:109]
	v_cvt_pk_bf16_f32 v127, v120, v121
	v_lshl_add_u64 v[120:121], s[2:3], 0, v[150:151]
	s_lshl_b64 s[14:15], s[14:15], 1
	v_cvt_pk_bf16_f32 v116, v116, v117
	v_cvt_pk_bf16_f32 v117, v118, v119
	v_cvt_pk_bf16_f32 v118, v108, v109
	v_pk_mul_f32 v[108:109], v[110:111], v[148:149] op_sel_hi:[1,0]
	v_lshl_add_u64 v[120:121], v[120:121], 0, s[14:15]
	v_pk_mul_f32 v[108:109], v[108:109], v[108:109]
	v_lshl_add_u64 v[120:121], v[120:121], 0, s[24:25]
	v_and_b32_e32 v144, 48, v144
	v_cvt_pk_bf16_f32 v119, v108, v109
	v_add_u32_e32 v108, 16, v140
	v_lshl_add_u64 v[120:121], v[120:121], 0, v[144:145]
	v_ashrrev_i32_e32 v109, 31, v108
	global_store_dwordx4 v[120:121], v[116:119], off offset:256
	v_max_f32_e32 v100, 0, v100
	v_max_f32_e32 v101, 0, v101
	v_lshlrev_b64 v[116:117], 13, v[108:109]
	v_max_f32_e32 v108, v112, v112
	v_mov_b32_e32 v112, v149
	v_max_f32_e32 v102, 0, v102
	v_max_f32_e32 v103, 0, v103
	v_max_f32_e32 v96, 0, v96
	v_max_f32_e32 v97, 0, v97
	v_pk_mul_f32 v[100:101], v[100:101], v[112:113] op_sel_hi:[1,0]
	v_pk_mul_f32 v[102:103], v[102:103], v[112:113] op_sel_hi:[1,0]
	v_pk_mul_f32 v[96:97], v[96:97], v[112:113] op_sel_hi:[1,0]
	v_pk_mul_f32 v[100:101], v[100:101], v[100:101]
	v_pk_mul_f32 v[102:103], v[102:103], v[102:103]
	v_max_f32_e32 v98, 0, v98
	v_max_f32_e32 v99, 0, v99
	v_pk_mul_f32 v[96:97], v[96:97], v[96:97]
	v_cvt_pk_bf16_f32 v100, v100, v101
	v_cvt_pk_bf16_f32 v101, v102, v103
	v_cvt_pk_bf16_f32 v102, v96, v97
	v_pk_mul_f32 v[96:97], v[98:99], v[112:113] op_sel_hi:[1,0]
	ds_read2_b32 v[98:99], v146 offset0:32 offset1:48
	v_max_f32_e32 v92, 0, v92
	v_max_f32_e32 v93, 0, v93
	v_max_f32_e32 v94, 0, v94
	v_max_f32_e32 v95, 0, v95
	v_max_f32_e32 v88, 0, v88
	v_max_f32_e32 v89, 0, v89
	v_pk_mul_f32 v[96:97], v[96:97], v[96:97]
	s_waitcnt lgkmcnt(0)
	v_pk_mul_f32 v[92:93], v[92:93], v[98:99] op_sel_hi:[1,0]
	v_pk_mul_f32 v[94:95], v[94:95], v[98:99] op_sel_hi:[1,0]
	v_pk_mul_f32 v[88:89], v[88:89], v[98:99] op_sel_hi:[1,0]
	v_cvt_pk_bf16_f32 v103, v96, v97
	v_add_u32_e32 v96, 32, v140
	v_pk_mul_f32 v[92:93], v[92:93], v[92:93]
	v_pk_mul_f32 v[94:95], v[94:95], v[94:95]
	v_max_f32_e32 v90, 0, v90
	v_max_f32_e32 v91, 0, v91
	v_pk_mul_f32 v[88:89], v[88:89], v[88:89]
	v_max_f32_e32 v84, 0, v84
	v_max_f32_e32 v85, 0, v85
	v_max_f32_e32 v86, 0, v86
	v_max_f32_e32 v87, 0, v87
	v_max_f32_e32 v76, 0, v76
	v_max_f32_e32 v77, 0, v77
	v_ashrrev_i32_e32 v97, 31, v96
	v_cvt_pk_bf16_f32 v92, v92, v93
	v_cvt_pk_bf16_f32 v93, v94, v95
	v_cvt_pk_bf16_f32 v94, v88, v89
	v_pk_mul_f32 v[88:89], v[90:91], v[98:99] op_sel_hi:[1,0]
	v_pk_mul_f32 v[84:85], v[84:85], v[98:99] op_sel_hi:[1,0]
	v_pk_mul_f32 v[86:87], v[86:87], v[98:99] op_sel_hi:[1,0]
	v_pk_mul_f32 v[76:77], v[76:77], v[98:99] op_sel_hi:[1,0]
	v_lshlrev_b64 v[96:97], 13, v[96:97]
	v_pk_mul_f32 v[88:89], v[88:89], v[88:89]
	v_pk_mul_f32 v[84:85], v[84:85], v[84:85]
	v_pk_mul_f32 v[86:87], v[86:87], v[86:87]
	v_max_f32_e32 v78, 0, v78
	v_max_f32_e32 v79, 0, v79
	v_pk_mul_f32 v[76:77], v[76:77], v[76:77]
	v_cvt_pk_bf16_f32 v95, v88, v89
	v_lshl_add_u64 v[88:89], s[2:3], 0, v[96:97]
	v_cvt_pk_bf16_f32 v84, v84, v85
	v_cvt_pk_bf16_f32 v85, v86, v87
	v_cvt_pk_bf16_f32 v86, v76, v77
	v_pk_mul_f32 v[76:77], v[78:79], v[98:99] op_sel_hi:[1,0]
	v_lshl_add_u64 v[88:89], v[88:89], 0, s[14:15]
	v_pk_mul_f32 v[76:77], v[76:77], v[76:77]
	v_lshl_add_u64 v[88:89], v[88:89], 0, s[24:25]
	v_cvt_pk_bf16_f32 v87, v76, v77
	v_add_u32_e32 v76, 48, v140
	v_lshl_add_u64 v[88:89], v[88:89], 0, v[144:145]
	v_ashrrev_i32_e32 v77, 31, v76
	global_store_dwordx4 v[88:89], v[84:87], off offset:256
	v_max_f32_e32 v68, 0, v68
	v_max_f32_e32 v69, 0, v69
	v_lshlrev_b64 v[84:85], 13, v[76:77]
	v_max_f32_e32 v76, v80, v80
	v_mov_b32_e32 v80, v99
	v_max_f32_e32 v70, 0, v70
	v_max_f32_e32 v71, 0, v71
	v_max_f32_e32 v64, 0, v64
	v_max_f32_e32 v65, 0, v65
	v_pk_mul_f32 v[68:69], v[68:69], v[80:81] op_sel_hi:[1,0]
	v_pk_mul_f32 v[70:71], v[70:71], v[80:81] op_sel_hi:[1,0]
	v_pk_mul_f32 v[64:65], v[64:65], v[80:81] op_sel_hi:[1,0]
	v_pk_mul_f32 v[68:69], v[68:69], v[68:69]
	v_pk_mul_f32 v[70:71], v[70:71], v[70:71]
	v_max_f32_e32 v66, 0, v66
	v_max_f32_e32 v67, 0, v67
	v_pk_mul_f32 v[64:65], v[64:65], v[64:65]
	v_cvt_pk_bf16_f32 v68, v68, v69
	v_cvt_pk_bf16_f32 v69, v70, v71
	v_cvt_pk_bf16_f32 v70, v64, v65
	v_pk_mul_f32 v[64:65], v[66:67], v[80:81] op_sel_hi:[1,0]
	ds_read2_b32 v[66:67], v146 offset0:128 offset1:144
	v_max_f32_e32 v60, 0, v60
	v_max_f32_e32 v61, 0, v61
	v_max_f32_e32 v62, 0, v62
	v_max_f32_e32 v63, 0, v63
	v_max_f32_e32 v56, 0, v56
	v_max_f32_e32 v57, 0, v57
	v_pk_mul_f32 v[64:65], v[64:65], v[64:65]
	s_waitcnt lgkmcnt(0)
;   DI void operator()(const f32x4 (&acc)[2][2][4][2], const pg8::Unit& u, int wr, int wc, int fr_, int fq_) const {
;     ...
;             } else {
;               if (n == 0) {
;                 const f32x4 v1 = acc[ai][bj][m][1];
;                 u32x4 o4;
;                 { const float t0 = fmaxf(v[0], 0.f) * rinv, t1 = fmaxf(v[1], 0.f) * rinv, t2 = fmaxf(v[2], 0.f) * rinv, t3 = fmaxf(v[3], 0.f) * rinv;
;                   o4.x = pack2(t0 * t0, t1 * t1); o4.y = pack2(t2 * t2, t3 * t3); }
;                 { const float t0 = fmaxf(v1[0], 0.f) * rinv, t1 = fmaxf(v1[1], 0.f) * rinv, t2 = fmaxf(v1[2], 0.f) * rinv, t3 = fmaxf(v1[3], 0.f) * rinv;
;                   o4.z = pack2(t0 * t0, t1 * t1); o4.w = pack2(t2 * t2, t3 * t3); }
;                 *(u32x4*)((u16*)big + (size_t)token * 4096 + u.pn * 256 + bj * 128 + wc * 32 + 8 * fq) = o4;
;               }
	v_pk_mul_f32 v[60:61], v[60:61], v[66:67] op_sel_hi:[1,0]
	v_pk_mul_f32 v[62:63], v[62:63], v[66:67] op_sel_hi:[1,0]
	v_pk_mul_f32 v[56:57], v[56:57], v[66:67] op_sel_hi:[1,0]
	v_cvt_pk_bf16_f32 v71, v64, v65
	v_add_u32_e32 v64, 0x80, v140
	v_pk_mul_f32 v[60:61], v[60:61], v[60:61]
	v_pk_mul_f32 v[62:63], v[62:63], v[62:63]
	v_max_f32_e32 v58, 0, v58
	v_max_f32_e32 v59, 0, v59
	v_pk_mul_f32 v[56:57], v[56:57], v[56:57]
	v_max_f32_e32 v52, 0, v52
	v_max_f32_e32 v53, 0, v53
	v_max_f32_e32 v54, 0, v54
	v_max_f32_e32 v55, 0, v55
	v_max_f32_e32 v44, 0, v44
	v_max_f32_e32 v45, 0, v45
	v_ashrrev_i32_e32 v65, 31, v64
	v_cvt_pk_bf16_f32 v60, v60, v61
	v_cvt_pk_bf16_f32 v61, v62, v63
	v_cvt_pk_bf16_f32 v62, v56, v57
	v_pk_mul_f32 v[56:57], v[58:59], v[66:67] op_sel_hi:[1,0]
	v_pk_mul_f32 v[52:53], v[52:53], v[66:67] op_sel_hi:[1,0]
	v_pk_mul_f32 v[54:55], v[54:55], v[66:67] op_sel_hi:[1,0]
	v_pk_mul_f32 v[44:45], v[44:45], v[66:67] op_sel_hi:[1,0]
	v_lshlrev_b64 v[64:65], 13, v[64:65]
	v_pk_mul_f32 v[56:57], v[56:57], v[56:57]
	v_pk_mul_f32 v[52:53], v[52:53], v[52:53]
	v_pk_mul_f32 v[54:55], v[54:55], v[54:55]
	v_max_f32_e32 v46, 0, v46
	v_max_f32_e32 v47, 0, v47
	v_pk_mul_f32 v[44:45], v[44:45], v[44:45]
	v_cvt_pk_bf16_f32 v63, v56, v57
	v_lshl_add_u64 v[56:57], s[2:3], 0, v[64:65]
	v_cvt_pk_bf16_f32 v52, v52, v53
	v_cvt_pk_bf16_f32 v53, v54, v55
	v_cvt_pk_bf16_f32 v54, v44, v45
	v_pk_mul_f32 v[44:45], v[46:47], v[66:67] op_sel_hi:[1,0]
	v_lshl_add_u64 v[56:57], v[56:57], 0, s[14:15]
	v_pk_mul_f32 v[44:45], v[44:45], v[44:45]
	v_lshl_add_u64 v[56:57], v[56:57], 0, s[24:25]
	v_cvt_pk_bf16_f32 v55, v44, v45
	v_add_u32_e32 v44, 0x90, v140
	v_lshl_add_u64 v[56:57], v[56:57], 0, v[144:145]
	v_ashrrev_i32_e32 v45, 31, v44
	global_store_dwordx4 v[56:57], v[52:55], off offset:256
	v_max_f32_e32 v36, 0, v36
	v_max_f32_e32 v37, 0, v37
	v_lshlrev_b64 v[52:53], 13, v[44:45]
	v_max_f32_e32 v44, v48, v48
	v_mov_b32_e32 v48, v67
	v_max_f32_e32 v38, 0, v38
	v_max_f32_e32 v39, 0, v39
	v_max_f32_e32 v32, 0, v32
	v_max_f32_e32 v33, 0, v33
	v_pk_mul_f32 v[36:37], v[36:37], v[48:49] op_sel_hi:[1,0]
	v_pk_mul_f32 v[38:39], v[38:39], v[48:49] op_sel_hi:[1,0]
	v_pk_mul_f32 v[32:33], v[32:33], v[48:49] op_sel_hi:[1,0]
	v_pk_mul_f32 v[36:37], v[36:37], v[36:37]
	v_pk_mul_f32 v[38:39], v[38:39], v[38:39]
	v_max_f32_e32 v34, 0, v34
	v_max_f32_e32 v35, 0, v35
	v_pk_mul_f32 v[32:33], v[32:33], v[32:33]
	v_cvt_pk_bf16_f32 v36, v36, v37
	v_cvt_pk_bf16_f32 v37, v38, v39
	v_cvt_pk_bf16_f32 v38, v32, v33
	v_pk_mul_f32 v[32:33], v[34:35], v[48:49] op_sel_hi:[1,0]
	ds_read2_b32 v[34:35], v146 offset0:160 offset1:176
	v_max_f32_e32 v28, 0, v28
	v_max_f32_e32 v29, 0, v29
	v_max_f32_e32 v30, 0, v30
	v_max_f32_e32 v31, 0, v31
	v_max_f32_e32 v24, 0, v24
	v_max_f32_e32 v25, 0, v25
	v_pk_mul_f32 v[32:33], v[32:33], v[32:33]
	s_waitcnt lgkmcnt(0)
	v_pk_mul_f32 v[28:29], v[28:29], v[34:35] op_sel_hi:[1,0]
	v_pk_mul_f32 v[30:31], v[30:31], v[34:35] op_sel_hi:[1,0]
	v_pk_mul_f32 v[24:25], v[24:25], v[34:35] op_sel_hi:[1,0]
	v_cvt_pk_bf16_f32 v39, v32, v33
	v_add_u32_e32 v32, 0xa0, v140
	v_pk_mul_f32 v[28:29], v[28:29], v[28:29]
	v_pk_mul_f32 v[30:31], v[30:31], v[30:31]
	v_max_f32_e32 v26, 0, v26
	v_max_f32_e32 v27, 0, v27
	v_pk_mul_f32 v[24:25], v[24:25], v[24:25]
	v_max_f32_e32 v20, 0, v20
	v_max_f32_e32 v21, 0, v21
	v_max_f32_e32 v22, 0, v22
	v_max_f32_e32 v23, 0, v23
	v_max_f32_e32 v12, 0, v12
	v_max_f32_e32 v13, 0, v13
	v_ashrrev_i32_e32 v33, 31, v32
	v_cvt_pk_bf16_f32 v28, v28, v29
	v_cvt_pk_bf16_f32 v29, v30, v31
	v_cvt_pk_bf16_f32 v30, v24, v25
	v_pk_mul_f32 v[24:25], v[26:27], v[34:35] op_sel_hi:[1,0]
	v_pk_mul_f32 v[20:21], v[20:21], v[34:35] op_sel_hi:[1,0]
	v_pk_mul_f32 v[22:23], v[22:23], v[34:35] op_sel_hi:[1,0]
	v_pk_mul_f32 v[12:13], v[12:13], v[34:35] op_sel_hi:[1,0]
	v_lshlrev_b64 v[32:33], 13, v[32:33]
	v_pk_mul_f32 v[24:25], v[24:25], v[24:25]
	v_pk_mul_f32 v[20:21], v[20:21], v[20:21]
	v_pk_mul_f32 v[22:23], v[22:23], v[22:23]
	v_max_f32_e32 v14, 0, v14
	v_max_f32_e32 v15, 0, v15
	v_pk_mul_f32 v[12:13], v[12:13], v[12:13]
	v_cvt_pk_bf16_f32 v31, v24, v25
	v_lshl_add_u64 v[24:25], s[2:3], 0, v[32:33]
	v_cvt_pk_bf16_f32 v20, v20, v21
	v_cvt_pk_bf16_f32 v21, v22, v23
	v_cvt_pk_bf16_f32 v22, v12, v13
	v_pk_mul_f32 v[12:13], v[14:15], v[34:35] op_sel_hi:[1,0]
	v_lshl_add_u64 v[24:25], v[24:25], 0, s[14:15]
	v_pk_mul_f32 v[12:13], v[12:13], v[12:13]
	v_lshl_add_u64 v[24:25], v[24:25], 0, s[24:25]
	v_cvt_pk_bf16_f32 v23, v12, v13
	v_add_u32_e32 v12, 0xb0, v140
	v_lshl_add_u64 v[24:25], v[24:25], 0, v[144:145]
	v_ashrrev_i32_e32 v13, 31, v12
	v_max_f32_e32 v109, v113, v113
	v_max_f32_e32 v110, v114, v114
	v_max_f32_e32 v111, v115, v115
	v_max_f32_e32 v77, v81, v81
	v_max_f32_e32 v78, v82, v82
	v_max_f32_e32 v79, v83, v83
	v_max_f32_e32 v45, v49, v49
	v_max_f32_e32 v46, v50, v50
	v_max_f32_e32 v47, v51, v51
	global_store_dwordx4 v[24:25], v[20:23], off offset:256
	v_max_f32_e32 v14, v18, v18
	v_max_f32_e32 v15, v19, v19
	v_lshlrev_b64 v[20:21], 13, v[12:13]
	v_max_f32_e32 v12, v16, v16
	v_max_f32_e32 v13, v17, v17
	v_max_f32_e32 v108, 0, v108
	v_max_f32_e32 v109, 0, v109
	v_max_f32_e32 v110, 0, v110
	v_max_f32_e32 v111, 0, v111
	v_max_f32_e32 v104, 0, v104
	v_max_f32_e32 v105, 0, v105
	v_max_f32_e32 v76, 0, v76
; #define PG8_WAIT_V(n) asm volatile("s_waitcnt vmcnt(" #n ")" ::: "memory")
; #define PG8_BAR __builtin_amdgcn_s_barrier()
; template <class Epi, class Sched>
; DI void gemm_phase(LAS unsigned char* lds, const Gemm g, const Sched& S, const Epi& E) {
;     ...
;   PG8_WAIT_V(0);
;   if (wr == 0) PG8_BAR;
;   PG8_BAR;
;   DI void operator()(const f32x4 (&acc)[2][2][4][2], const pg8::Unit& u, int wr, int wc, int fr_, int fq_) const {
;     ...
;               if (n == 0) {
;                 const f32x4 v1 = acc[ai][bj][m][1];
;                 u32x4 o4;
;                 { const float t0 = fmaxf(v[0], 0.f) * rinv, t1 = fmaxf(v[1], 0.f) * rinv, t2 = fmaxf(v[2], 0.f) * rinv, t3 = fmaxf(v[3], 0.f) * rinv;
;                   o4.x = pack2(t0 * t0, t1 * t1); o4.y = pack2(t2 * t2, t3 * t3); }
;                 { const float t0 = fmaxf(v1[0], 0.f) * rinv, t1 = fmaxf(v1[1], 0.f) * rinv, t2 = fmaxf(v1[2], 0.f) * rinv, t3 = fmaxf(v1[3], 0.f) * rinv;
;                   o4.z = pack2(t0 * t0, t1 * t1); o4.w = pack2(t2 * t2, t3 * t3); }
;                 *(u32x4*)((u16*)big + (size_t)token * 4096 + u.pn * 256 + bj * 128 + wc * 32 + 8 * fq) = o4;
	v_max_f32_e32 v77, 0, v77
	v_max_f32_e32 v78, 0, v78
	v_max_f32_e32 v79, 0, v79
	v_max_f32_e32 v72, 0, v72
	v_max_f32_e32 v73, 0, v73
	v_max_f32_e32 v44, 0, v44
	v_max_f32_e32 v45, 0, v45
	v_max_f32_e32 v46, 0, v46
	v_max_f32_e32 v47, 0, v47
	v_max_f32_e32 v40, 0, v40
	v_max_f32_e32 v41, 0, v41
	v_max_f32_e32 v12, 0, v12
	v_max_f32_e32 v13, 0, v13
	v_max_f32_e32 v14, 0, v14
	v_max_f32_e32 v15, 0, v15
	v_mov_b32_e32 v16, v35
	v_max_f32_e32 v8, 0, v8
	v_max_f32_e32 v9, 0, v9
	v_pk_mul_f32 v[108:109], v[108:109], v[112:113] op_sel_hi:[1,0]
	v_pk_mul_f32 v[110:111], v[110:111], v[112:113] op_sel_hi:[1,0]
	v_pk_mul_f32 v[104:105], v[104:105], v[112:113] op_sel_hi:[1,0]
	v_pk_mul_f32 v[76:77], v[76:77], v[80:81] op_sel_hi:[1,0]
	v_pk_mul_f32 v[78:79], v[78:79], v[80:81] op_sel_hi:[1,0]
	v_pk_mul_f32 v[72:73], v[72:73], v[80:81] op_sel_hi:[1,0]
	v_pk_mul_f32 v[44:45], v[44:45], v[48:49] op_sel_hi:[1,0]
	v_pk_mul_f32 v[46:47], v[46:47], v[48:49] op_sel_hi:[1,0]
	v_pk_mul_f32 v[40:41], v[40:41], v[48:49] op_sel_hi:[1,0]
	v_pk_mul_f32 v[12:13], v[12:13], v[16:17] op_sel_hi:[1,0]
	v_pk_mul_f32 v[14:15], v[14:15], v[16:17] op_sel_hi:[1,0]
	v_pk_mul_f32 v[8:9], v[8:9], v[16:17] op_sel_hi:[1,0]
	v_pk_mul_f32 v[108:109], v[108:109], v[108:109]
	v_pk_mul_f32 v[110:111], v[110:111], v[110:111]
	v_max_f32_e32 v106, 0, v106
	v_max_f32_e32 v107, 0, v107
	v_pk_mul_f32 v[104:105], v[104:105], v[104:105]
	v_pk_mul_f32 v[76:77], v[76:77], v[76:77]
	v_pk_mul_f32 v[78:79], v[78:79], v[78:79]
	v_max_f32_e32 v74, 0, v74
	v_max_f32_e32 v75, 0, v75
	v_pk_mul_f32 v[72:73], v[72:73], v[72:73]
	v_pk_mul_f32 v[44:45], v[44:45], v[44:45]
	v_pk_mul_f32 v[46:47], v[46:47], v[46:47]
	v_max_f32_e32 v42, 0, v42
	v_max_f32_e32 v43, 0, v43
	v_pk_mul_f32 v[40:41], v[40:41], v[40:41]
	v_pk_mul_f32 v[12:13], v[12:13], v[12:13]
	v_pk_mul_f32 v[14:15], v[14:15], v[14:15]
	v_max_f32_e32 v10, 0, v10
	v_max_f32_e32 v11, 0, v11
	v_pk_mul_f32 v[8:9], v[8:9], v[8:9]
	v_cvt_pk_bf16_f32 v108, v108, v109
	v_cvt_pk_bf16_f32 v109, v110, v111
	v_cvt_pk_bf16_f32 v110, v104, v105
	v_pk_mul_f32 v[104:105], v[106:107], v[112:113] op_sel_hi:[1,0]
	v_cvt_pk_bf16_f32 v76, v76, v77
	v_cvt_pk_bf16_f32 v77, v78, v79
	v_cvt_pk_bf16_f32 v78, v72, v73
	v_pk_mul_f32 v[72:73], v[74:75], v[80:81] op_sel_hi:[1,0]
	v_cvt_pk_bf16_f32 v44, v44, v45
	v_cvt_pk_bf16_f32 v45, v46, v47
	v_cvt_pk_bf16_f32 v46, v40, v41
	v_pk_mul_f32 v[40:41], v[42:43], v[48:49] op_sel_hi:[1,0]
	v_cvt_pk_bf16_f32 v12, v12, v13
	v_cvt_pk_bf16_f32 v13, v14, v15
	v_cvt_pk_bf16_f32 v14, v8, v9
	v_pk_mul_f32 v[8:9], v[10:11], v[16:17] op_sel_hi:[1,0]
	v_max_f32_e32 v4, 0, v4
	v_max_f32_e32 v5, 0, v5
	v_max_f32_e32 v6, 0, v6
	v_max_f32_e32 v7, 0, v7
	v_max_f32_e32 v0, 0, v0
	v_max_f32_e32 v1, 0, v1
	v_pk_mul_f32 v[104:105], v[104:105], v[104:105]
	v_pk_mul_f32 v[72:73], v[72:73], v[72:73]
	v_pk_mul_f32 v[40:41], v[40:41], v[40:41]
	v_pk_mul_f32 v[8:9], v[8:9], v[8:9]
	v_pk_mul_f32 v[4:5], v[4:5], v[16:17] op_sel_hi:[1,0]
	v_pk_mul_f32 v[6:7], v[6:7], v[16:17] op_sel_hi:[1,0]
	v_pk_mul_f32 v[0:1], v[0:1], v[16:17] op_sel_hi:[1,0]
	v_cvt_pk_bf16_f32 v111, v104, v105
	v_lshl_add_u64 v[104:105], s[2:3], 0, v[116:117]
	v_cvt_pk_bf16_f32 v79, v72, v73
	v_lshl_add_u64 v[72:73], s[2:3], 0, v[84:85]
	v_cvt_pk_bf16_f32 v47, v40, v41
	v_lshl_add_u64 v[40:41], s[2:3], 0, v[52:53]
	v_cvt_pk_bf16_f32 v15, v8, v9
	v_lshl_add_u64 v[8:9], s[2:3], 0, v[20:21]
	v_pk_mul_f32 v[4:5], v[4:5], v[4:5]
	v_pk_mul_f32 v[6:7], v[6:7], v[6:7]
	v_max_f32_e32 v2, 0, v2
	v_max_f32_e32 v3, 0, v3
	v_pk_mul_f32 v[0:1], v[0:1], v[0:1]
	v_lshl_add_u64 v[104:105], v[104:105], 0, s[14:15]
	v_lshl_add_u64 v[72:73], v[72:73], 0, s[14:15]
	v_lshl_add_u64 v[40:41], v[40:41], 0, s[14:15]
	v_lshl_add_u64 v[8:9], v[8:9], 0, s[14:15]
	v_cvt_pk_bf16_f32 v4, v4, v5
	v_cvt_pk_bf16_f32 v5, v6, v7
	v_cvt_pk_bf16_f32 v6, v0, v1
	v_pk_mul_f32 v[0:1], v[2:3], v[16:17] op_sel_hi:[1,0]
	v_lshl_add_u64 v[104:105], v[104:105], 0, s[24:25]
	v_lshl_add_u64 v[72:73], v[72:73], 0, s[24:25]
	v_lshl_add_u64 v[40:41], v[40:41], 0, s[24:25]
	v_lshl_add_u64 v[8:9], v[8:9], 0, s[24:25]
	v_pk_mul_f32 v[0:1], v[0:1], v[0:1]
	v_lshl_add_u64 v[104:105], v[104:105], 0, v[144:145]
	v_lshl_add_u64 v[72:73], v[72:73], 0, v[144:145]
	v_lshl_add_u64 v[40:41], v[40:41], 0, v[144:145]
	v_lshl_add_u64 v[8:9], v[8:9], 0, v[144:145]
	v_cvt_pk_bf16_f32 v7, v0, v1
	s_and_b64 vcc, exec, s[36:37]
	s_mov_b32 s43, s42
	s_mov_b32 s45, s4
	s_mov_b32 s44, s6
	s_mov_b64 s[16:17], s[12:13]
	s_mov_b64 s[14:15], s[10:11]
	v_readlane_b32 s51, v237, 11
	global_store_dwordx4 v[120:121], v[124:127], off
	global_store_dwordx4 v[104:105], v[108:111], off
	global_store_dwordx4 v[104:105], v[100:103], off offset:256
	global_store_dwordx4 v[88:89], v[92:95], off
	global_store_dwordx4 v[72:73], v[76:79], off
	global_store_dwordx4 v[72:73], v[68:71], off offset:256
	global_store_dwordx4 v[56:57], v[60:63], off
	global_store_dwordx4 v[40:41], v[44:47], off
	global_store_dwordx4 v[40:41], v[36:39], off offset:256
	global_store_dwordx4 v[24:25], v[28:31], off
	global_store_dwordx4 v[8:9], v[12:15], off
	global_store_dwordx4 v[8:9], v[4:7], off offset:256
	s_cbranch_vccz .LBB0_1822
	s_waitcnt vmcnt(0)
	s_cmpk_gt_u32 s9, 0xff
	s_cbranch_scc1 .LBB0_1833
	s_barrier

; #define PG8_STAGE(bufoff, gbase, voff) do { _Pragma("unroll") for (int _i = 0; _i < 2; ++_i) \
;     __builtin_amdgcn_global_load_lds((const unsigned*)((const char*)(gbase) + (voff)[_i]), (LAS unsigned*)(lds + (bufoff) + ldsw + _i * 8192), 16, 0, 0); } while (0)
; #define PG8_LDA(dst, b, h) do { _Pragma("unroll") for (int m = 0; m < 4; ++m) _Pragma("unroll") for (int k = 0; k < 2; ++k) dst[m][k] = *(const LAS bf16x8*)(lds + PG8_SA(b, h) + aoff + m * 2048 + k * 1024); } while (0)
; #define PG8_LDB(dst, b, h) do { _Pragma("unroll") for (int n = 0; n < 2; ++n) _Pragma("unroll") for (int k = 0; k < 2; ++k) dst[n][k] = *(const LAS bf16x8*)(lds + PG8_SB(b, h) + boff + n * 2048 + k * 1024); } while (0)
; #define PG8_MMA(ai, bj, At, Bt) do { __builtin_amdgcn_s_setprio(1); _Pragma("unroll") for (int m = 0; m < 4; ++m) _Pragma("unroll") for (int n = 0; n < 2; ++n) _Pragma("unroll") for (int k = 0; k < 2; ++k) \
;     acc[ai][bj][m][n] = __builtin_amdgcn_mfma_f32_16x16x32_bf16(Bt[n][k], At[m][k], acc[ai][bj][m][n], 0, 0, 0); __builtin_amdgcn_s_setprio(0); } while (0)
; template <class Epi, class Sched>
; DI void gemm_phase(LAS unsigned char* lds, const Gemm g, const Sched& S, const Epi& E) {
;     ...
;     const bool has_next = S.next(ui + 1, nxt);
;     const char* nA = has_next ? (const char*)g.A + (size_t)nxt.pm * tstep : cA; const char* nB = has_next ? (const char*)g.Bt + (size_t)nxt.pn * tstep : cB;
; #pragma unroll 1
;     for (int t = 0; t < nt; t += 2) {
;       const bool last = (t == nt - 2);
;       const char* a1 = cA + (size_t)(t + 1) * kstep;
;       const char* a2 = last ? nA : cA + (size_t)(t + 2) * kstep; const char* b2 = last ? nB : cB + (size_t)(t + 2) * kstep;
;       const char* a3 = a2 + kstep; const char* b3 = b2 + kstep;
;       PG8_LDB(B0, 0, 0); PG8_SCHED; PG8_LDA(At, 0, 0); PG8_STAGE(PG8_SA(1, 1), a1 + hstep, voffA);
;       PG8_WAIT_L(8); PG8_BAR; PG8_WAIT_L(0); PG8_MMA(0, 0, At, B0); PG8_BAR; PG8_SCHED;
;       PG8_LDB(B1, 0, 1); PG8_STAGE(PG8_SB(0, 0), b2, voffB);
;       PG8_BAR; PG8_WAIT_L(0); PG8_MMA(0, 1, At, B1); PG8_BAR;
;     ...
; #pragma unroll
;     for (int a = 0; a < 2; ++a)
; #pragma unroll
;       for (int b = 0; b < 2; ++b)
; #pragma unroll
;         for (int m = 0; m < 4; ++m)
; #pragma unroll
;           for (int n = 0; n < 2; ++n) acc[a][b][m][n] = (f32x4){0.f, 0.f, 0.f, 0.f};
;     cur = nxt; cA = nA; cB = nB; ++ui;
.LBB0_1904:
	v_mov_b64_e32 v[0:1], s[30:31]
	s_ashr_i32 s11, s10, 31
	v_cmp_lt_i64_e32 vcc, s[12:13], v[0:1]
	s_lshl_b64 s[12:13], s[10:11], 21
	s_add_u32 s12, s34, s12
	s_addc_u32 s13, s35, s13
	s_and_b64 s[14:15], vcc, exec
	s_cselect_b32 s11, s13, s21
	s_cselect_b32 s17, s12, s20
	s_ashr_i32 s7, s6, 31
	s_lshl_b64 s[14:15], s[6:7], 21
	s_add_u32 s14, s36, s14
	s_addc_u32 s15, s37, s15
	s_and_b64 s[28:29], vcc, exec
	s_cselect_b32 s7, s15, s23
	s_cselect_b32 s19, s14, s22
	s_add_u32 s20, s20, 0x100080
	s_addc_u32 s21, s21, 0
	s_add_u32 s24, s22, 0x100
	v_mov_b32_e32 v0, 0
	s_addc_u32 s49, s23, 0
	s_mov_b32 s50, -2
	v_mov_b32_e32 v1, v0
	v_mov_b64_e32 v[2:3], v[0:1]
	v_mov_b64_e32 v[4:5], v[0:1]
	v_mov_b64_e32 v[6:7], v[0:1]
	v_mov_b64_e32 v[8:9], v[0:1]
	v_mov_b64_e32 v[10:11], v[0:1]
	v_mov_b64_e32 v[12:13], v[0:1]
	v_mov_b64_e32 v[14:15], v[0:1]
	v_mov_b64_e32 v[16:17], v[0:1]
	v_mov_b64_e32 v[18:19], v[0:1]
	v_mov_b64_e32 v[20:21], v[0:1]
	v_mov_b64_e32 v[22:23], v[0:1]
	v_mov_b64_e32 v[24:25], v[0:1]
	v_mov_b64_e32 v[26:27], v[0:1]
	v_mov_b64_e32 v[28:29], v[0:1]
	v_mov_b64_e32 v[30:31], v[0:1]
	v_mov_b64_e32 v[32:33], v[0:1]
	v_mov_b64_e32 v[34:35], v[0:1]
	v_mov_b64_e32 v[36:37], v[0:1]
	v_mov_b64_e32 v[38:39], v[0:1]
	v_mov_b64_e32 v[40:41], v[0:1]
	v_mov_b64_e32 v[42:43], v[0:1]
	v_mov_b64_e32 v[44:45], v[0:1]
	v_mov_b64_e32 v[46:47], v[0:1]
	v_mov_b64_e32 v[48:49], v[0:1]
	v_mov_b64_e32 v[50:51], v[0:1]
	v_mov_b64_e32 v[52:53], v[0:1]
	v_mov_b64_e32 v[54:55], v[0:1]
	v_mov_b64_e32 v[56:57], v[0:1]
	v_mov_b64_e32 v[58:59], v[0:1]
	v_mov_b64_e32 v[60:61], v[0:1]
	v_mov_b64_e32 v[62:63], v[0:1]
	v_mov_b64_e32 v[64:65], v[0:1]
	v_mov_b64_e32 v[66:67], v[0:1]
	v_mov_b64_e32 v[68:69], v[0:1]
	v_mov_b64_e32 v[70:71], v[0:1]
	v_mov_b64_e32 v[72:73], v[0:1]
	v_mov_b64_e32 v[74:75], v[0:1]
	v_mov_b64_e32 v[76:77], v[0:1]
	v_mov_b64_e32 v[78:79], v[0:1]
	v_mov_b64_e32 v[80:81], v[0:1]
	v_mov_b64_e32 v[82:83], v[0:1]
	v_mov_b64_e32 v[84:85], v[0:1]
	v_mov_b64_e32 v[86:87], v[0:1]
	v_mov_b64_e32 v[88:89], v[0:1]
	v_mov_b64_e32 v[90:91], v[0:1]
	v_mov_b64_e32 v[92:93], v[0:1]
	v_mov_b64_e32 v[94:95], v[0:1]
	v_mov_b64_e32 v[96:97], v[0:1]
	v_mov_b64_e32 v[98:99], v[0:1]
	v_mov_b64_e32 v[100:101], v[0:1]
	v_mov_b64_e32 v[102:103], v[0:1]
	v_mov_b64_e32 v[104:105], v[0:1]
	v_mov_b64_e32 v[106:107], v[0:1]
	v_mov_b64_e32 v[108:109], v[0:1]
	v_mov_b64_e32 v[110:111], v[0:1]
	v_mov_b64_e32 v[112:113], v[0:1]
	v_mov_b64_e32 v[114:115], v[0:1]
	v_mov_b64_e32 v[116:117], v[0:1]
	v_mov_b64_e32 v[118:119], v[0:1]
	v_mov_b64_e32 v[120:121], v[0:1]
	v_mov_b64_e32 v[122:123], v[0:1]
	v_mov_b64_e32 v[124:125], v[0:1]
	v_mov_b64_e32 v[126:127], v[0:1]
	v_add_u32_e32 v224, 0x10000, v146
	v_add_u32_e32 v225, 0x14000, v146
	v_add_u32_e32 v226, 0x18000, v146
	v_add_u32_e32 v227, 0x1c000, v146
.LBB0_1905:
	s_add_u32 s22, s20, 0xfff00080
	s_addc_u32 s23, s21, -1
	s_add_i32 s51, 0, 0x10000
	ds_read_b128 v[138:141], v224
	ds_read_b128 v[148:151], v224 offset:1024
	ds_read_b128 v[152:155], v224 offset:2048
	ds_read_b128 v[156:159], v224 offset:3072
	s_cmp_eq_u32 s50, 60
	s_cselect_b32 s29, s11, s23
	s_cselect_b32 s28, s17, s22
	s_cselect_b32 s23, s7, s49
	s_cselect_b32 s22, s19, s24
	s_add_i32 m0, s39, 0xc000
	ds_read_b128 v[160:163], v147
	ds_read_b128 v[164:167], v147 offset:1024
	ds_read_b128 v[168:171], v147 offset:2048
	ds_read_b128 v[172:175], v147 offset:3072
	ds_read_b128 v[176:179], v147 offset:4096
	ds_read_b128 v[196:199], v147 offset:5120
	ds_read_b128 v[200:203], v147 offset:6144
	ds_read_b128 v[204:207], v147 offset:7168
	global_load_lds_dwordx4 v134, s[20:21]
	s_add_i32 m0, s39, 0xe000
	s_nop 0
	global_load_lds_dwordx4 v136, s[20:21]
	s_waitcnt lgkmcnt(8)
	s_barrier
	s_waitcnt lgkmcnt(0)
	s_waitcnt lgkmcnt(0)
	v_mfma_f32_16x16x32_bf16 v[124:127], v[138:141], v[160:163], v[124:127]
	v_mfma_f32_16x16x32_bf16 v[120:123], v[152:155], v[160:163], v[120:123]
	v_mfma_f32_16x16x32_bf16 v[108:111], v[138:141], v[168:171], v[108:111]
	v_mfma_f32_16x16x32_bf16 v[104:107], v[152:155], v[168:171], v[104:107]
	v_mfma_f32_16x16x32_bf16 v[92:95], v[138:141], v[176:179], v[92:95]
	v_mfma_f32_16x16x32_bf16 v[88:91], v[152:155], v[176:179], v[88:91]
	v_mfma_f32_16x16x32_bf16 v[76:79], v[138:141], v[200:203], v[76:79]
	v_mfma_f32_16x16x32_bf16 v[72:75], v[152:155], v[200:203], v[72:75]
	v_mfma_f32_16x16x32_bf16 v[124:127], v[148:151], v[164:167], v[124:127]
	v_mfma_f32_16x16x32_bf16 v[120:123], v[156:159], v[164:167], v[120:123]
	v_mfma_f32_16x16x32_bf16 v[108:111], v[148:151], v[172:175], v[108:111]
	v_mfma_f32_16x16x32_bf16 v[104:107], v[156:159], v[172:175], v[104:107]
	v_mfma_f32_16x16x32_bf16 v[92:95], v[148:151], v[196:199], v[92:95]
	v_mfma_f32_16x16x32_bf16 v[88:91], v[156:159], v[196:199], v[88:91]
	v_mfma_f32_16x16x32_bf16 v[76:79], v[148:151], v[204:207], v[76:79]
	v_mfma_f32_16x16x32_bf16 v[72:75], v[156:159], v[204:207], v[72:75]
	s_barrier
	s_add_i32 s54, 0, 0x14000
	s_add_i32 s51, s51, s38
	ds_read_b128 v[208:211], v225
	ds_read_b128 v[212:215], v225 offset:1024
	ds_read_b128 v[216:219], v225 offset:2048
	ds_read_b128 v[220:223], v225 offset:3072
	s_add_u32 vcc_lo, s22, s0
	s_addc_u32 vcc_hi, s23, s1
	s_mov_b32 m0, s51
	s_nop 0
	global_load_lds_dwordx4 v144, s[22:23]
	s_add_i32 m0, s51, 0x2000
	s_nop 0
	global_load_lds_dwordx4 v132, s[22:23]
	s_barrier
; #define PG8_STAGE(bufoff, gbase, voff) do { _Pragma("unroll") for (int _i = 0; _i < 2; ++_i) \
;     __builtin_amdgcn_global_load_lds((const unsigned*)((const char*)(gbase) + (voff)[_i]), (LAS unsigned*)(lds + (bufoff) + ldsw + _i * 8192), 16, 0, 0); } while (0)
; #define PG8_LDA(dst, b, h) do { _Pragma("unroll") for (int m = 0; m < 4; ++m) _Pragma("unroll") for (int k = 0; k < 2; ++k) dst[m][k] = *(const LAS bf16x8*)(lds + PG8_SA(b, h) + aoff + m * 2048 + k * 1024); } while (0)
; #define PG8_LDB(dst, b, h) do { _Pragma("unroll") for (int n = 0; n < 2; ++n) _Pragma("unroll") for (int k = 0; k < 2; ++k) dst[n][k] = *(const LAS bf16x8*)(lds + PG8_SB(b, h) + boff + n * 2048 + k * 1024); } while (0)
; #define PG8_MMA(ai, bj, At, Bt) do { __builtin_amdgcn_s_setprio(1); _Pragma("unroll") for (int m = 0; m < 4; ++m) _Pragma("unroll") for (int n = 0; n < 2; ++n) _Pragma("unroll") for (int k = 0; k < 2; ++k) \
;     acc[ai][bj][m][n] = __builtin_amdgcn_mfma_f32_16x16x32_bf16(Bt[n][k], At[m][k], acc[ai][bj][m][n], 0, 0, 0); __builtin_amdgcn_s_setprio(0); } while (0)
; #define PG8_WAIT_V(n) asm volatile("s_waitcnt vmcnt(" #n ")" ::: "memory")
; #define PG8_WAIT_L(n) asm volatile("s_waitcnt lgkmcnt(" #n ")" ::: "memory")
; #define PG8_BAR __builtin_amdgcn_s_barrier()
; #define PG8_SCHED __builtin_amdgcn_sched_barrier(0)
; template <class Epi, class Sched>
; DI void gemm_phase(LAS unsigned char* lds, const Gemm g, const Sched& S, const Epi& E) {
;     ...
;       PG8_BAR; PG8_WAIT_L(0); PG8_MMA(0, 1, At, B1); PG8_BAR;
;       PG8_LDA(At, 0, 1); PG8_STAGE(PG8_SA(0, 0), a2, voffA);
;       PG8_BAR; PG8_WAIT_L(0); PG8_MMA(1, 0, At, B0); PG8_BAR; PG8_SCHED;
;       PG8_STAGE(PG8_SB(0, 1), b2 + hstep, voffB);
;       PG8_WAIT_V(6); PG8_BAR; PG8_MMA(1, 1, At, B1); PG8_BAR;
;       PG8_LDB(B0, 1, 0); PG8_SCHED; PG8_LDA(At, 1, 0); PG8_STAGE(PG8_SA(0, 1), a2 + hstep, voffA);
;       PG8_WAIT_L(8); PG8_BAR; PG8_WAIT_L(0); PG8_MMA(0, 0, At, B0); PG8_BAR; PG8_SCHED;
	s_waitcnt lgkmcnt(0)
	s_waitcnt lgkmcnt(0)
	v_mfma_f32_16x16x32_bf16 v[116:119], v[208:211], v[160:163], v[116:119]
	v_mfma_f32_16x16x32_bf16 v[112:115], v[216:219], v[160:163], v[112:115]
	v_mfma_f32_16x16x32_bf16 v[100:103], v[208:211], v[168:171], v[100:103]
	v_mfma_f32_16x16x32_bf16 v[96:99], v[216:219], v[168:171], v[96:99]
	v_mfma_f32_16x16x32_bf16 v[84:87], v[208:211], v[176:179], v[84:87]
	v_mfma_f32_16x16x32_bf16 v[80:83], v[216:219], v[176:179], v[80:83]
	v_mfma_f32_16x16x32_bf16 v[68:71], v[208:211], v[200:203], v[68:71]
	v_mfma_f32_16x16x32_bf16 v[64:67], v[216:219], v[200:203], v[64:67]
	v_mfma_f32_16x16x32_bf16 v[116:119], v[212:215], v[164:167], v[116:119]
	v_mfma_f32_16x16x32_bf16 v[112:115], v[220:223], v[164:167], v[112:115]
	v_mfma_f32_16x16x32_bf16 v[100:103], v[212:215], v[172:175], v[100:103]
	v_mfma_f32_16x16x32_bf16 v[96:99], v[220:223], v[172:175], v[96:99]
	v_mfma_f32_16x16x32_bf16 v[84:87], v[212:215], v[196:199], v[84:87]
	v_mfma_f32_16x16x32_bf16 v[80:83], v[220:223], v[196:199], v[80:83]
	v_mfma_f32_16x16x32_bf16 v[68:71], v[212:215], v[204:207], v[68:71]
	v_mfma_f32_16x16x32_bf16 v[64:67], v[220:223], v[204:207], v[64:67]
	s_mov_b32 m0, s39
	s_add_u32 s100, s28, s0
	s_addc_u32 s101, s29, s1
	s_barrier
	ds_read_b128 v[160:163], v147 offset:16384
	ds_read_b128 v[164:167], v147 offset:17408
	ds_read_b128 v[168:171], v147 offset:18432
	ds_read_b128 v[172:175], v147 offset:19456
	ds_read_b128 v[176:179], v147 offset:20480
	ds_read_b128 v[196:199], v147 offset:21504
	ds_read_b128 v[200:203], v147 offset:22528
	ds_read_b128 v[204:207], v147 offset:23552
	global_load_lds_dwordx4 v128, s[28:29]
	s_mov_b32 m0, s40
	s_nop 0
	global_load_lds_dwordx4 v130, s[28:29]
	s_barrier
	s_waitcnt lgkmcnt(0)
	s_waitcnt lgkmcnt(0)
	v_mfma_f32_16x16x32_bf16 v[60:63], v[138:141], v[160:163], v[60:63]
	v_mfma_f32_16x16x32_bf16 v[56:59], v[152:155], v[160:163], v[56:59]
	v_mfma_f32_16x16x32_bf16 v[44:47], v[138:141], v[168:171], v[44:47]
	v_mfma_f32_16x16x32_bf16 v[40:43], v[152:155], v[168:171], v[40:43]
	v_mfma_f32_16x16x32_bf16 v[28:31], v[138:141], v[176:179], v[28:31]
	v_mfma_f32_16x16x32_bf16 v[24:27], v[152:155], v[176:179], v[24:27]
	v_mfma_f32_16x16x32_bf16 v[12:15], v[138:141], v[200:203], v[12:15]
	v_mfma_f32_16x16x32_bf16 v[8:11], v[152:155], v[200:203], v[8:11]
	v_mfma_f32_16x16x32_bf16 v[60:63], v[148:151], v[164:167], v[60:63]
	v_mfma_f32_16x16x32_bf16 v[56:59], v[156:159], v[164:167], v[56:59]
	v_mfma_f32_16x16x32_bf16 v[44:47], v[148:151], v[172:175], v[44:47]
	v_mfma_f32_16x16x32_bf16 v[40:43], v[156:159], v[172:175], v[40:43]
	v_mfma_f32_16x16x32_bf16 v[28:31], v[148:151], v[196:199], v[28:31]
	v_mfma_f32_16x16x32_bf16 v[24:27], v[156:159], v[196:199], v[24:27]
	v_mfma_f32_16x16x32_bf16 v[12:15], v[148:151], v[204:207], v[12:15]
	v_mfma_f32_16x16x32_bf16 v[8:11], v[156:159], v[204:207], v[8:11]
	s_barrier
	s_add_u32 s52, s22, 0x100000
	s_addc_u32 s53, s23, 0
	s_add_i32 s51, s54, s38
	s_mov_b32 m0, s51
	s_nop 0
	global_load_lds_dwordx4 v144, s[52:53]
	s_add_i32 m0, s51, 0x2000
	s_nop 0
	global_load_lds_dwordx4 v132, s[52:53]
	s_waitcnt vmcnt(6)
	s_barrier
	v_mfma_f32_16x16x32_bf16 v[52:55], v[208:211], v[160:163], v[52:55]
	v_mfma_f32_16x16x32_bf16 v[48:51], v[216:219], v[160:163], v[48:51]
	v_mfma_f32_16x16x32_bf16 v[36:39], v[208:211], v[168:171], v[36:39]
	v_mfma_f32_16x16x32_bf16 v[32:35], v[216:219], v[168:171], v[32:35]
	v_mfma_f32_16x16x32_bf16 v[20:23], v[208:211], v[176:179], v[20:23]
	v_mfma_f32_16x16x32_bf16 v[16:19], v[216:219], v[176:179], v[16:19]
	v_mfma_f32_16x16x32_bf16 v[4:7], v[208:211], v[200:203], v[4:7]
	v_mfma_f32_16x16x32_bf16 v[0:3], v[216:219], v[200:203], v[0:3]
	v_mfma_f32_16x16x32_bf16 v[52:55], v[212:215], v[164:167], v[52:55]
	v_mfma_f32_16x16x32_bf16 v[48:51], v[220:223], v[164:167], v[48:51]
	v_mfma_f32_16x16x32_bf16 v[36:39], v[212:215], v[172:175], v[36:39]
	v_mfma_f32_16x16x32_bf16 v[32:35], v[220:223], v[172:175], v[32:35]
	v_mfma_f32_16x16x32_bf16 v[20:23], v[212:215], v[196:199], v[20:23]
	v_mfma_f32_16x16x32_bf16 v[16:19], v[220:223], v[196:199], v[16:19]
	v_mfma_f32_16x16x32_bf16 v[4:7], v[212:215], v[204:207], v[4:7]
	v_mfma_f32_16x16x32_bf16 v[0:3], v[220:223], v[204:207], v[0:3]
	s_add_i32 s51, 0, 0x18000
	s_barrier
	ds_read_b128 v[138:141], v226
	ds_read_b128 v[148:151], v226 offset:1024
	ds_read_b128 v[152:155], v226 offset:2048
	ds_read_b128 v[156:159], v226 offset:3072
	s_add_u32 s28, s28, 0x100000
	s_addc_u32 s29, s29, 0
	s_mov_b32 m0, s41
	ds_read_b128 v[160:163], v147 offset:32768
	ds_read_b128 v[164:167], v147 offset:33792
	ds_read_b128 v[168:171], v147 offset:34816
	ds_read_b128 v[172:175], v147 offset:35840
	ds_read_b128 v[176:179], v147 offset:36864
	ds_read_b128 v[196:199], v147 offset:37888
	ds_read_b128 v[200:203], v147 offset:38912
	ds_read_b128 v[204:207], v147 offset:39936
	global_load_lds_dwordx4 v128, s[28:29]
	s_mov_b32 m0, s42
	s_nop 0
	global_load_lds_dwordx4 v130, s[28:29]
	s_waitcnt lgkmcnt(8)
	s_barrier
	s_waitcnt lgkmcnt(0)
	s_waitcnt lgkmcnt(0)
	v_mfma_f32_16x16x32_bf16 v[124:127], v[138:141], v[160:163], v[124:127]
	v_mfma_f32_16x16x32_bf16 v[120:123], v[152:155], v[160:163], v[120:123]
	v_mfma_f32_16x16x32_bf16 v[108:111], v[138:141], v[168:171], v[108:111]
	v_mfma_f32_16x16x32_bf16 v[104:107], v[152:155], v[168:171], v[104:107]
	v_mfma_f32_16x16x32_bf16 v[92:95], v[138:141], v[176:179], v[92:95]
	v_mfma_f32_16x16x32_bf16 v[88:91], v[152:155], v[176:179], v[88:91]
	v_mfma_f32_16x16x32_bf16 v[76:79], v[138:141], v[200:203], v[76:79]
	v_mfma_f32_16x16x32_bf16 v[72:75], v[152:155], v[200:203], v[72:75]
	v_mfma_f32_16x16x32_bf16 v[124:127], v[148:151], v[164:167], v[124:127]
	v_mfma_f32_16x16x32_bf16 v[120:123], v[156:159], v[164:167], v[120:123]
	v_mfma_f32_16x16x32_bf16 v[108:111], v[148:151], v[172:175], v[108:111]
	v_mfma_f32_16x16x32_bf16 v[104:107], v[156:159], v[172:175], v[104:107]
	v_mfma_f32_16x16x32_bf16 v[92:95], v[148:151], v[196:199], v[92:95]
	v_mfma_f32_16x16x32_bf16 v[88:91], v[156:159], v[196:199], v[88:91]
	v_mfma_f32_16x16x32_bf16 v[76:79], v[148:151], v[204:207], v[76:79]
	v_mfma_f32_16x16x32_bf16 v[72:75], v[156:159], v[204:207], v[72:75]
	s_barrier
; #define PG8_STAGE(bufoff, gbase, voff) do { _Pragma("unroll") for (int _i = 0; _i < 2; ++_i) \
;     __builtin_amdgcn_global_load_lds((const unsigned*)((const char*)(gbase) + (voff)[_i]), (LAS unsigned*)(lds + (bufoff) + ldsw + _i * 8192), 16, 0, 0); } while (0)
; #define PG8_LDA(dst, b, h) do { _Pragma("unroll") for (int m = 0; m < 4; ++m) _Pragma("unroll") for (int k = 0; k < 2; ++k) dst[m][k] = *(const LAS bf16x8*)(lds + PG8_SA(b, h) + aoff + m * 2048 + k * 1024); } while (0)
; #define PG8_LDB(dst, b, h) do { _Pragma("unroll") for (int n = 0; n < 2; ++n) _Pragma("unroll") for (int k = 0; k < 2; ++k) dst[n][k] = *(const LAS bf16x8*)(lds + PG8_SB(b, h) + boff + n * 2048 + k * 1024); } while (0)
; #define PG8_MMA(ai, bj, At, Bt) do { __builtin_amdgcn_s_setprio(1); _Pragma("unroll") for (int m = 0; m < 4; ++m) _Pragma("unroll") for (int n = 0; n < 2; ++n) _Pragma("unroll") for (int k = 0; k < 2; ++k) \
;     acc[ai][bj][m][n] = __builtin_amdgcn_mfma_f32_16x16x32_bf16(Bt[n][k], At[m][k], acc[ai][bj][m][n], 0, 0, 0); __builtin_amdgcn_s_setprio(0); } while (0)
; #define PG8_WAIT_V(n) asm volatile("s_waitcnt vmcnt(" #n ")" ::: "memory")
; #define PG8_WAIT_L(n) asm volatile("s_waitcnt lgkmcnt(" #n ")" ::: "memory")
; #define PG8_BAR __builtin_amdgcn_s_barrier()
; #define PG8_SCHED __builtin_amdgcn_sched_barrier(0)
; template <class Epi, class Sched>
; DI void gemm_phase(LAS unsigned char* lds, const Gemm g, const Sched& S, const Epi& E) {
;     ...
;       PG8_LDB(B1, 1, 1); PG8_STAGE(PG8_SB(1, 0), b3, voffB);
;       PG8_BAR; PG8_WAIT_L(0); PG8_MMA(0, 1, At, B1); PG8_BAR;
;       PG8_LDA(At, 1, 1); PG8_STAGE(PG8_SA(1, 0), a3, voffA);
;       PG8_BAR; PG8_WAIT_L(0); PG8_MMA(1, 0, At, B0); PG8_BAR; PG8_SCHED;
;       PG8_STAGE(PG8_SB(1, 1), b3 + hstep, voffB);
;       PG8_WAIT_V(6); PG8_BAR; PG8_MMA(1, 1, At, B1); PG8_BAR;
	s_add_i32 s28, 0, 0x1c000
	s_add_i32 s29, s51, s38
	s_mov_b32 m0, s29
	ds_read_b128 v[208:211], v227
	ds_read_b128 v[212:215], v227 offset:1024
	ds_read_b128 v[216:219], v227 offset:2048
	ds_read_b128 v[220:223], v227 offset:3072
	global_load_lds_dwordx4 v144, vcc
	s_add_i32 m0, s29, 0x2000
	s_nop 0
	global_load_lds_dwordx4 v132, vcc
	s_barrier
	s_waitcnt lgkmcnt(0)
	s_waitcnt lgkmcnt(0)
	v_mfma_f32_16x16x32_bf16 v[116:119], v[208:211], v[160:163], v[116:119]
	v_mfma_f32_16x16x32_bf16 v[112:115], v[216:219], v[160:163], v[112:115]
	v_mfma_f32_16x16x32_bf16 v[100:103], v[208:211], v[168:171], v[100:103]
	v_mfma_f32_16x16x32_bf16 v[96:99], v[216:219], v[168:171], v[96:99]
	v_mfma_f32_16x16x32_bf16 v[84:87], v[208:211], v[176:179], v[84:87]
	v_mfma_f32_16x16x32_bf16 v[80:83], v[216:219], v[176:179], v[80:83]
	v_mfma_f32_16x16x32_bf16 v[68:71], v[208:211], v[200:203], v[68:71]
	v_mfma_f32_16x16x32_bf16 v[64:67], v[216:219], v[200:203], v[64:67]
	v_mfma_f32_16x16x32_bf16 v[116:119], v[212:215], v[164:167], v[116:119]
	v_mfma_f32_16x16x32_bf16 v[112:115], v[220:223], v[164:167], v[112:115]
	v_mfma_f32_16x16x32_bf16 v[100:103], v[212:215], v[172:175], v[100:103]
	v_mfma_f32_16x16x32_bf16 v[96:99], v[220:223], v[172:175], v[96:99]
	v_mfma_f32_16x16x32_bf16 v[84:87], v[212:215], v[196:199], v[84:87]
	v_mfma_f32_16x16x32_bf16 v[80:83], v[220:223], v[196:199], v[80:83]
	v_mfma_f32_16x16x32_bf16 v[68:71], v[212:215], v[204:207], v[68:71]
	v_mfma_f32_16x16x32_bf16 v[64:67], v[220:223], v[204:207], v[64:67]
	s_mov_b32 m0, s46
	s_barrier
	ds_read_b128 v[160:163], v147 offset:49152
	ds_read_b128 v[164:167], v147 offset:50176
	ds_read_b128 v[168:171], v147 offset:51200
	ds_read_b128 v[172:175], v147 offset:52224
	ds_read_b128 v[176:179], v147 offset:53248
	ds_read_b128 v[196:199], v147 offset:54272
	ds_read_b128 v[200:203], v147 offset:55296
	ds_read_b128 v[204:207], v147 offset:56320
	global_load_lds_dwordx4 v128, s[100:101]
	s_mov_b32 m0, s47
	s_nop 0
	global_load_lds_dwordx4 v130, s[100:101]
	s_barrier
	s_waitcnt lgkmcnt(0)
	s_waitcnt lgkmcnt(0)
	v_mfma_f32_16x16x32_bf16 v[60:63], v[138:141], v[160:163], v[60:63]
	v_mfma_f32_16x16x32_bf16 v[56:59], v[152:155], v[160:163], v[56:59]
	v_mfma_f32_16x16x32_bf16 v[44:47], v[138:141], v[168:171], v[44:47]
	v_mfma_f32_16x16x32_bf16 v[40:43], v[152:155], v[168:171], v[40:43]
	v_mfma_f32_16x16x32_bf16 v[28:31], v[138:141], v[176:179], v[28:31]
	v_mfma_f32_16x16x32_bf16 v[24:27], v[152:155], v[176:179], v[24:27]
	v_mfma_f32_16x16x32_bf16 v[12:15], v[138:141], v[200:203], v[12:15]
	v_mfma_f32_16x16x32_bf16 v[8:11], v[152:155], v[200:203], v[8:11]
	v_mfma_f32_16x16x32_bf16 v[60:63], v[148:151], v[164:167], v[60:63]
	v_mfma_f32_16x16x32_bf16 v[56:59], v[156:159], v[164:167], v[56:59]
	v_mfma_f32_16x16x32_bf16 v[44:47], v[148:151], v[172:175], v[44:47]
	v_mfma_f32_16x16x32_bf16 v[40:43], v[156:159], v[172:175], v[40:43]
	v_mfma_f32_16x16x32_bf16 v[28:31], v[148:151], v[196:199], v[28:31]
	v_mfma_f32_16x16x32_bf16 v[24:27], v[156:159], v[196:199], v[24:27]
	v_mfma_f32_16x16x32_bf16 v[12:15], v[148:151], v[204:207], v[12:15]
	v_mfma_f32_16x16x32_bf16 v[8:11], v[156:159], v[204:207], v[8:11]
	s_barrier
	s_add_u32 s22, s22, 0x100080
	s_addc_u32 s23, s23, 0
	s_add_i32 s28, s28, s38
	s_mov_b32 m0, s28
	s_nop 0
	global_load_lds_dwordx4 v144, s[22:23]
	s_add_i32 m0, s28, 0x2000
	s_nop 0
	global_load_lds_dwordx4 v132, s[22:23]
	s_waitcnt vmcnt(6)
	s_barrier
; DI float bf2f(unsigned v) { return __uint_as_float(v << 16); }
;   DI void operator()(const f32x4 (&acc)[2][2][4][2], const pg8::Unit& u, int wr, int wc, int fr_, int fq_) const {
;     ...
;             } else if (EPI == EPI_RESID) {
;               if (n == 0) {
;                 const int f8 = u.pn * 256 + bj * 128 + wc * 32 + 8 * fq;
;                 const f32x4 v1 = acc[ai][bj][m][1];
;                 f32x4 r0, r1;
;                 if (rsrc) {
;                   r0 = *(const f32x4*)(rsrc + (size_t)token * 1024 + f8); r1 = *(const f32x4*)(rsrc + (size_t)token * 1024 + f8 + 4);
;                 } else {
;                   const u32x4 xu = *(const u32x4*)(xr + (size_t)token * 1024 + f8);
;                   r0 = (f32x4){bf2f(xu.x & 0xffffu), bf2f(xu.x >> 16), bf2f(xu.y & 0xffffu), bf2f(xu.y >> 16)};
;                   r1 = (f32x4){bf2f(xu.z & 0xffffu), bf2f(xu.z >> 16), bf2f(xu.w & 0xffffu), bf2f(xu.w >> 16)};
;                 }
;                 r0 += v; r1 += v1;
;                 st_bf8(xr + (size_t)token * 1024 + f8, r0, r1, 1.f);
;                 ssq += r0[0] * r0[0] + r0[1] * r0[1] + r0[2] * r0[2] + r0[3] * r0[3] + r1[0] * r1[0] + r1[1] * r1[1] + r1[2] * r1[2] + r1[3] * r1[3];
;               }
;             } else {
;               if (n == 0) {
;                 const f32x4 v1 = acc[ai][bj][m][1];
;                 u32x4 o4;
;                 { const float t0 = fmaxf(v[0], 0.f) * rinv, t1 = fmaxf(v[1], 0.f) * rinv, t2 = fmaxf(v[2], 0.f) * rinv, t3 = fmaxf(v[3], 0.f) * rinv;
;                   o4.x = pack2(t0 * t0, t1 * t1); o4.y = pack2(t2 * t2, t3 * t3); }
;                 { const float t0 = fmaxf(v1[0], 0.f) * rinv, t1 = fmaxf(v1[1], 0.f) * rinv, t2 = fmaxf(v1[2], 0.f) * rinv, t3 = fmaxf(v1[3], 0.f) * rinv;
;                   o4.z = pack2(t0 * t0, t1 * t1); o4.w = pack2(t2 * t2, t3 * t3); }
;                 *(u32x4*)((u16*)big + (size_t)token * 4096 + u.pn * 256 + bj * 128 + wc * 32 + 8 * fq) = o4;
;               }
;             }
;           }
;         if (EPI == EPI_RESID) {
;           ssq += shx(ssq, 16, t_ & 63);
;           ssq += shx(ssq, 32, t_ & 63);
;           if (fq == 0) ss_out[(size_t)token * 16 + u.pn * 4 + wc] = ssq;
	v_mfma_f32_16x16x32_bf16 v[52:55], v[208:211], v[160:163], v[52:55]
	v_mfma_f32_16x16x32_bf16 v[48:51], v[216:219], v[160:163], v[48:51]
	v_mfma_f32_16x16x32_bf16 v[36:39], v[208:211], v[168:171], v[36:39]
	v_mfma_f32_16x16x32_bf16 v[32:35], v[216:219], v[168:171], v[32:35]
	v_mfma_f32_16x16x32_bf16 v[20:23], v[208:211], v[176:179], v[20:23]
	v_mfma_f32_16x16x32_bf16 v[16:19], v[216:219], v[176:179], v[16:19]
	v_mfma_f32_16x16x32_bf16 v[4:7], v[208:211], v[200:203], v[4:7]
	v_mfma_f32_16x16x32_bf16 v[0:3], v[216:219], v[200:203], v[0:3]
	v_mfma_f32_16x16x32_bf16 v[52:55], v[212:215], v[164:167], v[52:55]
	v_mfma_f32_16x16x32_bf16 v[48:51], v[220:223], v[164:167], v[48:51]
	v_mfma_f32_16x16x32_bf16 v[36:39], v[212:215], v[172:175], v[36:39]
	v_mfma_f32_16x16x32_bf16 v[32:35], v[220:223], v[172:175], v[32:35]
	v_mfma_f32_16x16x32_bf16 v[20:23], v[212:215], v[196:199], v[20:23]
	v_mfma_f32_16x16x32_bf16 v[16:19], v[220:223], v[196:199], v[16:19]
	v_mfma_f32_16x16x32_bf16 v[4:7], v[212:215], v[204:207], v[4:7]
	v_mfma_f32_16x16x32_bf16 v[0:3], v[220:223], v[204:207], v[0:3]
	s_add_i32 s50, s50, 2
	s_add_u32 s20, s20, 0x100
	s_addc_u32 s21, s21, 0
	s_add_u32 s24, s24, 0x100
	s_addc_u32 s49, s49, 0
	s_cmp_gt_u32 s50, 61
	s_barrier
	s_cbranch_scc0 .LBB0_1905
	s_lshl_b32 s7, s18, 8
	v_mov_b32_e32 v139, v182
	s_add_i32 s7, s7, s44
	s_nop 0
	v_and_or_b32 v140, v139, 15, s7
	s_lshl_b32 s7, s16, 8
	v_bfe_u32 v141, v139, 4, 2
	s_or_b32 s7, s7, s45
	v_lshl_or_b32 v138, v141, 3, s7
	v_cmp_eq_u32_e32 vcc, 0, v141
	v_ashrrev_i32_e32 v141, 31, v140
	v_lshlrev_b32_e32 v139, 2, v139
	s_movk_i32 s7, 0x80
	v_lshlrev_b64 v[142:143], 11, v[140:141]
	v_bitop3_b32 v149, v139, 64, v190 bitop3:0x6c
	v_bitop3_b32 v148, v139, s7, v190 bitop3:0x6c
	v_ashrrev_i32_e32 v139, 31, v138
	v_lshl_add_u64 v[142:143], s[4:5], 0, v[142:143]
	v_lshl_add_u64 v[142:143], v[138:139], 1, v[142:143]
	global_load_dwordx4 v[150:153], v[142:143], off
	s_lshl_b32 s16, s16, 2
	s_ashr_i32 s17, s16, 31
	s_waitcnt vmcnt(0)
	v_lshlrev_b32_e32 v154, 16, v150
	v_and_b32_e32 v155, 0xffff0000, v150
	v_lshlrev_b32_e32 v150, 16, v151
	v_and_b32_e32 v151, 0xffff0000, v151
	v_lshlrev_b32_e32 v156, 16, v152
	v_and_b32_e32 v157, 0xffff0000, v152
	v_lshlrev_b32_e32 v152, 16, v153
	v_and_b32_e32 v153, 0xffff0000, v153
	v_pk_add_f32 v[126:127], v[126:127], v[150:151]
	v_pk_add_f32 v[124:125], v[124:125], v[154:155]
	v_pk_add_f32 v[150:151], v[122:123], v[152:153]
	v_pk_add_f32 v[152:153], v[120:121], v[156:157]
	v_cvt_pk_bf16_f32 v120, v124, v125
	v_cvt_pk_bf16_f32 v121, v126, v127
	v_cvt_pk_bf16_f32 v122, v152, v153
	v_cvt_pk_bf16_f32 v123, v150, v151
	global_store_dwordx4 v[142:143], v[120:123], off
	global_load_dwordx4 v[120:123], v[142:143], off offset:256
	v_mul_f32_e32 v154, v125, v125
	v_fmac_f32_e32 v154, v124, v124
	v_fmac_f32_e32 v154, v126, v126
	v_fmac_f32_e32 v154, v127, v127
	v_fmac_f32_e32 v154, v152, v152
	v_fmac_f32_e32 v154, v153, v153
	v_fmac_f32_e32 v154, v150, v150
	v_fmac_f32_e32 v154, v151, v151
	s_waitcnt vmcnt(0)
	v_lshlrev_b32_e32 v124, 16, v120
	v_and_b32_e32 v125, 0xffff0000, v120
	v_lshlrev_b32_e32 v120, 16, v121
	v_and_b32_e32 v121, 0xffff0000, v121
	v_lshlrev_b32_e32 v126, 16, v122
	v_and_b32_e32 v127, 0xffff0000, v122
	v_lshlrev_b32_e32 v122, 16, v123
	v_and_b32_e32 v123, 0xffff0000, v123
	v_pk_add_f32 v[118:119], v[118:119], v[120:121]
	v_pk_add_f32 v[116:117], v[116:117], v[124:125]
	v_pk_add_f32 v[120:121], v[114:115], v[122:123]
	v_pk_add_f32 v[122:123], v[112:113], v[126:127]
	v_cvt_pk_bf16_f32 v112, v116, v117
	v_cvt_pk_bf16_f32 v113, v118, v119
	v_cvt_pk_bf16_f32 v114, v122, v123
	v_cvt_pk_bf16_f32 v115, v120, v121
	global_store_dwordx4 v[142:143], v[112:115], off offset:256
	s_nop 1
	v_mul_f32_e32 v112, v117, v117
	v_fmac_f32_e32 v112, v116, v116
	v_fmac_f32_e32 v112, v118, v118
	v_fmac_f32_e32 v112, v119, v119
	v_fmac_f32_e32 v112, v122, v122
	v_fmac_f32_e32 v112, v123, v123
	v_fmac_f32_e32 v112, v120, v120
	v_fmac_f32_e32 v112, v121, v121
	v_add_f32_e32 v112, v154, v112
	ds_bpermute_b32 v113, v149, v112
	s_waitcnt lgkmcnt(0)
	v_add_f32_e32 v112, v112, v113
	ds_bpermute_b32 v113, v148, v112
	s_and_saveexec_b64 s[18:19], vcc
	s_cbranch_execz .LBB0_1908
	s_waitcnt lgkmcnt(0)
	v_add_f32_e32 v114, v112, v113
	v_lshlrev_b64 v[112:113], 6, v[140:141]
	v_lshl_add_u64 v[112:113], s[2:3], 0, v[112:113]
	v_lshl_add_u64 v[112:113], s[16:17], 2, v[112:113]
	s_lshl_b32 s24, s43, 2
	v_lshl_add_u64 v[112:113], v[112:113], 0, s[24:25]
	global_store_dword v[112:113], v114, off
